# S5 scan/prefix loops: removed hipcc's conservative 1-state pads between dependent packed-f32 VOP3P ops (outputs bit-identical)
# speedup vs baseline: 1.0060x; 1.0060x over previous
; template <int DIRN> DI void s5_dir(const S5P& P, const f32x2* END, const LAS float* UF, LAS bf16* XT, int b, int seg, int g, const bf16x8 (&bfr)[4], f32x4 (&acc)[8], int lane) {
;     ...
; #pragma unroll 8
;         for (int j = 0; j < sl; ++j) { const float* ep = (const float*)END + ((size_t)((b * 2 + DIRN) * SNSEG + j)) * 8192 + g * 128 + lane; const f32x2 e = {ep[0], ep[64]}; const float nr = Lr * xr - Li * xi + e.x, ni = Lr * xi + Li * xr + e.y; xr = nr; xi = ni; } }
.LBB0_617:
	global_load_dword v184, v[80:81], off
	global_load_dword v185, v[80:81], off offset:256
	v_add_co_u32_e32 v80, vcc, 0x8000, v80
	s_nop 1
	v_addc_co_u32_e32 v81, vcc, 0, v81, vcc
	global_load_dword v186, v[80:81], off
	global_load_dword v187, v[80:81], off offset:256
	v_add_co_u32_e32 v80, vcc, 0x8000, v80
	s_nop 1
	v_addc_co_u32_e32 v81, vcc, 0, v81, vcc
	global_load_dword v188, v[80:81], off
	global_load_dword v189, v[80:81], off offset:256
	v_add_co_u32_e32 v80, vcc, 0x8000, v80
	s_nop 1
	v_addc_co_u32_e32 v81, vcc, 0, v81, vcc
	global_load_dword v190, v[80:81], off
	global_load_dword v191, v[80:81], off offset:256
	v_add_co_u32_e32 v80, vcc, 0x8000, v80
	s_nop 1
	v_addc_co_u32_e32 v81, vcc, 0, v81, vcc
	global_load_dword v192, v[80:81], off
	global_load_dword v193, v[80:81], off offset:256
	v_add_co_u32_e32 v80, vcc, 0x8000, v80
	s_nop 1
	v_addc_co_u32_e32 v81, vcc, 0, v81, vcc
	global_load_dword v194, v[80:81], off
	global_load_dword v195, v[80:81], off offset:256
	v_add_co_u32_e32 v80, vcc, 0x8000, v80
	s_nop 1
	v_addc_co_u32_e32 v81, vcc, 0, v81, vcc
	global_load_dword v196, v[80:81], off
	global_load_dword v197, v[80:81], off offset:256
	v_add_co_u32_e32 v80, vcc, 0x8000, v80
	s_nop 1
	v_addc_co_u32_e32 v81, vcc, 0, v81, vcc
	global_load_dword v198, v[80:81], off
	global_load_dword v199, v[80:81], off offset:256
	v_add_co_u32_e32 v80, vcc, 0x8000, v80
	s_nop 1
	v_addc_co_u32_e32 v81, vcc, 0, v81, vcc
	s_add_i32 s1, s1, 8
	v_pk_mul_f32 v[84:85], v[74:75], v[174:175] op_sel:[0,1] op_sel_hi:[1,0]
	v_pk_fma_f32 v[88:89], v[76:77], v[174:175], v[84:85]
	v_pk_fma_f32 v[82:83], v[76:77], v[174:175], v[84:85] neg_lo:[0,0,1] neg_hi:[0,0,1]
	s_nop 0
	v_mov_b32_e32 v83, v89
	s_waitcnt vmcnt(14) lgkmcnt(0)
	v_pk_add_f32 v[174:175], v[82:83], v[184:185]
	v_pk_mul_f32 v[84:85], v[74:75], v[174:175] op_sel:[0,1] op_sel_hi:[1,0]
	v_pk_fma_f32 v[88:89], v[76:77], v[174:175], v[84:85]
	v_pk_fma_f32 v[82:83], v[76:77], v[174:175], v[84:85] neg_lo:[0,0,1] neg_hi:[0,0,1]
	s_nop 0
	v_mov_b32_e32 v83, v89
	s_waitcnt vmcnt(12)
	v_pk_add_f32 v[174:175], v[82:83], v[186:187]
	v_pk_mul_f32 v[84:85], v[74:75], v[174:175] op_sel:[0,1] op_sel_hi:[1,0]
	v_pk_fma_f32 v[88:89], v[76:77], v[174:175], v[84:85]
	v_pk_fma_f32 v[82:83], v[76:77], v[174:175], v[84:85] neg_lo:[0,0,1] neg_hi:[0,0,1]
	s_nop 0
	v_mov_b32_e32 v83, v89
	s_waitcnt vmcnt(10)
	v_pk_add_f32 v[174:175], v[82:83], v[188:189]
	v_pk_mul_f32 v[84:85], v[74:75], v[174:175] op_sel:[0,1] op_sel_hi:[1,0]
	v_pk_fma_f32 v[88:89], v[76:77], v[174:175], v[84:85]
	v_pk_fma_f32 v[82:83], v[76:77], v[174:175], v[84:85] neg_lo:[0,0,1] neg_hi:[0,0,1]
	s_nop 0
	v_mov_b32_e32 v83, v89
	s_waitcnt vmcnt(8)
	v_pk_add_f32 v[174:175], v[82:83], v[190:191]
	v_pk_mul_f32 v[84:85], v[74:75], v[174:175] op_sel:[0,1] op_sel_hi:[1,0]
	v_pk_fma_f32 v[88:89], v[76:77], v[174:175], v[84:85]
	v_pk_fma_f32 v[82:83], v[76:77], v[174:175], v[84:85] neg_lo:[0,0,1] neg_hi:[0,0,1]
	s_nop 0
	v_mov_b32_e32 v83, v89
	s_waitcnt vmcnt(6)
	v_pk_add_f32 v[174:175], v[82:83], v[192:193]
	v_pk_mul_f32 v[84:85], v[74:75], v[174:175] op_sel:[0,1] op_sel_hi:[1,0]
	v_pk_fma_f32 v[88:89], v[76:77], v[174:175], v[84:85]
	v_pk_fma_f32 v[82:83], v[76:77], v[174:175], v[84:85] neg_lo:[0,0,1] neg_hi:[0,0,1]
	s_nop 0
	v_mov_b32_e32 v83, v89
	s_waitcnt vmcnt(4)
	v_pk_add_f32 v[174:175], v[82:83], v[194:195]
	v_pk_mul_f32 v[84:85], v[74:75], v[174:175] op_sel:[0,1] op_sel_hi:[1,0]
	v_pk_fma_f32 v[88:89], v[76:77], v[174:175], v[84:85]
	v_pk_fma_f32 v[82:83], v[76:77], v[174:175], v[84:85] neg_lo:[0,0,1] neg_hi:[0,0,1]
	s_nop 0
	v_mov_b32_e32 v83, v89
	s_waitcnt vmcnt(2)
	v_pk_add_f32 v[174:175], v[82:83], v[196:197]
	v_pk_mul_f32 v[84:85], v[74:75], v[174:175] op_sel:[0,1] op_sel_hi:[1,0]
	v_pk_fma_f32 v[88:89], v[76:77], v[174:175], v[84:85]
	v_pk_fma_f32 v[82:83], v[76:77], v[174:175], v[84:85] neg_lo:[0,0,1] neg_hi:[0,0,1]
	s_nop 0
	v_mov_b32_e32 v83, v89
	s_waitcnt vmcnt(0)
	v_pk_add_f32 v[174:175], v[82:83], v[198:199]
	s_cmp_eq_u32 s11, s1
	s_cbranch_scc0 .LBB0_617
	s_bfe_u32 s1, s30, 0x30006
	s_cmp_eq_u32 s1, 0
	s_cbranch_scc0 .LBB0_620
	s_branch .LBB0_622

; #define LAS __attribute__((address_space(3)))
; DI unsigned pk2(float lo, float hi) { return pg8::cvt_pk_bf16(lo, hi); }
; DI f32x4 mfma16(bf16x8 a, bf16x8 b, f32x4 c) { return __builtin_amdgcn_mfma_f32_16x16x32_bf16(a, b, c, 0, 0, 0); }
; template <int DIRN, int SUB> DI void s5_subtile(const LAS float* UF, LAS bf16* XT, float lr, float li, const f32x2 (&bb)[16], f32x2& x,
;                                                 const bf16x8 (&bfr)[4], f32x4& acc0, f32x4& acc1, int lane) {
; #pragma unroll 1
;     for (int i = 0; i < 32; ++i) { const int r = DIRN ? 31 - i : i;
;         x = s5_step((const LAS f32x4*)(UF + (32 * SUB + r) * 16), bb, lr, li, x);
;         const unsigned pkd = pk2(x.x, x.y); XT[r * 136 + lane] = (bf16)(pkd & 0xffffu); XT[r * 136 + 64 + lane] = (bf16)(pkd >> 16); }
; #pragma unroll
;     for (int ks = 0; ks < 4; ++ks) { const bf16x8 a0 = *(const LAS bf16x8*)(XT + (lane & 15) * 136 + 32 * ks + 8 * (lane >> 4)), a1 = *(const LAS bf16x8*)(XT + (16 + (lane & 15)) * 136 + 32 * ks + 8 * (lane >> 4));
;         acc0 = mfma16(a0, bfr[ks], acc0); acc1 = mfma16(a1, bfr[ks], acc1); }
.LBB0_623:
	s_add_i32 s1, s49, s0
	v_mov_b32_e32 v2, s1
	ds_read_b128 v[72:75], v2
	ds_read_b128 v[76:79], v2 offset:16
	ds_read_b128 v[80:83], v2 offset:32
	ds_read_b128 v[84:87], v2 offset:48
	s_waitcnt lgkmcnt(3)
	v_pk_mul_f32 v[88:89], v[180:181], v[72:73] op_sel:[0,1]
	v_pk_fma_f32 v[72:73], v[178:179], v[72:73], v[88:89] op_sel_hi:[1,0,1]
	v_mov_b32_e32 v2, v75
	v_pk_fma_f32 v[72:73], v[182:183], v[74:75], v[72:73] op_sel_hi:[1,0,1]
	s_waitcnt lgkmcnt(1)
	v_pk_mul_f32 v[74:75], v[196:197], v[80:81] op_sel:[0,1]
	v_pk_fma_f32 v[72:73], v[184:185], v[2:3], v[72:73] op_sel_hi:[1,0,1]
	v_mov_b32_e32 v2, v79
	v_pk_fma_f32 v[72:73], v[186:187], v[76:77], v[72:73] op_sel_hi:[1,0,1]
	v_pk_fma_f32 v[74:75], v[194:195], v[80:81], v[74:75] op_sel_hi:[1,0,1]
	v_pk_fma_f32 v[72:73], v[188:189], v[76:77], v[72:73] op_sel:[0,1,0]
	v_pk_fma_f32 v[74:75], v[198:199], v[82:83], v[74:75] op_sel_hi:[1,0,1]
	v_pk_fma_f32 v[72:73], v[190:191], v[78:79], v[72:73] op_sel_hi:[1,0,1]
	v_pk_fma_f32 v[72:73], v[192:193], v[2:3], v[72:73] op_sel_hi:[1,0,1]
	v_mov_b32_e32 v2, v83
	v_pk_fma_f32 v[74:75], v[200:201], v[2:3], v[74:75] op_sel_hi:[1,0,1]
	s_waitcnt lgkmcnt(0)
	v_mov_b32_e32 v2, v87
	v_pk_fma_f32 v[74:75], v[202:203], v[84:85], v[74:75] op_sel_hi:[1,0,1]
	v_pk_fma_f32 v[74:75], v[204:205], v[84:85], v[74:75] op_sel:[0,1,0]
	v_pk_fma_f32 v[74:75], v[206:207], v[86:87], v[74:75] op_sel_hi:[1,0,1]
	v_pk_fma_f32 v[74:75], v[176:177], v[2:3], v[74:75] op_sel_hi:[1,0,1]
	v_pk_add_f32 v[72:73], v[72:73], v[74:75]
	v_pk_fma_f32 v[72:73], v[128:129], v[174:175], v[72:73] op_sel:[0,1,0] op_sel_hi:[1,0,1]
	v_pk_fma_f32 v[174:175], v[126:127], v[174:175], v[72:73]
	v_add_u32_e32 v72, s49, v1
	v_cvt_pk_bf16_f32 v2, v174, s0
	v_cvt_pk_bf16_f32 v71, v175, s0
	s_add_i32 s0, s0, 64
	v_add_u32_e32 v1, 0x110, v1
	s_cmpk_lg_i32 s0, 0x800
	ds_write_b16 v72, v2
	ds_write_b16 v72, v71 offset:128
	s_cbranch_scc1 .LBB0_623
	v_and_b32_e32 v125, 15, v122
	v_mul_u32_u24_e32 v1, 0x110, v125
	v_lshlrev_b32_e32 v2, 1, v70
	v_add3_u32 v1, s49, v1, v2
	ds_read_b128 v[98:101], v1 offset:8192
	ds_read_b128 v[94:97], v1 offset:8256
	ds_read_b128 v[82:85], v1 offset:12544
	ds_read_b128 v[86:89], v1 offset:12608
	ds_read_b128 v[90:93], v1 offset:8320
	ds_read_b128 v[78:81], v1 offset:8384
	ds_read_b128 v[70:73], v1 offset:12672
	ds_read_b128 v[74:77], v1 offset:12736
	v_add_u32_e32 v2, s40, v152
	s_mov_b32 s0, 0
	v_mov_b32_e32 v102, v2
.LBB0_625:
	s_add_i32 s1, s41, s0
	v_mov_b32_e32 v103, s1
	ds_read_b128 v[104:107], v103
	ds_read_b128 v[108:111], v103 offset:16
	ds_read_b128 v[112:115], v103 offset:32
	ds_read_b128 v[116:119], v103 offset:48
	s_waitcnt lgkmcnt(3)
	v_pk_mul_f32 v[120:121], v[180:181], v[104:105] op_sel:[0,1]
	v_pk_fma_f32 v[104:105], v[178:179], v[104:105], v[120:121] op_sel_hi:[1,0,1]
	v_pk_fma_f32 v[104:105], v[182:183], v[106:107], v[104:105] op_sel_hi:[1,0,1]
	v_mov_b32_e32 v106, v107
	v_pk_fma_f32 v[104:105], v[184:185], v[106:107], v[104:105] op_sel_hi:[1,0,1]
	s_waitcnt lgkmcnt(2)
	v_mov_b32_e32 v106, v111
	v_pk_fma_f32 v[104:105], v[186:187], v[108:109], v[104:105] op_sel_hi:[1,0,1]
	v_pk_fma_f32 v[104:105], v[188:189], v[108:109], v[104:105] op_sel:[0,1,0]
	s_waitcnt lgkmcnt(1)
	v_mov_b32_e32 v108, v115
	v_pk_fma_f32 v[104:105], v[190:191], v[110:111], v[104:105] op_sel_hi:[1,0,1]
	v_pk_fma_f32 v[104:105], v[192:193], v[106:107], v[104:105] op_sel_hi:[1,0,1]
	v_pk_mul_f32 v[106:107], v[196:197], v[112:113] op_sel:[0,1]
	v_pk_fma_f32 v[106:107], v[194:195], v[112:113], v[106:107] op_sel_hi:[1,0,1]
	v_pk_fma_f32 v[106:107], v[198:199], v[114:115], v[106:107] op_sel_hi:[1,0,1]
	v_pk_fma_f32 v[106:107], v[200:201], v[108:109], v[106:107] op_sel_hi:[1,0,1]
	s_waitcnt lgkmcnt(0)
	v_mov_b32_e32 v108, v119
	v_pk_fma_f32 v[106:107], v[202:203], v[116:117], v[106:107] op_sel_hi:[1,0,1]
	v_pk_fma_f32 v[106:107], v[204:205], v[116:117], v[106:107] op_sel:[0,1,0]
	v_pk_fma_f32 v[106:107], v[206:207], v[118:119], v[106:107] op_sel_hi:[1,0,1]
	v_pk_fma_f32 v[106:107], v[176:177], v[108:109], v[106:107] op_sel_hi:[1,0,1]
	v_pk_add_f32 v[104:105], v[104:105], v[106:107]
	v_pk_fma_f32 v[104:105], v[128:129], v[174:175], v[104:105] op_sel:[0,1,0] op_sel_hi:[1,0,1]
	v_pk_fma_f32 v[174:175], v[126:127], v[174:175], v[104:105]
	s_nop 0
	v_cvt_pk_bf16_f32 v103, v174, s0
	v_cvt_pk_bf16_f32 v104, v175, s0
	s_add_i32 s0, s0, 64
	ds_write_b16 v102, v103
	ds_write_b16 v102, v104 offset:128
	v_add_u32_e32 v102, 0x110, v102
	s_cmpk_lg_i32 s0, 0x800
	s_cbranch_scc1 .LBB0_625
	v_cvt_pk_bf16_f32 v46, v46, v47
	v_cvt_pk_bf16_f32 v47, v48, v49
	v_cvt_pk_bf16_f32 v48, v66, v67
	v_cvt_pk_bf16_f32 v49, v68, v69
	v_cvt_pk_bf16_f32 v54, v54, v55
	v_cvt_pk_bf16_f32 v55, v56, v57
	v_cvt_pk_bf16_f32 v57, v52, v53
	v_cvt_pk_bf16_f32 v52, -v58, -v59
	v_cvt_pk_bf16_f32 v53, -v60, -v61
	v_mfma_f32_16x16x32_bf16 v[58:61], v[98:101], v[46:49], 0
	v_cvt_pk_bf16_f32 v56, v50, v51
	v_cvt_pk_bf16_f32 v50, -v62, -v63
	v_cvt_pk_bf16_f32 v51, -v64, -v65
	v_mfma_f32_16x16x32_bf16 v[58:61], v[94:97], v[54:57], v[58:61]
	s_mov_b32 s0, 0
	v_mov_b32_e32 v110, v2
	v_mfma_f32_16x16x32_bf16 v[90:93], v[90:93], v[50:53], v[58:61]
	v_mfma_f32_16x16x32_bf16 v[58:61], v[82:85], v[46:49], 0
	v_mfma_f32_16x16x32_bf16 v[58:61], v[86:89], v[54:57], v[58:61]
	ds_read_b128 v[94:97], v1 offset:8192
	ds_read_b128 v[86:89], v1 offset:12544
	ds_read_b128 v[98:101], v1 offset:8256
	ds_read_b128 v[102:105], v1 offset:12608
	ds_read_b128 v[106:109], v1 offset:8320
	ds_read_b128 v[66:69], v1 offset:12672
	ds_read_b128 v[62:65], v1 offset:8384
	ds_read_b128 v[82:85], v1 offset:12736
; #define LAS __attribute__((address_space(3)))
; DI unsigned pk2(float lo, float hi) { return pg8::cvt_pk_bf16(lo, hi); }
; DI f32x4 mfma16(bf16x8 a, bf16x8 b, f32x4 c) { return __builtin_amdgcn_mfma_f32_16x16x32_bf16(a, b, c, 0, 0, 0); }
; template <int DIRN, int SUB> DI void s5_subtile(const LAS float* UF, LAS bf16* XT, float lr, float li, const f32x2 (&bb)[16], f32x2& x,
;                                                 const bf16x8 (&bfr)[4], f32x4& acc0, f32x4& acc1, int lane) {
; #pragma unroll 1
;     for (int i = 0; i < 32; ++i) { const int r = DIRN ? 31 - i : i;
;         x = s5_step((const LAS f32x4*)(UF + (32 * SUB + r) * 16), bb, lr, li, x);
;         const unsigned pkd = pk2(x.x, x.y); XT[r * 136 + lane] = (bf16)(pkd & 0xffffu); XT[r * 136 + 64 + lane] = (bf16)(pkd >> 16); }
; #pragma unroll
;     for (int ks = 0; ks < 4; ++ks) { const bf16x8 a0 = *(const LAS bf16x8*)(XT + (lane & 15) * 136 + 32 * ks + 8 * (lane >> 4)), a1 = *(const LAS bf16x8*)(XT + (16 + (lane & 15)) * 136 + 32 * ks + 8 * (lane >> 4));
;         acc0 = mfma16(a0, bfr[ks], acc0); acc1 = mfma16(a1, bfr[ks], acc1); }
.LBB0_627:
	s_add_i32 s1, s42, s0
	v_mov_b32_e32 v111, s1
	ds_read_b128 v[112:115], v111
	ds_read_b128 v[116:119], v111 offset:16
	ds_read_b128 v[230:233], v111 offset:32
	ds_read_b128 v[234:237], v111 offset:48
	s_waitcnt lgkmcnt(3)
	v_pk_mul_f32 v[120:121], v[180:181], v[112:113] op_sel:[0,1]
	v_pk_fma_f32 v[112:113], v[178:179], v[112:113], v[120:121] op_sel_hi:[1,0,1]
	v_pk_fma_f32 v[112:113], v[182:183], v[114:115], v[112:113] op_sel_hi:[1,0,1]
	v_mov_b32_e32 v114, v115
	v_pk_fma_f32 v[112:113], v[184:185], v[114:115], v[112:113] op_sel_hi:[1,0,1]
	s_waitcnt lgkmcnt(2)
	v_mov_b32_e32 v114, v119
	v_pk_fma_f32 v[112:113], v[186:187], v[116:117], v[112:113] op_sel_hi:[1,0,1]
	v_pk_fma_f32 v[112:113], v[188:189], v[116:117], v[112:113] op_sel:[0,1,0]
	s_waitcnt lgkmcnt(1)
	v_mov_b32_e32 v116, v233
	v_pk_fma_f32 v[112:113], v[190:191], v[118:119], v[112:113] op_sel_hi:[1,0,1]
	v_pk_fma_f32 v[112:113], v[192:193], v[114:115], v[112:113] op_sel_hi:[1,0,1]
	v_pk_mul_f32 v[114:115], v[196:197], v[230:231] op_sel:[0,1]
	v_pk_fma_f32 v[114:115], v[194:195], v[230:231], v[114:115] op_sel_hi:[1,0,1]
	v_pk_fma_f32 v[114:115], v[198:199], v[232:233], v[114:115] op_sel_hi:[1,0,1]
	v_pk_fma_f32 v[114:115], v[200:201], v[116:117], v[114:115] op_sel_hi:[1,0,1]
	s_waitcnt lgkmcnt(0)
	v_mov_b32_e32 v116, v237
	v_pk_fma_f32 v[114:115], v[202:203], v[234:235], v[114:115] op_sel_hi:[1,0,1]
	v_pk_fma_f32 v[114:115], v[204:205], v[234:235], v[114:115] op_sel:[0,1,0]
	v_pk_fma_f32 v[114:115], v[206:207], v[236:237], v[114:115] op_sel_hi:[1,0,1]
	v_pk_fma_f32 v[114:115], v[176:177], v[116:117], v[114:115] op_sel_hi:[1,0,1]
	v_pk_add_f32 v[112:113], v[112:113], v[114:115]
	v_pk_fma_f32 v[112:113], v[128:129], v[174:175], v[112:113] op_sel:[0,1,0] op_sel_hi:[1,0,1]
	v_pk_fma_f32 v[174:175], v[126:127], v[174:175], v[112:113]
	s_nop 0
	v_cvt_pk_bf16_f32 v111, v174, s0
	v_cvt_pk_bf16_f32 v112, v175, s0
	s_add_i32 s0, s0, 64
	ds_write_b16 v110, v111
	ds_write_b16 v110, v112 offset:128
	v_add_u32_e32 v110, 0x110, v110
	s_cmpk_lg_i32 s0, 0x800
	s_cbranch_scc1 .LBB0_627
	v_cvt_pk_bf16_f32 v42, -v42, -v43
	v_cvt_pk_bf16_f32 v43, -v44, -v45
	v_cvt_pk_bf16_f32 v44, -v38, -v39
	v_cvt_pk_bf16_f32 v45, -v40, -v41
	v_mfma_f32_16x16x32_bf16 v[86:89], v[86:89], v[46:49], 0
	s_mov_b32 s0, 0
	v_mfma_f32_16x16x32_bf16 v[38:41], v[78:81], v[42:45], v[90:93]
	v_mfma_f32_16x16x32_bf16 v[78:81], v[94:97], v[46:49], 0
	v_mfma_f32_16x16x32_bf16 v[78:81], v[98:101], v[54:57], v[78:81]
	v_mfma_f32_16x16x32_bf16 v[78:81], v[106:109], v[50:53], v[78:81]
	v_mfma_f32_16x16x32_bf16 v[86:89], v[102:105], v[54:57], v[86:89]
	ds_read_b128 v[94:97], v1 offset:8192
	ds_read_b128 v[90:93], v1 offset:12544
	ds_read_b128 v[102:105], v1 offset:8256
	ds_read_b128 v[98:101], v1 offset:12608
	ds_read_b128 v[110:113], v1 offset:8320
	ds_read_b128 v[106:109], v1 offset:12672
	ds_read_b128 v[118:121], v1 offset:8384
	ds_read_b128 v[114:117], v1 offset:12736
.LBB0_629:
	s_add_i32 s1, s43, s0
	v_mov_b32_e32 v158, s1
	ds_read_b128 v[230:233], v158
	ds_read_b128 v[234:237], v158 offset:16
	ds_read_b128 v[238:241], v158 offset:32
	ds_read_b128 v[242:245], v158 offset:48
	s_waitcnt lgkmcnt(3)
	v_pk_mul_f32 v[158:159], v[180:181], v[230:231] op_sel:[0,1]
	v_pk_fma_f32 v[158:159], v[178:179], v[230:231], v[158:159] op_sel_hi:[1,0,1]
	v_mov_b32_e32 v160, v233
	v_pk_fma_f32 v[158:159], v[182:183], v[232:233], v[158:159] op_sel_hi:[1,0,1]
	s_waitcnt lgkmcnt(1)
	v_mov_b32_e32 v230, v241
	v_pk_fma_f32 v[158:159], v[184:185], v[160:161], v[158:159] op_sel_hi:[1,0,1]
	v_mov_b32_e32 v160, v237
	v_pk_fma_f32 v[158:159], v[186:187], v[234:235], v[158:159] op_sel_hi:[1,0,1]
	v_pk_fma_f32 v[158:159], v[188:189], v[234:235], v[158:159] op_sel:[0,1,0]
	v_pk_fma_f32 v[158:159], v[190:191], v[236:237], v[158:159] op_sel_hi:[1,0,1]
	v_pk_fma_f32 v[158:159], v[192:193], v[160:161], v[158:159] op_sel_hi:[1,0,1]
	v_pk_mul_f32 v[160:161], v[196:197], v[238:239] op_sel:[0,1]
	v_pk_fma_f32 v[160:161], v[194:195], v[238:239], v[160:161] op_sel_hi:[1,0,1]
	v_pk_fma_f32 v[160:161], v[198:199], v[240:241], v[160:161] op_sel_hi:[1,0,1]
	v_pk_fma_f32 v[160:161], v[200:201], v[230:231], v[160:161] op_sel_hi:[1,0,1]
	s_waitcnt lgkmcnt(0)
	v_mov_b32_e32 v230, v245
	v_pk_fma_f32 v[160:161], v[202:203], v[242:243], v[160:161] op_sel_hi:[1,0,1]
	v_pk_fma_f32 v[160:161], v[204:205], v[242:243], v[160:161] op_sel:[0,1,0]
	v_pk_fma_f32 v[160:161], v[206:207], v[244:245], v[160:161] op_sel_hi:[1,0,1]
	v_pk_fma_f32 v[160:161], v[176:177], v[230:231], v[160:161] op_sel_hi:[1,0,1]
	v_pk_add_f32 v[158:159], v[158:159], v[160:161]
	v_pk_fma_f32 v[158:159], v[128:129], v[174:175], v[158:159] op_sel:[0,1,0] op_sel_hi:[1,0,1]
	v_pk_fma_f32 v[174:175], v[126:127], v[174:175], v[158:159]
	s_nop 0
	v_cvt_pk_bf16_f32 v158, v174, s0
	v_cvt_pk_bf16_f32 v159, v175, s0
	s_add_i32 s0, s0, 64
	ds_write_b16 v2, v158
	ds_write_b16 v2, v159 offset:128
	v_add_u32_e32 v2, 0x110, v2
	s_cmpk_eq_i32 s0, 0x800
	s_cbranch_scc0 .LBB0_629
; #define LAS __attribute__((address_space(3)))
; DI f32x4 mfma16(bf16x8 a, bf16x8 b, f32x4 c) { return __builtin_amdgcn_mfma_f32_16x16x32_bf16(a, b, c, 0, 0, 0); }
; DI void s5_disc(const S5P& P, int dir, int g, int p, float& lr, float& li, f32x2 (&bb)[16]) {
;     const float dt = expf(P.log_dt[dir * 64 + g]); const float are = P.a_re[(dir * 64 + g) * 64 + p], aim = P.a_im[(dir * 64 + g) * 64 + p];
;     const float mag = expf(dt * are); lr = mag * cosf(dt * aim); li = mag * sinf(dt * aim);
;     const float den = are * are + aim * aim, nr = lr - 1.0f; const float cr = (nr * are + li * aim) / den, ci = (li * are - nr * aim) / den;
; template <int DIRN, int SUB> DI void s5_subtile(const LAS float* UF, LAS bf16* XT, float lr, float li, const f32x2 (&bb)[16], f32x2& x,
;                                                 const bf16x8 (&bfr)[4], f32x4& acc0, f32x4& acc1, int lane) {
;     ...
;     for (int ks = 0; ks < 4; ++ks) { const bf16x8 a0 = *(const LAS bf16x8*)(XT + (lane & 15) * 136 + 32 * ks + 8 * (lane >> 4)), a1 = *(const LAS bf16x8*)(XT + (16 + (lane & 15)) * 136 + 32 * ks + 8 * (lane >> 4));
;         acc0 = mfma16(a0, bfr[ks], acc0); acc1 = mfma16(a1, bfr[ks], acc1); }
	v_mfma_f32_16x16x32_bf16 v[58:61], v[70:73], v[50:53], v[58:61]
	v_readlane_b32 s72, v252, 4
	v_readlane_b32 s84, v252, 16
	v_readlane_b32 s85, v252, 17
	v_mfma_f32_16x16x32_bf16 v[66:69], v[66:69], v[50:53], v[86:89]
	v_readlane_b32 s82, v252, 14
	v_readlane_b32 s83, v252, 15
	s_mov_b32 s0, 0x3fb8aa3b
	v_mfma_f32_16x16x32_bf16 v[62:65], v[62:65], v[42:45], v[78:81]
	v_readlane_b32 s73, v252, 5
	v_readlane_b32 s74, v252, 6
	v_readlane_b32 s75, v252, 7
	v_mfma_f32_16x16x32_bf16 v[58:61], v[74:77], v[42:45], v[58:61]
	v_readlane_b32 s76, v252, 8
	v_readlane_b32 s77, v252, 9
	v_readlane_b32 s78, v252, 10
	v_mfma_f32_16x16x32_bf16 v[66:69], v[82:85], v[42:45], v[66:69]
	ds_read_b128 v[78:81], v1 offset:8192
	ds_read_b128 v[82:85], v1 offset:8256
	v_readlane_b32 s79, v252, 11
	v_readlane_b32 s80, v252, 12
	v_mfma_f32_16x16x32_bf16 v[74:77], v[90:93], v[46:49], 0
	ds_read_b128 v[86:89], v1 offset:12544
	ds_read_b128 v[90:93], v1 offset:12608
	global_load_dword v2, v3, s[22:23] offset:256
	v_readlane_b32 s81, v252, 13
	s_waitcnt lgkmcnt(1)
	v_mfma_f32_16x16x32_bf16 v[86:89], v[86:89], v[46:49], 0
	v_readlane_b32 s86, v252, 18
	v_readlane_b32 s87, v252, 19
	v_mfma_f32_16x16x32_bf16 v[70:73], v[94:97], v[46:49], 0
	ds_read_b128 v[94:97], v1 offset:8320
	v_mfma_f32_16x16x32_bf16 v[78:81], v[78:81], v[46:49], 0
	s_waitcnt lgkmcnt(1)
	v_mfma_f32_16x16x32_bf16 v[86:89], v[90:93], v[54:57], v[86:89]
	v_add_u32_e32 v90, 0x1000, v124
	v_ashrrev_i32_e32 v91, 31, v90
	v_lshlrev_b64 v[90:91], 2, v[90:91]
	v_lshl_add_u64 v[92:93], s[84:85], 0, v[90:91]
	v_mfma_f32_16x16x32_bf16 v[70:73], v[102:105], v[54:57], v[70:73]
	v_lshl_add_u64 v[90:91], s[82:83], 0, v[90:91]
	v_mfma_f32_16x16x32_bf16 v[74:77], v[98:101], v[54:57], v[74:77]
	v_mfma_f32_16x16x32_bf16 v[78:81], v[82:85], v[54:57], v[78:81]
	ds_read_b128 v[82:85], v1 offset:8384
	ds_read_b128 v[98:101], v1 offset:12672
	ds_read_b128 v[102:105], v1 offset:12736
	global_load_dword v93, v[92:93], off
	s_nop 0
	global_load_dword v92, v[90:91], off
	s_waitcnt lgkmcnt(3)
	v_mfma_f32_16x16x32_bf16 v[78:81], v[94:97], v[50:53], v[78:81]
	s_waitcnt lgkmcnt(2)
	v_mfma_f32_16x16x32_bf16 v[78:81], v[82:85], v[42:45], v[78:81]
	s_waitcnt vmcnt(2)
	v_mul_f32_e32 v82, 0x3fb8aa3b, v2
	v_fma_f32 v83, v2, s0, -v82
	v_rndne_f32_e32 v84, v82
	v_fmac_f32_e32 v83, 0x32a5705f, v2
	v_sub_f32_e32 v82, v82, v84
	v_add_f32_e32 v82, v82, v83
	s_waitcnt lgkmcnt(1)
	v_mfma_f32_16x16x32_bf16 v[86:89], v[98:101], v[50:53], v[86:89]
	v_cvt_i32_f32_e32 v90, v84
	v_exp_f32_e32 v91, v82
	s_mov_b32 s0, 0xc2ce8ed0
	v_mfma_f32_16x16x32_bf16 v[70:73], v[110:113], v[50:53], v[70:73]
	v_cmp_ngt_f32_e32 vcc, s0, v2
	s_mov_b32 s0, 0x42b17218
	v_mfma_f32_16x16x32_bf16 v[74:77], v[106:109], v[50:53], v[74:77]
	s_waitcnt lgkmcnt(0)
	v_mfma_f32_16x16x32_bf16 v[82:85], v[102:105], v[42:45], v[86:89]
	v_mfma_f32_16x16x32_bf16 v[70:73], v[118:121], v[42:45], v[70:73]
	s_nop 1
	v_ldexp_f32 v86, v91, v90
	v_cndmask_b32_e32 v86, 0, v86, vcc
	v_cmp_nlt_f32_e32 vcc, s0, v2
	v_mfma_f32_16x16x32_bf16 v[74:77], v[114:117], v[42:45], v[74:77]
	s_brev_b32 s0, 18
	v_cndmask_b32_e32 v86, v219, v86, vcc
	s_waitcnt vmcnt(1)
	v_mul_f32_e32 v87, v86, v93
	v_and_b32_e32 v88, 0x7fffffff, v87
	v_cmp_nlt_f32_e64 s[22:23], |v87|, s0
	s_and_saveexec_b64 s[0:1], s[22:23]
	s_xor_b64 s[24:25], exec, s[0:1]
	s_cbranch_execz .LBB0_632
	v_lshrrev_b32_e32 v2, 23, v88
	v_add_u32_e32 v2, 0xffffff88, v2
	v_cmp_lt_u32_e32 vcc, 63, v2
	s_mov_b32 s10, 0xfe5163ab
	s_nop 0
	v_cndmask_b32_e32 v89, 0, v220, vcc
	v_add_u32_e32 v2, v89, v2
	v_cmp_lt_u32_e64 s[0:1], 31, v2
	s_nop 1
	v_cndmask_b32_e64 v89, 0, v221, s[0:1]
	v_add_u32_e32 v2, v89, v2
	v_cmp_lt_u32_e64 s[8:9], 31, v2
	s_nop 1
	v_cndmask_b32_e64 v89, 0, v221, s[8:9]
	v_add_u32_e32 v89, v89, v2
	v_and_b32_e32 v2, 0x7fffff, v88
	v_or_b32_e32 v104, 0x800000, v2
	v_mad_u64_u32 v[90:91], s[10:11], v104, s10, 0
	v_mov_b32_e32 v2, v91
	s_mov_b32 s10, 0x3c439041
	v_mad_u64_u32 v[94:95], s[10:11], v104, s10, v[2:3]
	v_mov_b32_e32 v2, v95
	s_mov_b32 s10, 0xdb629599
	v_mad_u64_u32 v[96:97], s[10:11], v104, s10, v[2:3]
	v_mov_b32_e32 v2, v97
	s_mov_b32 s10, 0xf534ddc0
	v_mad_u64_u32 v[98:99], s[10:11], v104, s10, v[2:3]
	v_mov_b32_e32 v2, v99
	s_mov_b32 s10, 0xfc2757d1
	v_mad_u64_u32 v[100:101], s[10:11], v104, s10, v[2:3]
	v_mov_b32_e32 v2, v101
	s_mov_b32 s10, 0x4e441529
	v_mad_u64_u32 v[102:103], s[10:11], v104, s10, v[2:3]
	v_mov_b32_e32 v2, v103
	s_mov_b32 s10, 0xa2f9836e
	v_mad_u64_u32 v[104:105], s[10:11], v104, s10, v[2:3]
	v_cndmask_b32_e32 v91, v102, v98, vcc
	v_cndmask_b32_e32 v2, v104, v100, vcc
	v_cndmask_b32_e32 v97, v105, v102, vcc
	v_cndmask_b32_e64 v95, v2, v91, s[0:1]
	v_cndmask_b32_e64 v2, v97, v2, s[0:1]
	v_cndmask_b32_e32 v97, v100, v96, vcc
	v_cndmask_b32_e64 v91, v91, v97, s[0:1]
	v_sub_u32_e32 v99, 32, v89
	v_cmp_eq_u32_e64 s[10:11], 0, v89
	v_cndmask_b32_e32 v89, v98, v94, vcc
	v_cndmask_b32_e64 v2, v2, v95, s[8:9]
	v_cndmask_b32_e64 v95, v95, v91, s[8:9]
	v_cndmask_b32_e64 v94, v97, v89, s[0:1]
	v_alignbit_b32 v100, v2, v95, v99
	v_cndmask_b32_e64 v91, v91, v94, s[8:9]
	v_cndmask_b32_e64 v2, v100, v2, s[10:11]
	v_alignbit_b32 v97, v95, v91, v99
	v_cndmask_b32_e32 v90, v96, v90, vcc
	v_cndmask_b32_e64 v95, v97, v95, s[10:11]
	v_bfe_u32 v100, v2, 29, 1
	v_cndmask_b32_e64 v89, v89, v90, s[0:1]
	v_alignbit_b32 v97, v2, v95, 30
	v_sub_u32_e32 v101, 0, v100
	v_cndmask_b32_e64 v89, v94, v89, s[8:9]
	v_xor_b32_e32 v97, v97, v101
	v_alignbit_b32 v90, v91, v89, v99
	v_cndmask_b32_e64 v90, v90, v91, s[10:11]
	v_ffbh_u32_e32 v94, v97
	v_alignbit_b32 v91, v95, v90, 30
	v_min_u32_e32 v94, 32, v94
	v_alignbit_b32 v89, v90, v89, 30
	v_xor_b32_e32 v91, v91, v101
	v_sub_u32_e32 v95, 31, v94
	v_xor_b32_e32 v89, v89, v101
	v_alignbit_b32 v96, v97, v91, v95
	v_alignbit_b32 v89, v91, v89, v95
	v_alignbit_b32 v90, v96, v89, 9
	v_ffbh_u32_e32 v91, v90
	v_min_u32_e32 v91, 32, v91
	v_lshrrev_b32_e32 v98, 29, v2
	v_not_b32_e32 v95, v91
	v_alignbit_b32 v89, v90, v89, v95
	v_lshlrev_b32_e32 v90, 31, v98
	v_or_b32_e32 v95, 0x33000000, v90
	v_add_lshl_u32 v91, v91, v94, 23
	v_lshrrev_b32_e32 v89, 9, v89
	v_sub_u32_e32 v91, v95, v91
	v_or_b32_e32 v90, 0.5, v90
	v_lshlrev_b32_e32 v94, 23, v94
	v_or_b32_e32 v89, v91, v89
	v_lshrrev_b32_e32 v91, 9, v96
	v_sub_u32_e32 v90, v90, v94
	v_or_b32_e32 v90, v91, v90
	v_mul_f32_e32 v91, 0x3fc90fda, v90
	s_mov_b32 s0, 0x3fc90fda
	v_fma_f32 v94, v90, s0, -v91
	v_fmac_f32_e32 v94, 0x33a22168, v90
	v_fmac_f32_e32 v94, 0x3fc90fda, v89
	v_lshrrev_b32_e32 v2, 30, v2
	v_add_f32_e32 v90, v91, v94
	v_add_u32_e32 v89, v100, v2
	s_andn2_saveexec_b64 s[0:1], s[24:25]
	s_cbranch_execz .LBB0_634
	s_branch .LBB0_633

; template <int DIRN> DI void s5_dir(const S5P& P, const f32x2* END, const LAS float* UF, LAS bf16* XT, int b, int seg, int g, const bf16x8 (&bfr)[4], f32x4 (&acc)[8], int lane) {
;     ...
;     { float Lr = lr, Li = li;
; #pragma unroll
;         for (int i = 0; i < 7; ++i) { const float nr = Lr * Lr - Li * Li, ni = 2.0f * Lr * Li; Lr = nr; Li = ni; }
; #pragma unroll 8
;         for (int j = 0; j < sl; ++j) { const float* ep = (const float*)END + ((size_t)((b * 2 + DIRN) * SNSEG + j)) * 8192 + g * 128 + lane; const f32x2 e = {ep[0], ep[64]}; const float nr = Lr * xr - Li * xi + e.x, ni = Lr * xi + Li * xr + e.y; xr = nr; xi = ni; } }
.Ls5p1_blk_a:
	s_sub_i32 s0, s10, s9
	s_cmp_lt_i32 s0, 8
	s_cbranch_scc1 .Ls5p1_rem_a
	global_load_dword v184, v[200:201], off
	global_load_dword v185, v[200:201], off offset:256
	v_add_co_u32_e32 v200, vcc, 0x8000, v200
	s_nop 1
	v_addc_co_u32_e32 v201, vcc, 0, v201, vcc
	global_load_dword v186, v[200:201], off
	global_load_dword v187, v[200:201], off offset:256
	v_add_co_u32_e32 v200, vcc, 0x8000, v200
	s_nop 1
	v_addc_co_u32_e32 v201, vcc, 0, v201, vcc
	global_load_dword v188, v[200:201], off
	global_load_dword v189, v[200:201], off offset:256
	v_add_co_u32_e32 v200, vcc, 0x8000, v200
	s_nop 1
	v_addc_co_u32_e32 v201, vcc, 0, v201, vcc
	global_load_dword v190, v[200:201], off
	global_load_dword v191, v[200:201], off offset:256
	v_add_co_u32_e32 v200, vcc, 0x8000, v200
	s_nop 1
	v_addc_co_u32_e32 v201, vcc, 0, v201, vcc
	global_load_dword v192, v[200:201], off
	global_load_dword v193, v[200:201], off offset:256
	v_add_co_u32_e32 v200, vcc, 0x8000, v200
	s_nop 1
	v_addc_co_u32_e32 v201, vcc, 0, v201, vcc
	global_load_dword v194, v[200:201], off
	global_load_dword v195, v[200:201], off offset:256
	v_add_co_u32_e32 v200, vcc, 0x8000, v200
	s_nop 1
	v_addc_co_u32_e32 v201, vcc, 0, v201, vcc
	global_load_dword v196, v[200:201], off
	global_load_dword v197, v[200:201], off offset:256
	v_add_co_u32_e32 v200, vcc, 0x8000, v200
	s_nop 1
	v_addc_co_u32_e32 v201, vcc, 0, v201, vcc
	global_load_dword v198, v[200:201], off
	global_load_dword v199, v[200:201], off offset:256
	v_add_co_u32_e32 v200, vcc, 0x8000, v200
	s_nop 1
	v_addc_co_u32_e32 v201, vcc, 0, v201, vcc
	v_pk_mul_f32 v[100:101], v[94:95], v[90:91]
	v_pk_fma_f32 v[104:105], v[96:97], v[90:91], v[100:101] op_sel:[0,0,1] op_sel_hi:[1,1,0] neg_lo:[0,0,1] neg_hi:[0,0,1]
	v_pk_fma_f32 v[90:91], v[96:97], v[90:91], v[100:101] op_sel:[0,0,1] op_sel_hi:[1,1,0]
	s_nop 0
	v_mov_b32_e32 v105, v91
	s_waitcnt vmcnt(14) lgkmcnt(0)
	v_pk_add_f32 v[90:91], v[104:105], v[184:185]
	v_pk_mul_f32 v[100:101], v[94:95], v[90:91]
	v_pk_fma_f32 v[104:105], v[96:97], v[90:91], v[100:101] op_sel:[0,0,1] op_sel_hi:[1,1,0] neg_lo:[0,0,1] neg_hi:[0,0,1]
	v_pk_fma_f32 v[90:91], v[96:97], v[90:91], v[100:101] op_sel:[0,0,1] op_sel_hi:[1,1,0]
	s_nop 0
	v_mov_b32_e32 v105, v91
	s_waitcnt vmcnt(12)
	v_pk_add_f32 v[90:91], v[104:105], v[186:187]
	v_pk_mul_f32 v[100:101], v[94:95], v[90:91]
	v_pk_fma_f32 v[104:105], v[96:97], v[90:91], v[100:101] op_sel:[0,0,1] op_sel_hi:[1,1,0] neg_lo:[0,0,1] neg_hi:[0,0,1]
	v_pk_fma_f32 v[90:91], v[96:97], v[90:91], v[100:101] op_sel:[0,0,1] op_sel_hi:[1,1,0]
	s_nop 0
	v_mov_b32_e32 v105, v91
	s_waitcnt vmcnt(10)
	v_pk_add_f32 v[90:91], v[104:105], v[188:189]
	v_pk_mul_f32 v[100:101], v[94:95], v[90:91]
	v_pk_fma_f32 v[104:105], v[96:97], v[90:91], v[100:101] op_sel:[0,0,1] op_sel_hi:[1,1,0] neg_lo:[0,0,1] neg_hi:[0,0,1]
	v_pk_fma_f32 v[90:91], v[96:97], v[90:91], v[100:101] op_sel:[0,0,1] op_sel_hi:[1,1,0]
	s_nop 0
	v_mov_b32_e32 v105, v91
	s_waitcnt vmcnt(8)
	v_pk_add_f32 v[90:91], v[104:105], v[190:191]
	v_pk_mul_f32 v[100:101], v[94:95], v[90:91]
	v_pk_fma_f32 v[104:105], v[96:97], v[90:91], v[100:101] op_sel:[0,0,1] op_sel_hi:[1,1,0] neg_lo:[0,0,1] neg_hi:[0,0,1]
	v_pk_fma_f32 v[90:91], v[96:97], v[90:91], v[100:101] op_sel:[0,0,1] op_sel_hi:[1,1,0]
	s_nop 0
	v_mov_b32_e32 v105, v91
	s_waitcnt vmcnt(6)
	v_pk_add_f32 v[90:91], v[104:105], v[192:193]
	v_pk_mul_f32 v[100:101], v[94:95], v[90:91]
	v_pk_fma_f32 v[104:105], v[96:97], v[90:91], v[100:101] op_sel:[0,0,1] op_sel_hi:[1,1,0] neg_lo:[0,0,1] neg_hi:[0,0,1]
	v_pk_fma_f32 v[90:91], v[96:97], v[90:91], v[100:101] op_sel:[0,0,1] op_sel_hi:[1,1,0]
	s_nop 0
	v_mov_b32_e32 v105, v91
	s_waitcnt vmcnt(4)
	v_pk_add_f32 v[90:91], v[104:105], v[194:195]
	v_pk_mul_f32 v[100:101], v[94:95], v[90:91]
	v_pk_fma_f32 v[104:105], v[96:97], v[90:91], v[100:101] op_sel:[0,0,1] op_sel_hi:[1,1,0] neg_lo:[0,0,1] neg_hi:[0,0,1]
	v_pk_fma_f32 v[90:91], v[96:97], v[90:91], v[100:101] op_sel:[0,0,1] op_sel_hi:[1,1,0]
	s_nop 0
	v_mov_b32_e32 v105, v91
	s_waitcnt vmcnt(2)
	v_pk_add_f32 v[90:91], v[104:105], v[196:197]
	v_pk_mul_f32 v[100:101], v[94:95], v[90:91]
	v_pk_fma_f32 v[104:105], v[96:97], v[90:91], v[100:101] op_sel:[0,0,1] op_sel_hi:[1,1,0] neg_lo:[0,0,1] neg_hi:[0,0,1]
	v_pk_fma_f32 v[90:91], v[96:97], v[90:91], v[100:101] op_sel:[0,0,1] op_sel_hi:[1,1,0]
	s_nop 0
	v_mov_b32_e32 v105, v91
	s_waitcnt vmcnt(0)
	v_pk_add_f32 v[90:91], v[104:105], v[198:199]
	s_add_i32 s9, s9, 8
	s_branch .Ls5p1_blk_a

; template <int DIRN> DI void s5_dir(const S5P& P, const f32x2* END, const LAS float* UF, LAS bf16* XT, int b, int seg, int g, const bf16x8 (&bfr)[4], f32x4 (&acc)[8], int lane) {
;     ...
; #pragma unroll 8
;         for (int j = 0; j < sl; ++j) { const float* ep = (const float*)END + ((size_t)((b * 2 + DIRN) * SNSEG + j)) * 8192 + g * 128 + lane; const f32x2 e = {ep[0], ep[64]}; const float nr = Lr * xr - Li * xi + e.x, ni = Lr * xi + Li * xr + e.y; xr = nr; xi = ni; } }
.Ls5p1_reml_a:
	global_load_dword v184, v[200:201], off
	global_load_dword v185, v[200:201], off offset:256
	v_add_co_u32_e32 v200, vcc, 0x8000, v200
	s_nop 1
	v_addc_co_u32_e32 v201, vcc, 0, v201, vcc
	v_pk_mul_f32 v[100:101], v[94:95], v[90:91]
	v_pk_fma_f32 v[104:105], v[96:97], v[90:91], v[100:101] op_sel:[0,0,1] op_sel_hi:[1,1,0] neg_lo:[0,0,1] neg_hi:[0,0,1]
	v_pk_fma_f32 v[90:91], v[96:97], v[90:91], v[100:101] op_sel:[0,0,1] op_sel_hi:[1,1,0]
	s_nop 0
	v_mov_b32_e32 v105, v91
	s_waitcnt vmcnt(0) lgkmcnt(0)
	v_pk_add_f32 v[90:91], v[104:105], v[184:185]
	s_add_i32 s0, s0, -1
	s_cmp_lg_u32 s0, 0
	s_cbranch_scc1 .Ls5p1_reml_a
	s_branch .LBB0_650

; #define LAS __attribute__((address_space(3)))
; DI unsigned pk2(float lo, float hi) { return pg8::cvt_pk_bf16(lo, hi); }
; DI f32x4 mfma16(bf16x8 a, bf16x8 b, f32x4 c) { return __builtin_amdgcn_mfma_f32_16x16x32_bf16(a, b, c, 0, 0, 0); }
; template <int DIRN, int SUB> DI void s5_subtile(const LAS float* UF, LAS bf16* XT, float lr, float li, const f32x2 (&bb)[16], f32x2& x,
;                                                 const bf16x8 (&bfr)[4], f32x4& acc0, f32x4& acc1, int lane) {
; #pragma unroll 1
;     for (int i = 0; i < 32; ++i) { const int r = DIRN ? 31 - i : i;
;         x = s5_step((const LAS f32x4*)(UF + (32 * SUB + r) * 16), bb, lr, li, x);
;         const unsigned pkd = pk2(x.x, x.y); XT[r * 136 + lane] = (bf16)(pkd & 0xffffu); XT[r * 136 + 64 + lane] = (bf16)(pkd >> 16); }
; #pragma unroll
;     for (int ks = 0; ks < 4; ++ks) { const bf16x8 a0 = *(const LAS bf16x8*)(XT + (lane & 15) * 136 + 32 * ks + 8 * (lane >> 4)), a1 = *(const LAS bf16x8*)(XT + (16 + (lane & 15)) * 136 + 32 * ks + 8 * (lane >> 4));
;         acc0 = mfma16(a0, bfr[ks], acc0); acc1 = mfma16(a1, bfr[ks], acc1); }
.LBB0_651:
	s_add_i32 s1, s53, s0
	v_mov_b32_e32 v18, s1
	ds_read_b128 v[6:9], v18
	ds_read_b128 v[10:13], v18 offset:16
	ds_read_b128 v[14:17], v18 offset:32
	ds_read_b128 v[18:21], v18 offset:48
	s_waitcnt lgkmcnt(3)
	v_pk_mul_f32 v[22:23], v[96:97], v[6:7] op_sel:[0,1]
	v_pk_fma_f32 v[6:7], v[94:95], v[6:7], v[22:23] op_sel_hi:[1,0,1]
	v_pk_fma_f32 v[6:7], v[34:35], v[8:9], v[6:7] op_sel_hi:[1,0,1]
	v_mov_b32_e32 v8, v9
	v_pk_fma_f32 v[6:7], v[30:31], v[8:9], v[6:7] op_sel_hi:[1,0,1]
	s_waitcnt lgkmcnt(2)
	v_mov_b32_e32 v8, v13
	v_pk_fma_f32 v[6:7], v[32:33], v[10:11], v[6:7] op_sel_hi:[1,0,1]
	v_pk_fma_f32 v[6:7], v[36:37], v[10:11], v[6:7] op_sel:[0,1,0]
	s_waitcnt lgkmcnt(1)
	v_mov_b32_e32 v10, v17
	v_pk_fma_f32 v[6:7], v[98:99], v[12:13], v[6:7] op_sel_hi:[1,0,1]
	v_pk_fma_f32 v[6:7], v[100:101], v[8:9], v[6:7] op_sel_hi:[1,0,1]
	v_pk_mul_f32 v[8:9], v[104:105], v[14:15] op_sel:[0,1]
	v_pk_fma_f32 v[8:9], v[102:103], v[14:15], v[8:9] op_sel_hi:[1,0,1]
	v_pk_fma_f32 v[8:9], v[106:107], v[16:17], v[8:9] op_sel_hi:[1,0,1]
	v_pk_fma_f32 v[8:9], v[108:109], v[10:11], v[8:9] op_sel_hi:[1,0,1]
	s_waitcnt lgkmcnt(0)
	v_mov_b32_e32 v10, v21
	v_pk_fma_f32 v[8:9], v[110:111], v[18:19], v[8:9] op_sel_hi:[1,0,1]
	v_pk_fma_f32 v[8:9], v[112:113], v[18:19], v[8:9] op_sel:[0,1,0]
	v_pk_fma_f32 v[8:9], v[114:115], v[20:21], v[8:9] op_sel_hi:[1,0,1]
	v_pk_fma_f32 v[8:9], v[92:93], v[10:11], v[8:9] op_sel_hi:[1,0,1]
	v_pk_add_f32 v[6:7], v[6:7], v[8:9]
	v_pk_fma_f32 v[6:7], v[88:89], v[90:91], v[6:7] op_sel:[0,1,0] op_sel_hi:[1,0,1]
	v_pk_fma_f32 v[90:91], v[86:87], v[90:91], v[6:7]
	s_nop 0
	v_cvt_pk_bf16_f32 v6, v90, s0
	v_cvt_pk_bf16_f32 v7, v91, s0
	s_sub_i32 s0, s0, 64
	ds_write_b16 v2, v6
	ds_write_b16 v2, v7 offset:128
	v_add_u32_e32 v2, 0xfffffef0, v2
	s_cmpk_lg_i32 s0, 0xf800
	s_cbranch_scc1 .LBB0_651
	ds_read_b128 v[6:9], v1 offset:8192
	ds_read_b128 v[10:13], v1 offset:12544
	ds_read_b128 v[14:17], v1 offset:8256
	ds_read_b128 v[18:21], v1 offset:12608
	v_add_u32_e32 v2, 0x40f0, v152
	s_movk_i32 s0, 0x17c0
	s_waitcnt lgkmcnt(3)
	v_mfma_f32_16x16x32_bf16 v[6:9], v[6:9], v[46:49], v[78:81]
	v_readlane_b32 s8, v253, 21
	v_readlane_b32 s9, v253, 22
	s_waitcnt lgkmcnt(2)
	v_mfma_f32_16x16x32_bf16 v[10:13], v[10:13], v[46:49], v[82:85]
	s_waitcnt lgkmcnt(1)
	v_mfma_f32_16x16x32_bf16 v[6:9], v[14:17], v[54:57], v[6:9]
	s_waitcnt lgkmcnt(0)
	v_mfma_f32_16x16x32_bf16 v[10:13], v[18:21], v[54:57], v[10:13]
	ds_read_b128 v[14:17], v1 offset:8320
	ds_read_b128 v[18:21], v1 offset:12672
	s_waitcnt lgkmcnt(1)
	v_mfma_f32_16x16x32_bf16 v[6:9], v[14:17], v[50:53], v[6:9]
	s_waitcnt lgkmcnt(0)
	v_mfma_f32_16x16x32_bf16 v[14:17], v[18:21], v[50:53], v[10:13]
	s_nop 2
	ds_read_b128 v[10:13], v1 offset:8384
	ds_read_b128 v[18:21], v1 offset:12736
	s_waitcnt lgkmcnt(1)
	v_mfma_f32_16x16x32_bf16 v[10:13], v[10:13], v[42:45], v[6:9]
	s_waitcnt lgkmcnt(0)
	v_mfma_f32_16x16x32_bf16 v[6:9], v[18:21], v[42:45], v[14:17]
	s_nop 2
	v_mov_b32_e32 v14, v2
.LBB0_653:
	s_add_i32 s1, s49, s0
	v_mov_b32_e32 v15, s1
	ds_read_b128 v[16:19], v15
	ds_read_b128 v[20:23], v15 offset:16
	ds_read_b128 v[24:27], v15 offset:32
	ds_read_b128 v[78:81], v15 offset:48
	s_waitcnt lgkmcnt(3)
	v_pk_mul_f32 v[28:29], v[96:97], v[16:17] op_sel:[0,1]
	v_pk_fma_f32 v[16:17], v[94:95], v[16:17], v[28:29] op_sel_hi:[1,0,1]
	v_pk_fma_f32 v[16:17], v[34:35], v[18:19], v[16:17] op_sel_hi:[1,0,1]
	v_mov_b32_e32 v18, v19
	v_pk_fma_f32 v[16:17], v[30:31], v[18:19], v[16:17] op_sel_hi:[1,0,1]
	s_waitcnt lgkmcnt(2)
	v_mov_b32_e32 v18, v23
	v_pk_fma_f32 v[16:17], v[32:33], v[20:21], v[16:17] op_sel_hi:[1,0,1]
	v_pk_fma_f32 v[16:17], v[36:37], v[20:21], v[16:17] op_sel:[0,1,0]
	s_waitcnt lgkmcnt(1)
	v_mov_b32_e32 v20, v27
	v_pk_fma_f32 v[16:17], v[98:99], v[22:23], v[16:17] op_sel_hi:[1,0,1]
	v_pk_fma_f32 v[16:17], v[100:101], v[18:19], v[16:17] op_sel_hi:[1,0,1]
	v_pk_mul_f32 v[18:19], v[104:105], v[24:25] op_sel:[0,1]
	v_pk_fma_f32 v[18:19], v[102:103], v[24:25], v[18:19] op_sel_hi:[1,0,1]
	v_pk_fma_f32 v[18:19], v[106:107], v[26:27], v[18:19] op_sel_hi:[1,0,1]
	v_pk_fma_f32 v[18:19], v[108:109], v[20:21], v[18:19] op_sel_hi:[1,0,1]
	s_waitcnt lgkmcnt(0)
	v_mov_b32_e32 v20, v81
	v_pk_fma_f32 v[18:19], v[110:111], v[78:79], v[18:19] op_sel_hi:[1,0,1]
	v_pk_fma_f32 v[18:19], v[112:113], v[78:79], v[18:19] op_sel:[0,1,0]
	v_pk_fma_f32 v[18:19], v[114:115], v[80:81], v[18:19] op_sel_hi:[1,0,1]
	v_pk_fma_f32 v[18:19], v[92:93], v[20:21], v[18:19] op_sel_hi:[1,0,1]
	v_pk_add_f32 v[16:17], v[16:17], v[18:19]
	v_pk_fma_f32 v[16:17], v[88:89], v[90:91], v[16:17] op_sel:[0,1,0] op_sel_hi:[1,0,1]
	v_pk_fma_f32 v[90:91], v[86:87], v[90:91], v[16:17]
	v_add_u32_e32 v17, s49, v14
	v_cvt_pk_bf16_f32 v15, v90, s0
	v_cvt_pk_bf16_f32 v16, v91, s0
	s_sub_i32 s0, s0, 64
	v_add_u32_e32 v14, 0xfffffef0, v14
	s_cmpk_lg_i32 s0, 0xfc0
	ds_write_b16 v17, v15
	ds_write_b16 v17, v16 offset:128
	s_cbranch_scc1 .LBB0_653
	ds_read_b128 v[14:17], v1 offset:8192
	ds_read_b128 v[22:25], v1 offset:8256
	ds_read_b128 v[18:21], v1 offset:12544
	s_movk_i32 s0, 0xfc0
	s_waitcnt lgkmcnt(2)
	v_mfma_f32_16x16x32_bf16 v[14:17], v[14:17], v[46:49], v[70:73]
	s_waitcnt lgkmcnt(1)
	v_mfma_f32_16x16x32_bf16 v[14:17], v[22:25], v[54:57], v[14:17]
	ds_read_b128 v[22:25], v1 offset:12608
	s_waitcnt lgkmcnt(1)
	v_mfma_f32_16x16x32_bf16 v[18:21], v[18:21], v[46:49], v[74:77]
	s_waitcnt lgkmcnt(0)
	v_mfma_f32_16x16x32_bf16 v[18:21], v[22:25], v[54:57], v[18:21]
	ds_read_b128 v[22:25], v1 offset:8320
	s_waitcnt lgkmcnt(0)
	v_mfma_f32_16x16x32_bf16 v[14:17], v[22:25], v[50:53], v[14:17]
	ds_read_b128 v[22:25], v1 offset:12672
	s_waitcnt lgkmcnt(0)
	v_mfma_f32_16x16x32_bf16 v[24:27], v[22:25], v[50:53], v[18:21]
	s_nop 2
	ds_read_b128 v[18:21], v1 offset:8384
	v_mov_b32_e32 v22, v2
	s_waitcnt lgkmcnt(0)
	v_mfma_f32_16x16x32_bf16 v[18:21], v[18:21], v[42:45], v[14:17]
	s_nop 2
	ds_read_b128 v[14:17], v1 offset:12736
	s_waitcnt lgkmcnt(0)
	v_mfma_f32_16x16x32_bf16 v[14:17], v[14:17], v[42:45], v[24:27]
; #define LAS __attribute__((address_space(3)))
; DI unsigned pk2(float lo, float hi) { return pg8::cvt_pk_bf16(lo, hi); }
; DI f32x4 mfma16(bf16x8 a, bf16x8 b, f32x4 c) { return __builtin_amdgcn_mfma_f32_16x16x32_bf16(a, b, c, 0, 0, 0); }
; template <int DIRN, int SUB> DI void s5_subtile(const LAS float* UF, LAS bf16* XT, float lr, float li, const f32x2 (&bb)[16], f32x2& x,
;                                                 const bf16x8 (&bfr)[4], f32x4& acc0, f32x4& acc1, int lane) {
; #pragma unroll 1
;     for (int i = 0; i < 32; ++i) { const int r = DIRN ? 31 - i : i;
;         x = s5_step((const LAS f32x4*)(UF + (32 * SUB + r) * 16), bb, lr, li, x);
;         const unsigned pkd = pk2(x.x, x.y); XT[r * 136 + lane] = (bf16)(pkd & 0xffffu); XT[r * 136 + 64 + lane] = (bf16)(pkd >> 16); }
; #pragma unroll
;     for (int ks = 0; ks < 4; ++ks) { const bf16x8 a0 = *(const LAS bf16x8*)(XT + (lane & 15) * 136 + 32 * ks + 8 * (lane >> 4)), a1 = *(const LAS bf16x8*)(XT + (16 + (lane & 15)) * 136 + 32 * ks + 8 * (lane >> 4));
;         acc0 = mfma16(a0, bfr[ks], acc0); acc1 = mfma16(a1, bfr[ks], acc1); }
.LBB0_655:
	s_add_i32 s1, s49, s0
	v_mov_b32_e32 v23, s1
	s_nop 0
	ds_read_b128 v[24:27], v23
	ds_read_b128 v[70:73], v23 offset:16
	ds_read_b128 v[74:77], v23 offset:32
	ds_read_b128 v[78:81], v23 offset:48
	s_waitcnt lgkmcnt(3)
	v_pk_mul_f32 v[28:29], v[96:97], v[24:25] op_sel:[0,1]
	v_pk_fma_f32 v[24:25], v[94:95], v[24:25], v[28:29] op_sel_hi:[1,0,1]
	s_waitcnt lgkmcnt(1)
	v_mov_b32_e32 v28, v77
	v_pk_fma_f32 v[24:25], v[34:35], v[26:27], v[24:25] op_sel_hi:[1,0,1]
	v_mov_b32_e32 v26, v27
	v_pk_fma_f32 v[24:25], v[30:31], v[26:27], v[24:25] op_sel_hi:[1,0,1]
	v_mov_b32_e32 v26, v73
	v_pk_fma_f32 v[24:25], v[32:33], v[70:71], v[24:25] op_sel_hi:[1,0,1]
	v_pk_fma_f32 v[24:25], v[36:37], v[70:71], v[24:25] op_sel:[0,1,0]
	v_pk_fma_f32 v[24:25], v[98:99], v[72:73], v[24:25] op_sel_hi:[1,0,1]
	v_pk_fma_f32 v[24:25], v[100:101], v[26:27], v[24:25] op_sel_hi:[1,0,1]
	v_pk_mul_f32 v[26:27], v[104:105], v[74:75] op_sel:[0,1]
	v_pk_fma_f32 v[26:27], v[102:103], v[74:75], v[26:27] op_sel_hi:[1,0,1]
	v_pk_fma_f32 v[26:27], v[106:107], v[76:77], v[26:27] op_sel_hi:[1,0,1]
	v_pk_fma_f32 v[26:27], v[108:109], v[28:29], v[26:27] op_sel_hi:[1,0,1]
	s_waitcnt lgkmcnt(0)
	v_mov_b32_e32 v28, v81
	v_pk_fma_f32 v[26:27], v[110:111], v[78:79], v[26:27] op_sel_hi:[1,0,1]
	v_pk_fma_f32 v[26:27], v[112:113], v[78:79], v[26:27] op_sel:[0,1,0]
	v_pk_fma_f32 v[26:27], v[114:115], v[80:81], v[26:27] op_sel_hi:[1,0,1]
	v_pk_fma_f32 v[26:27], v[92:93], v[28:29], v[26:27] op_sel_hi:[1,0,1]
	v_pk_add_f32 v[24:25], v[24:25], v[26:27]
	v_pk_fma_f32 v[24:25], v[88:89], v[90:91], v[24:25] op_sel:[0,1,0] op_sel_hi:[1,0,1]
	v_pk_fma_f32 v[90:91], v[86:87], v[90:91], v[24:25]
	v_add_u32_e32 v25, s49, v22
	v_cvt_pk_bf16_f32 v23, v90, s0
	v_cvt_pk_bf16_f32 v24, v91, s0
	s_sub_i32 s0, s0, 64
	v_add_u32_e32 v22, 0xfffffef0, v22
	s_cmpk_lg_i32 s0, 0x7c0
	ds_write_b16 v25, v23
	ds_write_b16 v25, v24 offset:128
	s_cbranch_scc1 .LBB0_655
	ds_read_b128 v[22:25], v1 offset:8192
	ds_read_b128 v[26:29], v1 offset:12544
	s_movk_i32 s0, 0x7c0
	s_waitcnt lgkmcnt(1)
	v_mfma_f32_16x16x32_bf16 v[22:25], v[22:25], v[46:49], v[62:65]
	s_nop 2
	ds_read_b128 v[62:65], v1 offset:8256
	s_waitcnt lgkmcnt(1)
	v_mfma_f32_16x16x32_bf16 v[26:29], v[26:29], v[46:49], v[66:69]
	s_waitcnt lgkmcnt(0)
	v_mfma_f32_16x16x32_bf16 v[22:25], v[62:65], v[54:57], v[22:25]
	ds_read_b128 v[62:65], v1 offset:12608
	s_waitcnt lgkmcnt(0)
	v_mfma_f32_16x16x32_bf16 v[26:29], v[62:65], v[54:57], v[26:29]
	ds_read_b128 v[62:65], v1 offset:8320
	s_waitcnt lgkmcnt(0)
	v_mfma_f32_16x16x32_bf16 v[22:25], v[62:65], v[50:53], v[22:25]
	ds_read_b128 v[62:65], v1 offset:12672
	s_waitcnt lgkmcnt(0)
	v_mfma_f32_16x16x32_bf16 v[62:65], v[62:65], v[50:53], v[26:29]
	s_nop 2
	ds_read_b128 v[26:29], v1 offset:8384
	s_waitcnt lgkmcnt(0)
	v_mfma_f32_16x16x32_bf16 v[26:29], v[26:29], v[42:45], v[22:25]
	s_nop 2
	ds_read_b128 v[22:25], v1 offset:12736
	s_waitcnt lgkmcnt(0)
	v_mfma_f32_16x16x32_bf16 v[22:25], v[22:25], v[42:45], v[62:65]
.LBB0_657:
	s_add_i32 s1, s49, s0
	v_mov_b32_e32 v74, s1
	s_nop 0
	ds_read_b128 v[62:65], v74
	ds_read_b128 v[66:69], v74 offset:16
	ds_read_b128 v[70:73], v74 offset:32
	ds_read_b128 v[74:77], v74 offset:48
	s_waitcnt lgkmcnt(3)
	v_pk_mul_f32 v[78:79], v[96:97], v[62:63] op_sel:[0,1]
	v_pk_fma_f32 v[62:63], v[94:95], v[62:63], v[78:79] op_sel_hi:[1,0,1]
	v_pk_fma_f32 v[62:63], v[34:35], v[64:65], v[62:63] op_sel_hi:[1,0,1]
	v_mov_b32_e32 v64, v65
	v_pk_fma_f32 v[62:63], v[30:31], v[64:65], v[62:63] op_sel_hi:[1,0,1]
	s_waitcnt lgkmcnt(2)
	v_mov_b32_e32 v64, v69
	v_pk_fma_f32 v[62:63], v[32:33], v[66:67], v[62:63] op_sel_hi:[1,0,1]
	v_pk_fma_f32 v[62:63], v[36:37], v[66:67], v[62:63] op_sel:[0,1,0]
	s_waitcnt lgkmcnt(1)
	v_mov_b32_e32 v66, v73
	v_pk_fma_f32 v[62:63], v[98:99], v[68:69], v[62:63] op_sel_hi:[1,0,1]
	v_pk_fma_f32 v[62:63], v[100:101], v[64:65], v[62:63] op_sel_hi:[1,0,1]
	v_pk_mul_f32 v[64:65], v[104:105], v[70:71] op_sel:[0,1]
	v_pk_fma_f32 v[64:65], v[102:103], v[70:71], v[64:65] op_sel_hi:[1,0,1]
	v_pk_fma_f32 v[64:65], v[106:107], v[72:73], v[64:65] op_sel_hi:[1,0,1]
	v_pk_fma_f32 v[64:65], v[108:109], v[66:67], v[64:65] op_sel_hi:[1,0,1]
	s_waitcnt lgkmcnt(0)
	v_mov_b32_e32 v66, v77
	v_pk_fma_f32 v[64:65], v[110:111], v[74:75], v[64:65] op_sel_hi:[1,0,1]
	v_pk_fma_f32 v[64:65], v[112:113], v[74:75], v[64:65] op_sel:[0,1,0]
	v_pk_fma_f32 v[64:65], v[114:115], v[76:77], v[64:65] op_sel_hi:[1,0,1]
	v_pk_fma_f32 v[64:65], v[92:93], v[66:67], v[64:65] op_sel_hi:[1,0,1]
	v_pk_add_f32 v[62:63], v[62:63], v[64:65]
	v_add_u32_e32 v64, s49, v2
	v_pk_fma_f32 v[62:63], v[88:89], v[90:91], v[62:63] op_sel:[0,1,0] op_sel_hi:[1,0,1]
	v_add_u32_e32 v2, 0xfffffef0, v2
	v_pk_fma_f32 v[90:91], v[86:87], v[90:91], v[62:63]
	s_nop 0
	v_cvt_pk_bf16_f32 v62, v90, s0
	v_cvt_pk_bf16_f32 v63, v91, s0
	s_sub_i32 s0, s0, 64
	s_cmpk_eq_i32 s0, 0xffc0
	ds_write_b16 v64, v62
	ds_write_b16 v64, v63 offset:128
	s_cbranch_scc0 .LBB0_657
; #define LAS __attribute__((address_space(3)))
; DI bf16 f2bf(float f) { return (bf16)(pk2(f, 0.f) & 0xffffu); }
; DI float gelu_tanh(float x) { const float u = 0.7978845608028654f * (x + 0.044715f * x * x * x); return x * sigm(2.0f * u); }
; DI f32x4 mfma16(bf16x8 a, bf16x8 b, f32x4 c) { return __builtin_amdgcn_mfma_f32_16x16x32_bf16(a, b, c, 0, 0, 0); }
; template <int DIRN, int SUB> DI void s5_subtile(const LAS float* UF, LAS bf16* XT, float lr, float li, const f32x2 (&bb)[16], f32x2& x,
;                                                 const bf16x8 (&bfr)[4], f32x4& acc0, f32x4& acc1, int lane) {
;     ...
;     for (int ks = 0; ks < 4; ++ks) { const bf16x8 a0 = *(const LAS bf16x8*)(XT + (lane & 15) * 136 + 32 * ks + 8 * (lane >> 4)), a1 = *(const LAS bf16x8*)(XT + (16 + (lane & 15)) * 136 + 32 * ks + 8 * (lane >> 4));
;         acc0 = mfma16(a0, bfr[ks], acc0); acc1 = mfma16(a1, bfr[ks], acc1); }
; DI void s5_passC(const Ctx& C, const S5P& P, const bf16* PROJ, const f32x2* END, bf16* YG  , int item_lo, int item_hi) {
;     ...
;         const float dv = P.d[g * 16 + (lane & 15)];
; #pragma unroll
;         for (int r = 0; r < 8; ++r)
; #pragma unroll
;             for (int j = 0; j < 4; ++j) { const int t = 16 * r + (lane >> 4) * 4 + j; const float y = acc[r][j] + dv * UF[t * 16 + (lane & 15)]; YG[(tok0 + t) * 1024 + g * 16 + (lane & 15)] = f2bf(gelu_tanh(y)); }
	ds_read_b128 v[30:33], v1 offset:8192
	ds_read_b128 v[34:37], v1 offset:12544
	v_lshlrev_b32_e32 v2, 2, v125
	v_readlane_b32 s72, v252, 20
	v_readlane_b32 s80, v252, 28
	s_waitcnt lgkmcnt(1)
	v_mfma_f32_16x16x32_bf16 v[30:33], v[30:33], v[46:49], v[38:41]
	v_readlane_b32 s81, v252, 29
	s_lshl_b32 s0, s67, 5
	s_add_u32 s0, s47, s0
	s_waitcnt lgkmcnt(0)
	v_mfma_f32_16x16x32_bf16 v[34:37], v[34:37], v[46:49], v[58:61]
	ds_read_b128 v[38:41], v1 offset:8256
	ds_read_b128 v[46:49], v1 offset:12608
	s_addc_u32 s1, s48, 0
	s_add_i32 s31, s31, s8
	s_waitcnt lgkmcnt(1)
	v_mfma_f32_16x16x32_bf16 v[30:33], v[38:41], v[54:57], v[30:33]
	v_readlane_b32 s76, v252, 24
	v_readlane_b32 s77, v252, 25
	v_readlane_b32 s78, v252, 26
	s_waitcnt lgkmcnt(0)
	v_mfma_f32_16x16x32_bf16 v[34:37], v[46:49], v[54:57], v[34:37]
	ds_read_b128 v[38:41], v1 offset:8320
	ds_read_b128 v[46:49], v1 offset:12672
	v_readlane_b32 s79, v252, 27
	v_readlane_b32 s73, v252, 21
	s_waitcnt lgkmcnt(1)
	v_mfma_f32_16x16x32_bf16 v[30:33], v[38:41], v[50:53], v[30:33]
	v_readlane_b32 s74, v252, 22
	v_readlane_b32 s75, v252, 23
	v_readlane_b32 s82, v252, 30
	s_waitcnt lgkmcnt(0)
	v_mfma_f32_16x16x32_bf16 v[38:41], v[46:49], v[50:53], v[34:37]
	s_nop 2
	ds_read_b128 v[34:37], v1 offset:8384
	ds_read_b128 v[46:49], v1 offset:12736
	v_lshl_or_b32 v1, s67, 6, v2
	global_load_dword v1, v1, s[80:81]
	s_waitcnt lgkmcnt(1)
	v_mfma_f32_16x16x32_bf16 v[34:37], v[34:37], v[42:45], v[30:33]
	v_readlane_b32 s83, v252, 31
	v_readlane_b32 s84, v252, 32
	v_readlane_b32 s85, v252, 33
	s_waitcnt lgkmcnt(0)
	v_mfma_f32_16x16x32_bf16 v[30:33], v[46:49], v[42:45], v[38:41]
	v_ashrrev_i32_e32 v43, 2, v122
	v_add_u32_e32 v42, s49, v2
	v_lshlrev_b32_e32 v2, 1, v125
	v_and_b32_e32 v40, -4, v43
	v_lshl_add_u64 v[38:39], s[0:1], 0, v[2:3]
	v_lshl_add_u32 v2, v40, 6, v42
	ds_read_b32 v2, v2
	v_ashrrev_i32_e32 v41, 31, v40
	v_lshl_add_u64 v[44:45], s[12:13], 0, v[40:41]
	v_lshlrev_b64 v[44:45], 11, v[44:45]
	v_lshl_add_u64 v[44:45], v[38:39], 0, v[44:45]
	v_readlane_b32 s86, v252, 34
	v_readlane_b32 s87, v252, 35
	s_waitcnt vmcnt(0) lgkmcnt(0)
	v_fma_f32 v2, v1, v2, v34
	v_mul_f32_e32 v34, 0x3d372713, v2
	v_mul_f32_e32 v34, v2, v34
	v_fma_f32 v34, v2, v34, v2
	v_mul_f32_e32 v34, 0x3f4c422a, v34
	v_add_f32_e32 v34, v34, v34
	v_mul_f32_e32 v34, 0xbfb8aa3b, v34
	v_exp_f32_e32 v34, v34
	s_nop 0
	v_add_f32_e32 v34, 1.0, v34
	v_rcp_f32_e32 v34, v34
	s_nop 0
	v_mul_f32_e32 v2, v2, v34
	v_cvt_pk_bf16_f32 v2, v2, s0
	v_or_b32_e32 v34, 1, v40
	global_store_short v[44:45], v2, off
	v_lshl_add_u32 v2, v34, 6, v42
	ds_read_b32 v2, v2
	s_waitcnt lgkmcnt(0)
	v_fma_f32 v2, v1, v2, v35
	v_mul_f32_e32 v35, 0x3d372713, v2
	v_mul_f32_e32 v35, v2, v35
	v_fma_f32 v35, v2, v35, v2
	v_mul_f32_e32 v35, 0x3f4c422a, v35
	v_add_f32_e32 v35, v35, v35
	v_mul_f32_e32 v35, 0xbfb8aa3b, v35
	v_exp_f32_e32 v35, v35
	s_nop 0
	v_add_f32_e32 v35, 1.0, v35
	v_rcp_f32_e32 v35, v35
	s_nop 0
	v_mul_f32_e32 v2, v2, v35
	v_ashrrev_i32_e32 v35, 31, v34
	v_lshl_add_u64 v[34:35], s[12:13], 0, v[34:35]
	v_lshlrev_b64 v[34:35], 11, v[34:35]
	v_cvt_pk_bf16_f32 v2, v2, s0
	v_lshl_add_u64 v[34:35], v[38:39], 0, v[34:35]
	global_store_short v[34:35], v2, off
	v_or_b32_e32 v34, 2, v40
	v_lshl_add_u32 v2, v34, 6, v42
	ds_read_b32 v2, v2
	s_waitcnt lgkmcnt(0)
	v_fma_f32 v2, v1, v2, v36
	v_mul_f32_e32 v35, 0x3d372713, v2
	v_mul_f32_e32 v35, v2, v35
	v_fma_f32 v35, v2, v35, v2
	v_mul_f32_e32 v35, 0x3f4c422a, v35
	v_add_f32_e32 v35, v35, v35
	v_mul_f32_e32 v35, 0xbfb8aa3b, v35
	v_exp_f32_e32 v35, v35
	s_nop 0
	v_add_f32_e32 v35, 1.0, v35
	v_rcp_f32_e32 v35, v35
	s_nop 0
	v_mul_f32_e32 v2, v2, v35
	v_ashrrev_i32_e32 v35, 31, v34
	v_lshl_add_u64 v[34:35], s[12:13], 0, v[34:35]
	v_lshlrev_b64 v[34:35], 11, v[34:35]
	v_cvt_pk_bf16_f32 v2, v2, s0
	v_lshl_add_u64 v[34:35], v[38:39], 0, v[34:35]
	global_store_short v[34:35], v2, off
	v_or_b32_e32 v34, 3, v43
	v_lshl_add_u32 v2, v34, 6, v42
	ds_read_b32 v2, v2
	v_ashrrev_i32_e32 v35, 31, v34
	v_lshl_add_u64 v[34:35], s[12:13], 0, v[34:35]
	v_lshlrev_b64 v[34:35], 11, v[34:35]
	v_lshl_add_u64 v[34:35], v[38:39], 0, v[34:35]
	s_waitcnt lgkmcnt(0)
	v_fmac_f32_e32 v37, v1, v2
	v_mul_f32_e32 v2, 0x3d372713, v37
	v_mul_f32_e32 v2, v37, v2
	v_fma_f32 v2, v37, v2, v37
	v_mul_f32_e32 v2, 0x3f4c422a, v2
	v_add_f32_e32 v2, v2, v2
	v_mul_f32_e32 v2, 0xbfb8aa3b, v2
	v_exp_f32_e32 v2, v2
	s_nop 0
	v_add_f32_e32 v2, 1.0, v2
	v_rcp_f32_e32 v2, v2
	s_nop 0
	v_mul_f32_e32 v2, v37, v2
	v_cvt_pk_bf16_f32 v2, v2, s0
	global_store_short v[34:35], v2, off
	v_add_u32_e32 v34, 16, v40
	v_lshl_add_u32 v2, v34, 6, v42
	ds_read_b32 v2, v2
	v_ashrrev_i32_e32 v35, 31, v34
	v_lshl_add_u64 v[34:35], s[12:13], 0, v[34:35]
	v_lshlrev_b64 v[34:35], 11, v[34:35]
	v_lshl_add_u64 v[34:35], v[38:39], 0, v[34:35]
	s_waitcnt lgkmcnt(0)
	v_fma_f32 v2, v1, v2, v30
	v_mul_f32_e32 v30, 0x3d372713, v2
	v_mul_f32_e32 v30, v2, v30
	v_fma_f32 v30, v2, v30, v2
	v_mul_f32_e32 v30, 0x3f4c422a, v30
	v_add_f32_e32 v30, v30, v30
	v_mul_f32_e32 v30, 0xbfb8aa3b, v30
	v_exp_f32_e32 v30, v30
	s_nop 0
	v_add_f32_e32 v30, 1.0, v30
	v_rcp_f32_e32 v30, v30
	s_nop 0
	v_mul_f32_e32 v2, v2, v30
	v_cvt_pk_bf16_f32 v2, v2, s0
	v_add_u32_e32 v30, 17, v40
	global_store_short v[34:35], v2, off
	v_lshl_add_u32 v2, v30, 6, v42
	ds_read_b32 v2, v2
	s_waitcnt lgkmcnt(0)
; DI bf16 f2bf(float f) { return (bf16)(pk2(f, 0.f) & 0xffffu); }
; DI float gelu_tanh(float x) { const float u = 0.7978845608028654f * (x + 0.044715f * x * x * x); return x * sigm(2.0f * u); }
; DI void s5_passC(const Ctx& C, const S5P& P, const bf16* PROJ, const f32x2* END, bf16* YG  , int item_lo, int item_hi) {
;     ...
;         const float dv = P.d[g * 16 + (lane & 15)];
; #pragma unroll
;         for (int r = 0; r < 8; ++r)
; #pragma unroll
;             for (int j = 0; j < 4; ++j) { const int t = 16 * r + (lane >> 4) * 4 + j; const float y = acc[r][j] + dv * UF[t * 16 + (lane & 15)]; YG[(tok0 + t) * 1024 + g * 16 + (lane & 15)] = f2bf(gelu_tanh(y)); }
	v_fma_f32 v2, v1, v2, v31
	v_mul_f32_e32 v31, 0x3d372713, v2
	v_mul_f32_e32 v31, v2, v31
	v_fma_f32 v31, v2, v31, v2
	v_mul_f32_e32 v31, 0x3f4c422a, v31
	v_add_f32_e32 v31, v31, v31
	v_mul_f32_e32 v31, 0xbfb8aa3b, v31
	v_exp_f32_e32 v31, v31
	s_nop 0
	v_add_f32_e32 v31, 1.0, v31
	v_rcp_f32_e32 v31, v31
	s_nop 0
	v_mul_f32_e32 v2, v2, v31
	v_ashrrev_i32_e32 v31, 31, v30
	v_lshl_add_u64 v[30:31], s[12:13], 0, v[30:31]
	v_lshlrev_b64 v[30:31], 11, v[30:31]
	v_cvt_pk_bf16_f32 v2, v2, s0
	v_lshl_add_u64 v[30:31], v[38:39], 0, v[30:31]
	global_store_short v[30:31], v2, off
	v_add_u32_e32 v30, 18, v40
	v_lshl_add_u32 v2, v30, 6, v42
	ds_read_b32 v2, v2
	s_waitcnt lgkmcnt(0)
	v_fma_f32 v2, v1, v2, v32
	v_mul_f32_e32 v31, 0x3d372713, v2
	v_mul_f32_e32 v31, v2, v31
	v_fma_f32 v31, v2, v31, v2
	v_mul_f32_e32 v31, 0x3f4c422a, v31
	v_add_f32_e32 v31, v31, v31
	v_mul_f32_e32 v31, 0xbfb8aa3b, v31
	v_exp_f32_e32 v31, v31
	s_nop 0
	v_add_f32_e32 v31, 1.0, v31
	v_rcp_f32_e32 v31, v31
	s_nop 0
	v_mul_f32_e32 v2, v2, v31
	v_ashrrev_i32_e32 v31, 31, v30
	v_lshl_add_u64 v[30:31], s[12:13], 0, v[30:31]
	v_lshlrev_b64 v[30:31], 11, v[30:31]
	v_cvt_pk_bf16_f32 v2, v2, s0
	v_lshl_add_u64 v[30:31], v[38:39], 0, v[30:31]
	global_store_short v[30:31], v2, off
	v_add_u32_e32 v30, 19, v40
	v_lshl_add_u32 v2, v30, 6, v42
	ds_read_b32 v2, v2
	v_ashrrev_i32_e32 v31, 31, v30
	v_lshl_add_u64 v[30:31], s[12:13], 0, v[30:31]
	v_lshlrev_b64 v[30:31], 11, v[30:31]
	v_lshl_add_u64 v[30:31], v[38:39], 0, v[30:31]
	s_waitcnt lgkmcnt(0)
	v_fmac_f32_e32 v33, v1, v2
	v_mul_f32_e32 v2, 0x3d372713, v33
	v_mul_f32_e32 v2, v33, v2
	v_fma_f32 v2, v33, v2, v33
	v_mul_f32_e32 v2, 0x3f4c422a, v2
	v_add_f32_e32 v2, v2, v2
	v_mul_f32_e32 v2, 0xbfb8aa3b, v2
	v_exp_f32_e32 v2, v2
	s_nop 0
	v_add_f32_e32 v2, 1.0, v2
	v_rcp_f32_e32 v2, v2
	s_nop 0
	v_mul_f32_e32 v2, v33, v2
	v_cvt_pk_bf16_f32 v2, v2, s0
	global_store_short v[30:31], v2, off
	v_add_u32_e32 v30, 32, v40
	v_lshl_add_u32 v2, v30, 6, v42
	ds_read_b32 v2, v2
	v_ashrrev_i32_e32 v31, 31, v30
	v_lshl_add_u64 v[30:31], s[12:13], 0, v[30:31]
	v_lshlrev_b64 v[30:31], 11, v[30:31]
	v_lshl_add_u64 v[30:31], v[38:39], 0, v[30:31]
	s_waitcnt lgkmcnt(0)
	v_fma_f32 v2, v1, v2, v26
	v_mul_f32_e32 v26, 0x3d372713, v2
	v_mul_f32_e32 v26, v2, v26
	v_fma_f32 v26, v2, v26, v2
	v_mul_f32_e32 v26, 0x3f4c422a, v26
	v_add_f32_e32 v26, v26, v26
	v_mul_f32_e32 v26, 0xbfb8aa3b, v26
	v_exp_f32_e32 v26, v26
	s_nop 0
	v_add_f32_e32 v26, 1.0, v26
	v_rcp_f32_e32 v26, v26
	s_nop 0
	v_mul_f32_e32 v2, v2, v26
	v_cvt_pk_bf16_f32 v2, v2, s0
	v_add_u32_e32 v26, 33, v40
	global_store_short v[30:31], v2, off
	v_lshl_add_u32 v2, v26, 6, v42
	ds_read_b32 v2, v2
	s_waitcnt lgkmcnt(0)
	v_fma_f32 v2, v1, v2, v27
	v_mul_f32_e32 v27, 0x3d372713, v2
	v_mul_f32_e32 v27, v2, v27
	v_fma_f32 v27, v2, v27, v2
	v_mul_f32_e32 v27, 0x3f4c422a, v27
	v_add_f32_e32 v27, v27, v27
	v_mul_f32_e32 v27, 0xbfb8aa3b, v27
	v_exp_f32_e32 v27, v27
	s_nop 0
	v_add_f32_e32 v27, 1.0, v27
	v_rcp_f32_e32 v27, v27
	s_nop 0
	v_mul_f32_e32 v2, v2, v27
	v_ashrrev_i32_e32 v27, 31, v26
	v_lshl_add_u64 v[26:27], s[12:13], 0, v[26:27]
	v_lshlrev_b64 v[26:27], 11, v[26:27]
	v_cvt_pk_bf16_f32 v2, v2, s0
	v_lshl_add_u64 v[26:27], v[38:39], 0, v[26:27]
	global_store_short v[26:27], v2, off
	v_add_u32_e32 v26, 34, v40
	v_lshl_add_u32 v2, v26, 6, v42
	ds_read_b32 v2, v2
	s_waitcnt lgkmcnt(0)
	v_fma_f32 v2, v1, v2, v28
	v_mul_f32_e32 v27, 0x3d372713, v2
	v_mul_f32_e32 v27, v2, v27
	v_fma_f32 v27, v2, v27, v2
	v_mul_f32_e32 v27, 0x3f4c422a, v27
	v_add_f32_e32 v27, v27, v27
	v_mul_f32_e32 v27, 0xbfb8aa3b, v27
	v_exp_f32_e32 v27, v27
	s_nop 0
	v_add_f32_e32 v27, 1.0, v27
	v_rcp_f32_e32 v27, v27
	s_nop 0
	v_mul_f32_e32 v2, v2, v27
	v_ashrrev_i32_e32 v27, 31, v26
	v_lshl_add_u64 v[26:27], s[12:13], 0, v[26:27]
	v_lshlrev_b64 v[26:27], 11, v[26:27]
	v_cvt_pk_bf16_f32 v2, v2, s0
	v_lshl_add_u64 v[26:27], v[38:39], 0, v[26:27]
	global_store_short v[26:27], v2, off
	v_add_u32_e32 v26, 35, v40
	v_lshl_add_u32 v2, v26, 6, v42
	ds_read_b32 v2, v2
	v_ashrrev_i32_e32 v27, 31, v26
	v_lshl_add_u64 v[26:27], s[12:13], 0, v[26:27]
	v_lshlrev_b64 v[26:27], 11, v[26:27]
	v_lshl_add_u64 v[26:27], v[38:39], 0, v[26:27]
	s_waitcnt lgkmcnt(0)
	v_fmac_f32_e32 v29, v1, v2
	v_mul_f32_e32 v2, 0x3d372713, v29
	v_mul_f32_e32 v2, v29, v2
	v_fma_f32 v2, v29, v2, v29
	v_mul_f32_e32 v2, 0x3f4c422a, v2
	v_add_f32_e32 v2, v2, v2
	v_mul_f32_e32 v2, 0xbfb8aa3b, v2
	v_exp_f32_e32 v2, v2
	s_nop 0
	v_add_f32_e32 v2, 1.0, v2
	v_rcp_f32_e32 v2, v2
	s_nop 0
	v_mul_f32_e32 v2, v29, v2
	v_cvt_pk_bf16_f32 v2, v2, s0
	global_store_short v[26:27], v2, off
	v_add_u32_e32 v26, 48, v40
	v_lshl_add_u32 v2, v26, 6, v42
	ds_read_b32 v2, v2
	v_ashrrev_i32_e32 v27, 31, v26
	v_lshl_add_u64 v[26:27], s[12:13], 0, v[26:27]
	v_lshlrev_b64 v[26:27], 11, v[26:27]
	v_lshl_add_u64 v[26:27], v[38:39], 0, v[26:27]
	s_waitcnt lgkmcnt(0)
	v_fma_f32 v2, v1, v2, v22
	v_mul_f32_e32 v22, 0x3d372713, v2
	v_mul_f32_e32 v22, v2, v22
	v_fma_f32 v22, v2, v22, v2
	v_mul_f32_e32 v22, 0x3f4c422a, v22
	v_add_f32_e32 v22, v22, v22
	v_mul_f32_e32 v22, 0xbfb8aa3b, v22
	v_exp_f32_e32 v22, v22
	s_nop 0
	v_add_f32_e32 v22, 1.0, v22
	v_rcp_f32_e32 v22, v22
	s_nop 0
	v_mul_f32_e32 v2, v2, v22
	v_cvt_pk_bf16_f32 v2, v2, s0
	v_add_u32_e32 v22, 49, v40
	global_store_short v[26:27], v2, off
	v_lshl_add_u32 v2, v22, 6, v42
	ds_read_b32 v2, v2
	s_waitcnt lgkmcnt(0)
; DI bf16 f2bf(float f) { return (bf16)(pk2(f, 0.f) & 0xffffu); }
; DI float gelu_tanh(float x) { const float u = 0.7978845608028654f * (x + 0.044715f * x * x * x); return x * sigm(2.0f * u); }
; DI void s5_passC(const Ctx& C, const S5P& P, const bf16* PROJ, const f32x2* END, bf16* YG  , int item_lo, int item_hi) {
;     ...
;         const float dv = P.d[g * 16 + (lane & 15)];
; #pragma unroll
;         for (int r = 0; r < 8; ++r)
; #pragma unroll
;             for (int j = 0; j < 4; ++j) { const int t = 16 * r + (lane >> 4) * 4 + j; const float y = acc[r][j] + dv * UF[t * 16 + (lane & 15)]; YG[(tok0 + t) * 1024 + g * 16 + (lane & 15)] = f2bf(gelu_tanh(y)); }
	v_fma_f32 v2, v1, v2, v23
	v_mul_f32_e32 v23, 0x3d372713, v2
	v_mul_f32_e32 v23, v2, v23
	v_fma_f32 v23, v2, v23, v2
	v_mul_f32_e32 v23, 0x3f4c422a, v23
	v_add_f32_e32 v23, v23, v23
	v_mul_f32_e32 v23, 0xbfb8aa3b, v23
	v_exp_f32_e32 v23, v23
	s_nop 0
	v_add_f32_e32 v23, 1.0, v23
	v_rcp_f32_e32 v23, v23
	s_nop 0
	v_mul_f32_e32 v2, v2, v23
	v_ashrrev_i32_e32 v23, 31, v22
	v_lshl_add_u64 v[22:23], s[12:13], 0, v[22:23]
	v_lshlrev_b64 v[22:23], 11, v[22:23]
	v_cvt_pk_bf16_f32 v2, v2, s0
	v_lshl_add_u64 v[22:23], v[38:39], 0, v[22:23]
	global_store_short v[22:23], v2, off
	v_add_u32_e32 v22, 50, v40
	v_lshl_add_u32 v2, v22, 6, v42
	ds_read_b32 v2, v2
	s_waitcnt lgkmcnt(0)
	v_fma_f32 v2, v1, v2, v24
	v_mul_f32_e32 v23, 0x3d372713, v2
	v_mul_f32_e32 v23, v2, v23
	v_fma_f32 v23, v2, v23, v2
	v_mul_f32_e32 v23, 0x3f4c422a, v23
	v_add_f32_e32 v23, v23, v23
	v_mul_f32_e32 v23, 0xbfb8aa3b, v23
	v_exp_f32_e32 v23, v23
	s_nop 0
	v_add_f32_e32 v23, 1.0, v23
	v_rcp_f32_e32 v23, v23
	s_nop 0
	v_mul_f32_e32 v2, v2, v23
	v_ashrrev_i32_e32 v23, 31, v22
	v_lshl_add_u64 v[22:23], s[12:13], 0, v[22:23]
	v_lshlrev_b64 v[22:23], 11, v[22:23]
	v_cvt_pk_bf16_f32 v2, v2, s0
	v_lshl_add_u64 v[22:23], v[38:39], 0, v[22:23]
	global_store_short v[22:23], v2, off
	v_add_u32_e32 v22, 51, v40
	v_lshl_add_u32 v2, v22, 6, v42
	ds_read_b32 v2, v2
	v_ashrrev_i32_e32 v23, 31, v22
	v_lshl_add_u64 v[22:23], s[12:13], 0, v[22:23]
	v_lshlrev_b64 v[22:23], 11, v[22:23]
	v_lshl_add_u64 v[22:23], v[38:39], 0, v[22:23]
	s_waitcnt lgkmcnt(0)
	v_fmac_f32_e32 v25, v1, v2
	v_mul_f32_e32 v2, 0x3d372713, v25
	v_mul_f32_e32 v2, v25, v2
	v_fma_f32 v2, v25, v2, v25
	v_mul_f32_e32 v2, 0x3f4c422a, v2
	v_add_f32_e32 v2, v2, v2
	v_mul_f32_e32 v2, 0xbfb8aa3b, v2
	v_exp_f32_e32 v2, v2
	s_nop 0
	v_add_f32_e32 v2, 1.0, v2
	v_rcp_f32_e32 v2, v2
	s_nop 0
	v_mul_f32_e32 v2, v25, v2
	v_cvt_pk_bf16_f32 v2, v2, s0
	global_store_short v[22:23], v2, off
	v_add_u32_e32 v22, 64, v40
	v_lshl_add_u32 v2, v22, 6, v42
	ds_read_b32 v2, v2
	v_ashrrev_i32_e32 v23, 31, v22
	v_lshl_add_u64 v[22:23], s[12:13], 0, v[22:23]
	v_lshlrev_b64 v[22:23], 11, v[22:23]
	v_lshl_add_u64 v[22:23], v[38:39], 0, v[22:23]
	s_waitcnt lgkmcnt(0)
	v_fma_f32 v2, v1, v2, v18
	v_mul_f32_e32 v18, 0x3d372713, v2
	v_mul_f32_e32 v18, v2, v18
	v_fma_f32 v18, v2, v18, v2
	v_mul_f32_e32 v18, 0x3f4c422a, v18
	v_add_f32_e32 v18, v18, v18
	v_mul_f32_e32 v18, 0xbfb8aa3b, v18
	v_exp_f32_e32 v18, v18
	s_nop 0
	v_add_f32_e32 v18, 1.0, v18
	v_rcp_f32_e32 v18, v18
	s_nop 0
	v_mul_f32_e32 v2, v2, v18
	v_cvt_pk_bf16_f32 v2, v2, s0
	v_add_u32_e32 v18, 0x41, v40
	global_store_short v[22:23], v2, off
	v_lshl_add_u32 v2, v18, 6, v42
	ds_read_b32 v2, v2
	s_waitcnt lgkmcnt(0)
	v_fma_f32 v2, v1, v2, v19
	v_mul_f32_e32 v19, 0x3d372713, v2
	v_mul_f32_e32 v19, v2, v19
	v_fma_f32 v19, v2, v19, v2
	v_mul_f32_e32 v19, 0x3f4c422a, v19
	v_add_f32_e32 v19, v19, v19
	v_mul_f32_e32 v19, 0xbfb8aa3b, v19
	v_exp_f32_e32 v19, v19
	s_nop 0
	v_add_f32_e32 v19, 1.0, v19
	v_rcp_f32_e32 v19, v19
	s_nop 0
	v_mul_f32_e32 v2, v2, v19
	v_ashrrev_i32_e32 v19, 31, v18
	v_lshl_add_u64 v[18:19], s[12:13], 0, v[18:19]
	v_lshlrev_b64 v[18:19], 11, v[18:19]
	v_cvt_pk_bf16_f32 v2, v2, s0
	v_lshl_add_u64 v[18:19], v[38:39], 0, v[18:19]
	global_store_short v[18:19], v2, off
	v_add_u32_e32 v18, 0x42, v40
	v_lshl_add_u32 v2, v18, 6, v42
	ds_read_b32 v2, v2
	s_waitcnt lgkmcnt(0)
	v_fma_f32 v2, v1, v2, v20
	v_mul_f32_e32 v19, 0x3d372713, v2
	v_mul_f32_e32 v19, v2, v19
	v_fma_f32 v19, v2, v19, v2
	v_mul_f32_e32 v19, 0x3f4c422a, v19
	v_add_f32_e32 v19, v19, v19
	v_mul_f32_e32 v19, 0xbfb8aa3b, v19
	v_exp_f32_e32 v19, v19
	s_nop 0
	v_add_f32_e32 v19, 1.0, v19
	v_rcp_f32_e32 v19, v19
	s_nop 0
	v_mul_f32_e32 v2, v2, v19
	v_ashrrev_i32_e32 v19, 31, v18
	v_lshl_add_u64 v[18:19], s[12:13], 0, v[18:19]
	v_lshlrev_b64 v[18:19], 11, v[18:19]
	v_cvt_pk_bf16_f32 v2, v2, s0
	v_lshl_add_u64 v[18:19], v[38:39], 0, v[18:19]
	global_store_short v[18:19], v2, off
	v_add_u32_e32 v18, 0x43, v40
	v_lshl_add_u32 v2, v18, 6, v42
	ds_read_b32 v2, v2
	v_ashrrev_i32_e32 v19, 31, v18
	v_lshl_add_u64 v[18:19], s[12:13], 0, v[18:19]
	v_lshlrev_b64 v[18:19], 11, v[18:19]
	v_lshl_add_u64 v[18:19], v[38:39], 0, v[18:19]
	s_waitcnt lgkmcnt(0)
	v_fmac_f32_e32 v21, v1, v2
	v_mul_f32_e32 v2, 0x3d372713, v21
	v_mul_f32_e32 v2, v21, v2
	v_fma_f32 v2, v21, v2, v21
	v_mul_f32_e32 v2, 0x3f4c422a, v2
	v_add_f32_e32 v2, v2, v2
	v_mul_f32_e32 v2, 0xbfb8aa3b, v2
	v_exp_f32_e32 v2, v2
	s_nop 0
	v_add_f32_e32 v2, 1.0, v2
	v_rcp_f32_e32 v2, v2
	s_nop 0
	v_mul_f32_e32 v2, v21, v2
	v_cvt_pk_bf16_f32 v2, v2, s0
	global_store_short v[18:19], v2, off
	v_add_u32_e32 v18, 0x50, v40
	v_lshl_add_u32 v2, v18, 6, v42
	ds_read_b32 v2, v2
	v_ashrrev_i32_e32 v19, 31, v18
	v_lshl_add_u64 v[18:19], s[12:13], 0, v[18:19]
	v_lshlrev_b64 v[18:19], 11, v[18:19]
	v_lshl_add_u64 v[18:19], v[38:39], 0, v[18:19]
	s_waitcnt lgkmcnt(0)
	v_fma_f32 v2, v1, v2, v14
	v_mul_f32_e32 v14, 0x3d372713, v2
	v_mul_f32_e32 v14, v2, v14
	v_fma_f32 v14, v2, v14, v2
	v_mul_f32_e32 v14, 0x3f4c422a, v14
	v_add_f32_e32 v14, v14, v14
	v_mul_f32_e32 v14, 0xbfb8aa3b, v14
	v_exp_f32_e32 v14, v14
	s_nop 0
	v_add_f32_e32 v14, 1.0, v14
	v_rcp_f32_e32 v14, v14
	s_nop 0
	v_mul_f32_e32 v2, v2, v14
	v_cvt_pk_bf16_f32 v2, v2, s0
	v_add_u32_e32 v14, 0x51, v40
	global_store_short v[18:19], v2, off
	v_lshl_add_u32 v2, v14, 6, v42
	ds_read_b32 v2, v2
	s_waitcnt lgkmcnt(0)
; DI bf16 f2bf(float f) { return (bf16)(pk2(f, 0.f) & 0xffffu); }
; DI float gelu_tanh(float x) { const float u = 0.7978845608028654f * (x + 0.044715f * x * x * x); return x * sigm(2.0f * u); }
; DI void s5_passC(const Ctx& C, const S5P& P, const bf16* PROJ, const f32x2* END, bf16* YG  , int item_lo, int item_hi) {
;     ...
;         const float dv = P.d[g * 16 + (lane & 15)];
; #pragma unroll
;         for (int r = 0; r < 8; ++r)
; #pragma unroll
;             for (int j = 0; j < 4; ++j) { const int t = 16 * r + (lane >> 4) * 4 + j; const float y = acc[r][j] + dv * UF[t * 16 + (lane & 15)]; YG[(tok0 + t) * 1024 + g * 16 + (lane & 15)] = f2bf(gelu_tanh(y)); }
	v_fma_f32 v2, v1, v2, v15
	v_mul_f32_e32 v15, 0x3d372713, v2
	v_mul_f32_e32 v15, v2, v15
	v_fma_f32 v15, v2, v15, v2
	v_mul_f32_e32 v15, 0x3f4c422a, v15
	v_add_f32_e32 v15, v15, v15
	v_mul_f32_e32 v15, 0xbfb8aa3b, v15
	v_exp_f32_e32 v15, v15
	s_nop 0
	v_add_f32_e32 v15, 1.0, v15
	v_rcp_f32_e32 v15, v15
	s_nop 0
	v_mul_f32_e32 v2, v2, v15
	v_ashrrev_i32_e32 v15, 31, v14
	v_lshl_add_u64 v[14:15], s[12:13], 0, v[14:15]
	v_lshlrev_b64 v[14:15], 11, v[14:15]
	v_cvt_pk_bf16_f32 v2, v2, s0
	v_lshl_add_u64 v[14:15], v[38:39], 0, v[14:15]
	global_store_short v[14:15], v2, off
	v_add_u32_e32 v14, 0x52, v40
	v_lshl_add_u32 v2, v14, 6, v42
	ds_read_b32 v2, v2
	s_waitcnt lgkmcnt(0)
	v_fma_f32 v2, v1, v2, v16
	v_mul_f32_e32 v15, 0x3d372713, v2
	v_mul_f32_e32 v15, v2, v15
	v_fma_f32 v15, v2, v15, v2
	v_mul_f32_e32 v15, 0x3f4c422a, v15
	v_add_f32_e32 v15, v15, v15
	v_mul_f32_e32 v15, 0xbfb8aa3b, v15
	v_exp_f32_e32 v15, v15
	s_nop 0
	v_add_f32_e32 v15, 1.0, v15
	v_rcp_f32_e32 v15, v15
	s_nop 0
	v_mul_f32_e32 v2, v2, v15
	v_ashrrev_i32_e32 v15, 31, v14
	v_lshl_add_u64 v[14:15], s[12:13], 0, v[14:15]
	v_lshlrev_b64 v[14:15], 11, v[14:15]
	v_cvt_pk_bf16_f32 v2, v2, s0
	v_lshl_add_u64 v[14:15], v[38:39], 0, v[14:15]
	global_store_short v[14:15], v2, off
	v_add_u32_e32 v14, 0x53, v40
	v_lshl_add_u32 v2, v14, 6, v42
	ds_read_b32 v2, v2
	v_ashrrev_i32_e32 v15, 31, v14
	v_lshl_add_u64 v[14:15], s[12:13], 0, v[14:15]
	v_lshlrev_b64 v[14:15], 11, v[14:15]
	v_lshl_add_u64 v[14:15], v[38:39], 0, v[14:15]
	s_waitcnt lgkmcnt(0)
	v_fmac_f32_e32 v17, v1, v2
	v_mul_f32_e32 v2, 0x3d372713, v17
	v_mul_f32_e32 v2, v17, v2
	v_fma_f32 v2, v17, v2, v17
	v_mul_f32_e32 v2, 0x3f4c422a, v2
	v_add_f32_e32 v2, v2, v2
	v_mul_f32_e32 v2, 0xbfb8aa3b, v2
	v_exp_f32_e32 v2, v2
	s_nop 0
	v_add_f32_e32 v2, 1.0, v2
	v_rcp_f32_e32 v2, v2
	s_nop 0
	v_mul_f32_e32 v2, v17, v2
	v_cvt_pk_bf16_f32 v2, v2, s0
	global_store_short v[14:15], v2, off
	v_add_u32_e32 v14, 0x60, v40
	v_lshl_add_u32 v2, v14, 6, v42
	ds_read_b32 v2, v2
	v_ashrrev_i32_e32 v15, 31, v14
	v_lshl_add_u64 v[14:15], s[12:13], 0, v[14:15]
	v_lshlrev_b64 v[14:15], 11, v[14:15]
	v_lshl_add_u64 v[14:15], v[38:39], 0, v[14:15]
	s_waitcnt lgkmcnt(0)
	v_fma_f32 v2, v1, v2, v10
	v_mul_f32_e32 v10, 0x3d372713, v2
	v_mul_f32_e32 v10, v2, v10
	v_fma_f32 v10, v2, v10, v2
	v_mul_f32_e32 v10, 0x3f4c422a, v10
	v_add_f32_e32 v10, v10, v10
	v_mul_f32_e32 v10, 0xbfb8aa3b, v10
	v_exp_f32_e32 v10, v10
	s_nop 0
	v_add_f32_e32 v10, 1.0, v10
	v_rcp_f32_e32 v10, v10
	s_nop 0
	v_mul_f32_e32 v2, v2, v10
	v_cvt_pk_bf16_f32 v2, v2, s0
	v_add_u32_e32 v10, 0x61, v40
	global_store_short v[14:15], v2, off
	v_lshl_add_u32 v2, v10, 6, v42
	ds_read_b32 v2, v2
	s_waitcnt lgkmcnt(0)
	v_fma_f32 v2, v1, v2, v11
	v_mul_f32_e32 v11, 0x3d372713, v2
	v_mul_f32_e32 v11, v2, v11
	v_fma_f32 v11, v2, v11, v2
	v_mul_f32_e32 v11, 0x3f4c422a, v11
	v_add_f32_e32 v11, v11, v11
	v_mul_f32_e32 v11, 0xbfb8aa3b, v11
	v_exp_f32_e32 v11, v11
	s_nop 0
	v_add_f32_e32 v11, 1.0, v11
	v_rcp_f32_e32 v11, v11
	s_nop 0
	v_mul_f32_e32 v2, v2, v11
	v_ashrrev_i32_e32 v11, 31, v10
	v_lshl_add_u64 v[10:11], s[12:13], 0, v[10:11]
	v_lshlrev_b64 v[10:11], 11, v[10:11]
	v_cvt_pk_bf16_f32 v2, v2, s0
	v_lshl_add_u64 v[10:11], v[38:39], 0, v[10:11]
	global_store_short v[10:11], v2, off
	v_add_u32_e32 v10, 0x62, v40
	v_lshl_add_u32 v2, v10, 6, v42
	ds_read_b32 v2, v2
	s_waitcnt lgkmcnt(0)
; DI bf16 f2bf(float f) { return (bf16)(pk2(f, 0.f) & 0xffffu); }
; DI float gelu_tanh(float x) { const float u = 0.7978845608028654f * (x + 0.044715f * x * x * x); return x * sigm(2.0f * u); }
; DI void s5_passC(const Ctx& C, const S5P& P, const bf16* PROJ, const f32x2* END, bf16* YG  , int item_lo, int item_hi) {
;     ...
;         const float dv = P.d[g * 16 + (lane & 15)];
; #pragma unroll
;         for (int r = 0; r < 8; ++r)
; #pragma unroll
;             for (int j = 0; j < 4; ++j) { const int t = 16 * r + (lane >> 4) * 4 + j; const float y = acc[r][j] + dv * UF[t * 16 + (lane & 15)]; YG[(tok0 + t) * 1024 + g * 16 + (lane & 15)] = f2bf(gelu_tanh(y)); }
	v_fma_f32 v2, v1, v2, v12
	v_mul_f32_e32 v11, 0x3d372713, v2
	v_mul_f32_e32 v11, v2, v11
	v_fma_f32 v11, v2, v11, v2
	v_mul_f32_e32 v11, 0x3f4c422a, v11
	v_add_f32_e32 v11, v11, v11
	v_mul_f32_e32 v11, 0xbfb8aa3b, v11
	v_exp_f32_e32 v11, v11
	s_nop 0
	v_add_f32_e32 v11, 1.0, v11
	v_rcp_f32_e32 v11, v11
	s_nop 0
	v_mul_f32_e32 v2, v2, v11
	v_ashrrev_i32_e32 v11, 31, v10
	v_lshl_add_u64 v[10:11], s[12:13], 0, v[10:11]
	v_lshlrev_b64 v[10:11], 11, v[10:11]
	v_cvt_pk_bf16_f32 v2, v2, s0
	v_lshl_add_u64 v[10:11], v[38:39], 0, v[10:11]
	global_store_short v[10:11], v2, off
	v_add_u32_e32 v10, 0x63, v40
	v_lshl_add_u32 v2, v10, 6, v42
	ds_read_b32 v2, v2
	v_ashrrev_i32_e32 v11, 31, v10
	v_lshl_add_u64 v[10:11], s[12:13], 0, v[10:11]
	v_lshlrev_b64 v[10:11], 11, v[10:11]
	v_lshl_add_u64 v[10:11], v[38:39], 0, v[10:11]
	s_waitcnt lgkmcnt(0)
	v_fmac_f32_e32 v13, v1, v2
	v_mul_f32_e32 v2, 0x3d372713, v13
	v_mul_f32_e32 v2, v13, v2
	v_fma_f32 v2, v13, v2, v13
	v_mul_f32_e32 v2, 0x3f4c422a, v2
	v_add_f32_e32 v2, v2, v2
	v_mul_f32_e32 v2, 0xbfb8aa3b, v2
	v_exp_f32_e32 v2, v2
	s_nop 0
	v_add_f32_e32 v2, 1.0, v2
	v_rcp_f32_e32 v2, v2
	s_nop 0
	v_mul_f32_e32 v2, v13, v2
	v_cvt_pk_bf16_f32 v2, v2, s0
	global_store_short v[10:11], v2, off
	v_add_u32_e32 v10, 0x70, v40
	v_lshl_add_u32 v2, v10, 6, v42
	ds_read_b32 v2, v2
	v_ashrrev_i32_e32 v11, 31, v10
	v_lshl_add_u64 v[10:11], s[12:13], 0, v[10:11]
	v_lshlrev_b64 v[10:11], 11, v[10:11]
	v_lshl_add_u64 v[10:11], v[38:39], 0, v[10:11]
	s_waitcnt lgkmcnt(0)
	v_fma_f32 v2, v1, v2, v6
	v_mul_f32_e32 v6, 0x3d372713, v2
	v_mul_f32_e32 v6, v2, v6
	v_fma_f32 v6, v2, v6, v2
	v_mul_f32_e32 v6, 0x3f4c422a, v6
	v_add_f32_e32 v6, v6, v6
	v_mul_f32_e32 v6, 0xbfb8aa3b, v6
	v_exp_f32_e32 v6, v6
	s_nop 0
	v_add_f32_e32 v6, 1.0, v6
	v_rcp_f32_e32 v6, v6
	s_nop 0
	v_mul_f32_e32 v2, v2, v6
	v_cvt_pk_bf16_f32 v2, v2, s0
	v_add_u32_e32 v6, 0x71, v40
	global_store_short v[10:11], v2, off
	v_lshl_add_u32 v2, v6, 6, v42
	ds_read_b32 v2, v2
	s_waitcnt lgkmcnt(0)
	v_fma_f32 v2, v1, v2, v7
	v_mul_f32_e32 v7, 0x3d372713, v2
	v_mul_f32_e32 v7, v2, v7
	v_fma_f32 v7, v2, v7, v2
	v_mul_f32_e32 v7, 0x3f4c422a, v7
	v_add_f32_e32 v7, v7, v7
	v_mul_f32_e32 v7, 0xbfb8aa3b, v7
	v_exp_f32_e32 v7, v7
	s_nop 0
	v_add_f32_e32 v7, 1.0, v7
	v_rcp_f32_e32 v7, v7
	s_nop 0
	v_mul_f32_e32 v2, v2, v7
	v_ashrrev_i32_e32 v7, 31, v6
	v_lshl_add_u64 v[6:7], s[12:13], 0, v[6:7]
	v_lshlrev_b64 v[6:7], 11, v[6:7]
	v_cvt_pk_bf16_f32 v2, v2, s0
	v_lshl_add_u64 v[6:7], v[38:39], 0, v[6:7]
	global_store_short v[6:7], v2, off
	v_add_u32_e32 v6, 0x72, v40
	v_lshl_add_u32 v2, v6, 6, v42
	ds_read_b32 v2, v2
	s_waitcnt lgkmcnt(0)
	v_fma_f32 v2, v1, v2, v8
	v_mul_f32_e32 v7, 0x3d372713, v2
	v_mul_f32_e32 v7, v2, v7
	v_fma_f32 v7, v2, v7, v2
	v_mul_f32_e32 v7, 0x3f4c422a, v7
	v_add_f32_e32 v7, v7, v7
	v_mul_f32_e32 v7, 0xbfb8aa3b, v7
	v_exp_f32_e32 v7, v7
	s_nop 0
	v_add_f32_e32 v7, 1.0, v7
	v_rcp_f32_e32 v7, v7
	s_nop 0
	v_mul_f32_e32 v2, v2, v7
	v_ashrrev_i32_e32 v7, 31, v6
	v_lshl_add_u64 v[6:7], s[12:13], 0, v[6:7]
	v_lshlrev_b64 v[6:7], 11, v[6:7]
	v_cvt_pk_bf16_f32 v2, v2, s0
	v_lshl_add_u64 v[6:7], v[38:39], 0, v[6:7]
	global_store_short v[6:7], v2, off
	v_add_u32_e32 v6, 0x73, v40
	v_lshl_add_u32 v2, v6, 6, v42
	ds_read_b32 v2, v2
	v_ashrrev_i32_e32 v7, 31, v6
	v_lshl_add_u64 v[6:7], s[12:13], 0, v[6:7]
	v_lshlrev_b64 v[6:7], 11, v[6:7]
	v_lshl_add_u64 v[6:7], v[38:39], 0, v[6:7]
	s_waitcnt lgkmcnt(0)
	v_fmac_f32_e32 v9, v1, v2
	v_mul_f32_e32 v1, 0x3d372713, v9
	v_mul_f32_e32 v1, v9, v1
	v_fma_f32 v1, v9, v1, v9
	v_mul_f32_e32 v1, 0x3f4c422a, v1
	v_add_f32_e32 v1, v1, v1
	v_mul_f32_e32 v1, 0xbfb8aa3b, v1
	v_exp_f32_e32 v1, v1
	s_nop 0
	v_add_f32_e32 v1, 1.0, v1
	v_rcp_f32_e32 v1, v1
	s_nop 0
	v_mul_f32_e32 v1, v9, v1
	v_cvt_pk_bf16_f32 v1, v1, s0
	global_store_short v[6:7], v1, off
	s_waitcnt lgkmcnt(0)
	v_readlane_b32 s0, v255, 52
	s_add_i32 s30, s30, s0
	s_cmpk_lt_i32 s30, 0x1800
	s_cbranch_scc1 .LBB0_606

; template <int DIRN> DI void s5_dir(const S5P& P, const f32x2* END, const LAS float* UF, LAS bf16* XT, int b, int seg, int g, const bf16x8 (&bfr)[4], f32x4 (&acc)[8], int lane) {
;     ...
; #pragma unroll 8
;         for (int j = 0; j < sl; ++j) { const float* ep = (const float*)END + ((size_t)((b * 2 + DIRN) * SNSEG + j)) * 8192 + g * 128 + lane; const f32x2 e = {ep[0], ep[64]}; const float nr = Lr * xr - Li * xi + e.x, ni = Lr * xi + Li * xr + e.y; xr = nr; xi = ni; } }
.LBB0_691:
	global_load_dword v184, v[80:81], off
	global_load_dword v185, v[80:81], off offset:256
	v_add_co_u32_e32 v80, vcc, 0x8000, v80
	s_nop 1
	v_addc_co_u32_e32 v81, vcc, 0, v81, vcc
	global_load_dword v186, v[80:81], off
	global_load_dword v187, v[80:81], off offset:256
	v_add_co_u32_e32 v80, vcc, 0x8000, v80
	s_nop 1
	v_addc_co_u32_e32 v81, vcc, 0, v81, vcc
	global_load_dword v188, v[80:81], off
	global_load_dword v189, v[80:81], off offset:256
	v_add_co_u32_e32 v80, vcc, 0x8000, v80
	s_nop 1
	v_addc_co_u32_e32 v81, vcc, 0, v81, vcc
	global_load_dword v190, v[80:81], off
	global_load_dword v191, v[80:81], off offset:256
	v_add_co_u32_e32 v80, vcc, 0x8000, v80
	s_nop 1
	v_addc_co_u32_e32 v81, vcc, 0, v81, vcc
	global_load_dword v192, v[80:81], off
	global_load_dword v193, v[80:81], off offset:256
	v_add_co_u32_e32 v80, vcc, 0x8000, v80
	s_nop 1
	v_addc_co_u32_e32 v81, vcc, 0, v81, vcc
	global_load_dword v194, v[80:81], off
	global_load_dword v195, v[80:81], off offset:256
	v_add_co_u32_e32 v80, vcc, 0x8000, v80
	s_nop 1
	v_addc_co_u32_e32 v81, vcc, 0, v81, vcc
	global_load_dword v196, v[80:81], off
	global_load_dword v197, v[80:81], off offset:256
	v_add_co_u32_e32 v80, vcc, 0x8000, v80
	s_nop 1
	v_addc_co_u32_e32 v81, vcc, 0, v81, vcc
	global_load_dword v198, v[80:81], off
	global_load_dword v199, v[80:81], off offset:256
	v_add_co_u32_e32 v80, vcc, 0x8000, v80
	s_nop 1
	v_addc_co_u32_e32 v81, vcc, 0, v81, vcc
	s_add_i32 s1, s1, 8
	v_pk_mul_f32 v[84:85], v[74:75], v[172:173] op_sel:[0,1] op_sel_hi:[1,0]
	v_pk_fma_f32 v[88:89], v[76:77], v[172:173], v[84:85]
	v_pk_fma_f32 v[82:83], v[76:77], v[172:173], v[84:85] neg_lo:[0,0,1] neg_hi:[0,0,1]
	s_nop 0
	v_mov_b32_e32 v83, v89
	s_waitcnt vmcnt(14) lgkmcnt(0)
	v_pk_add_f32 v[172:173], v[82:83], v[184:185]
	v_pk_mul_f32 v[84:85], v[74:75], v[172:173] op_sel:[0,1] op_sel_hi:[1,0]
	v_pk_fma_f32 v[88:89], v[76:77], v[172:173], v[84:85]
	v_pk_fma_f32 v[82:83], v[76:77], v[172:173], v[84:85] neg_lo:[0,0,1] neg_hi:[0,0,1]
	s_nop 0
	v_mov_b32_e32 v83, v89
	s_waitcnt vmcnt(12)
	v_pk_add_f32 v[172:173], v[82:83], v[186:187]
	v_pk_mul_f32 v[84:85], v[74:75], v[172:173] op_sel:[0,1] op_sel_hi:[1,0]
	v_pk_fma_f32 v[88:89], v[76:77], v[172:173], v[84:85]
	v_pk_fma_f32 v[82:83], v[76:77], v[172:173], v[84:85] neg_lo:[0,0,1] neg_hi:[0,0,1]
	s_nop 0
	v_mov_b32_e32 v83, v89
	s_waitcnt vmcnt(10)
	v_pk_add_f32 v[172:173], v[82:83], v[188:189]
	v_pk_mul_f32 v[84:85], v[74:75], v[172:173] op_sel:[0,1] op_sel_hi:[1,0]
	v_pk_fma_f32 v[88:89], v[76:77], v[172:173], v[84:85]
	v_pk_fma_f32 v[82:83], v[76:77], v[172:173], v[84:85] neg_lo:[0,0,1] neg_hi:[0,0,1]
	s_nop 0
	v_mov_b32_e32 v83, v89
	s_waitcnt vmcnt(8)
	v_pk_add_f32 v[172:173], v[82:83], v[190:191]
	v_pk_mul_f32 v[84:85], v[74:75], v[172:173] op_sel:[0,1] op_sel_hi:[1,0]
	v_pk_fma_f32 v[88:89], v[76:77], v[172:173], v[84:85]
	v_pk_fma_f32 v[82:83], v[76:77], v[172:173], v[84:85] neg_lo:[0,0,1] neg_hi:[0,0,1]
	s_nop 0
	v_mov_b32_e32 v83, v89
	s_waitcnt vmcnt(6)
	v_pk_add_f32 v[172:173], v[82:83], v[192:193]
	v_pk_mul_f32 v[84:85], v[74:75], v[172:173] op_sel:[0,1] op_sel_hi:[1,0]
	v_pk_fma_f32 v[88:89], v[76:77], v[172:173], v[84:85]
	v_pk_fma_f32 v[82:83], v[76:77], v[172:173], v[84:85] neg_lo:[0,0,1] neg_hi:[0,0,1]
	s_nop 0
	v_mov_b32_e32 v83, v89
	s_waitcnt vmcnt(4)
	v_pk_add_f32 v[172:173], v[82:83], v[194:195]
	v_pk_mul_f32 v[84:85], v[74:75], v[172:173] op_sel:[0,1] op_sel_hi:[1,0]
	v_pk_fma_f32 v[88:89], v[76:77], v[172:173], v[84:85]
	v_pk_fma_f32 v[82:83], v[76:77], v[172:173], v[84:85] neg_lo:[0,0,1] neg_hi:[0,0,1]
	s_nop 0
	v_mov_b32_e32 v83, v89
	s_waitcnt vmcnt(2)
	v_pk_add_f32 v[172:173], v[82:83], v[196:197]
	v_pk_mul_f32 v[84:85], v[74:75], v[172:173] op_sel:[0,1] op_sel_hi:[1,0]
	v_pk_fma_f32 v[88:89], v[76:77], v[172:173], v[84:85]
	v_pk_fma_f32 v[82:83], v[76:77], v[172:173], v[84:85] neg_lo:[0,0,1] neg_hi:[0,0,1]
	s_nop 0
	v_mov_b32_e32 v83, v89
	s_waitcnt vmcnt(0)
	v_pk_add_f32 v[172:173], v[82:83], v[198:199]
	s_cmp_eq_u32 s11, s1
	s_cbranch_scc0 .LBB0_691
	s_bfe_u32 s1, s54, 0x30006
	s_cmp_eq_u32 s1, 0
	s_cbranch_scc0 .LBB0_694
	s_branch .LBB0_696

; #define LAS __attribute__((address_space(3)))
; DI unsigned pk2(float lo, float hi) { return pg8::cvt_pk_bf16(lo, hi); }
; DI f32x4 mfma16(bf16x8 a, bf16x8 b, f32x4 c) { return __builtin_amdgcn_mfma_f32_16x16x32_bf16(a, b, c, 0, 0, 0); }
; template <int DIRN, int SUB> DI void s5_subtile(const LAS float* UF, LAS bf16* XT, float lr, float li, const f32x2 (&bb)[16], f32x2& x,
;                                                 const bf16x8 (&bfr)[4], f32x4& acc0, f32x4& acc1, int lane) {
; #pragma unroll 1
;     for (int i = 0; i < 32; ++i) { const int r = DIRN ? 31 - i : i;
;         x = s5_step((const LAS f32x4*)(UF + (32 * SUB + r) * 16), bb, lr, li, x);
;         const unsigned pkd = pk2(x.x, x.y); XT[r * 136 + lane] = (bf16)(pkd & 0xffffu); XT[r * 136 + 64 + lane] = (bf16)(pkd >> 16); }
; #pragma unroll
;     for (int ks = 0; ks < 4; ++ks) { const bf16x8 a0 = *(const LAS bf16x8*)(XT + (lane & 15) * 136 + 32 * ks + 8 * (lane >> 4)), a1 = *(const LAS bf16x8*)(XT + (16 + (lane & 15)) * 136 + 32 * ks + 8 * (lane >> 4));
;         acc0 = mfma16(a0, bfr[ks], acc0); acc1 = mfma16(a1, bfr[ks], acc1); }
.LBB0_697:
	s_add_i32 s1, s49, s0
	v_mov_b32_e32 v71, s1
	ds_read_b128 v[72:75], v71
	ds_read_b128 v[76:79], v71 offset:16
	ds_read_b128 v[80:83], v71 offset:32
	ds_read_b128 v[84:87], v71 offset:48
	s_waitcnt lgkmcnt(3)
	v_pk_mul_f32 v[88:89], v[178:179], v[72:73] op_sel:[0,1]
	v_pk_fma_f32 v[72:73], v[176:177], v[72:73], v[88:89] op_sel_hi:[1,0,1]
	v_pk_fma_f32 v[72:73], v[180:181], v[74:75], v[72:73] op_sel_hi:[1,0,1]
	v_mov_b32_e32 v74, v75
	v_pk_fma_f32 v[72:73], v[182:183], v[74:75], v[72:73] op_sel_hi:[1,0,1]
	s_waitcnt lgkmcnt(2)
	v_mov_b32_e32 v74, v79
	v_pk_fma_f32 v[72:73], v[184:185], v[76:77], v[72:73] op_sel_hi:[1,0,1]
	v_pk_fma_f32 v[72:73], v[186:187], v[76:77], v[72:73] op_sel:[0,1,0]
	s_waitcnt lgkmcnt(1)
	v_mov_b32_e32 v76, v83
	v_pk_fma_f32 v[72:73], v[188:189], v[78:79], v[72:73] op_sel_hi:[1,0,1]
	v_pk_fma_f32 v[72:73], v[190:191], v[74:75], v[72:73] op_sel_hi:[1,0,1]
	v_pk_mul_f32 v[74:75], v[194:195], v[80:81] op_sel:[0,1]
	v_pk_fma_f32 v[74:75], v[192:193], v[80:81], v[74:75] op_sel_hi:[1,0,1]
	v_pk_fma_f32 v[74:75], v[196:197], v[82:83], v[74:75] op_sel_hi:[1,0,1]
	v_pk_fma_f32 v[74:75], v[198:199], v[76:77], v[74:75] op_sel_hi:[1,0,1]
	s_waitcnt lgkmcnt(0)
	v_mov_b32_e32 v76, v87
	v_pk_fma_f32 v[74:75], v[200:201], v[84:85], v[74:75] op_sel_hi:[1,0,1]
	v_pk_fma_f32 v[74:75], v[202:203], v[84:85], v[74:75] op_sel:[0,1,0]
	v_pk_fma_f32 v[74:75], v[204:205], v[86:87], v[74:75] op_sel_hi:[1,0,1]
	v_pk_fma_f32 v[74:75], v[174:175], v[76:77], v[74:75] op_sel_hi:[1,0,1]
	v_pk_add_f32 v[72:73], v[72:73], v[74:75]
	v_pk_fma_f32 v[72:73], v[140:141], v[172:173], v[72:73] op_sel:[0,1,0] op_sel_hi:[1,0,1]
	v_pk_fma_f32 v[172:173], v[136:137], v[172:173], v[72:73]
	v_add_u32_e32 v73, s49, v2
	v_cvt_pk_bf16_f32 v71, v172, s0
	v_cvt_pk_bf16_f32 v72, v173, s0
	s_add_i32 s0, s0, 64
	v_add_u32_e32 v2, 0x110, v2
	s_cmpk_lg_i32 s0, 0x800
	ds_write_b16 v73, v71
	ds_write_b16 v73, v72 offset:128
	s_cbranch_scc1 .LBB0_697
	v_and_b32_e32 v123, 15, v0
	v_mul_u32_u24_e32 v2, 0x110, v123
	v_lshlrev_b32_e32 v70, 1, v70
	v_add3_u32 v152, s49, v2, v70
	ds_read_b128 v[98:101], v152 offset:8192
	ds_read_b128 v[94:97], v152 offset:8256
	ds_read_b128 v[82:85], v152 offset:12544
	ds_read_b128 v[86:89], v152 offset:12608
	ds_read_b128 v[90:93], v152 offset:8320
	ds_read_b128 v[78:81], v152 offset:8384
	ds_read_b128 v[70:73], v152 offset:12672
	ds_read_b128 v[74:77], v152 offset:12736
	v_add_u32_e32 v2, s35, v206
	s_mov_b32 s0, 0
	v_mov_b32_e32 v102, v2
.LBB0_699:
	s_add_i32 s1, s40, s0
	v_mov_b32_e32 v103, s1
	ds_read_b128 v[104:107], v103
	ds_read_b128 v[108:111], v103 offset:16
	ds_read_b128 v[112:115], v103 offset:32
	ds_read_b128 v[116:119], v103 offset:48
	s_waitcnt lgkmcnt(3)
	v_pk_mul_f32 v[120:121], v[178:179], v[104:105] op_sel:[0,1]
	v_pk_fma_f32 v[104:105], v[176:177], v[104:105], v[120:121] op_sel_hi:[1,0,1]
	v_pk_fma_f32 v[104:105], v[180:181], v[106:107], v[104:105] op_sel_hi:[1,0,1]
	v_mov_b32_e32 v106, v107
	v_pk_fma_f32 v[104:105], v[182:183], v[106:107], v[104:105] op_sel_hi:[1,0,1]
	s_waitcnt lgkmcnt(2)
	v_mov_b32_e32 v106, v111
	v_pk_fma_f32 v[104:105], v[184:185], v[108:109], v[104:105] op_sel_hi:[1,0,1]
	v_pk_fma_f32 v[104:105], v[186:187], v[108:109], v[104:105] op_sel:[0,1,0]
	s_waitcnt lgkmcnt(1)
	v_mov_b32_e32 v108, v115
	v_pk_fma_f32 v[104:105], v[188:189], v[110:111], v[104:105] op_sel_hi:[1,0,1]
	v_pk_fma_f32 v[104:105], v[190:191], v[106:107], v[104:105] op_sel_hi:[1,0,1]
	v_pk_mul_f32 v[106:107], v[194:195], v[112:113] op_sel:[0,1]
	v_pk_fma_f32 v[106:107], v[192:193], v[112:113], v[106:107] op_sel_hi:[1,0,1]
	v_pk_fma_f32 v[106:107], v[196:197], v[114:115], v[106:107] op_sel_hi:[1,0,1]
	v_pk_fma_f32 v[106:107], v[198:199], v[108:109], v[106:107] op_sel_hi:[1,0,1]
	s_waitcnt lgkmcnt(0)
	v_mov_b32_e32 v108, v119
	v_pk_fma_f32 v[106:107], v[200:201], v[116:117], v[106:107] op_sel_hi:[1,0,1]
	v_pk_fma_f32 v[106:107], v[202:203], v[116:117], v[106:107] op_sel:[0,1,0]
	v_pk_fma_f32 v[106:107], v[204:205], v[118:119], v[106:107] op_sel_hi:[1,0,1]
	v_pk_fma_f32 v[106:107], v[174:175], v[108:109], v[106:107] op_sel_hi:[1,0,1]
	v_pk_add_f32 v[104:105], v[104:105], v[106:107]
	v_pk_fma_f32 v[104:105], v[140:141], v[172:173], v[104:105] op_sel:[0,1,0] op_sel_hi:[1,0,1]
	v_pk_fma_f32 v[172:173], v[136:137], v[172:173], v[104:105]
	s_nop 0
	v_cvt_pk_bf16_f32 v103, v172, s0
	v_cvt_pk_bf16_f32 v104, v173, s0
	s_add_i32 s0, s0, 64
	ds_write_b16 v102, v103
	ds_write_b16 v102, v104 offset:128
	v_add_u32_e32 v102, 0x110, v102
	s_cmpk_lg_i32 s0, 0x800
	s_cbranch_scc1 .LBB0_699
	v_cvt_pk_bf16_f32 v38, v38, v39
	v_cvt_pk_bf16_f32 v39, v40, v41
	v_cvt_pk_bf16_f32 v40, v66, v67
	v_cvt_pk_bf16_f32 v41, v68, v69
	v_cvt_pk_bf16_f32 v46, v46, v47
	v_cvt_pk_bf16_f32 v47, v48, v49
	v_cvt_pk_bf16_f32 v49, v44, v45
	v_cvt_pk_bf16_f32 v44, -v58, -v59
	v_cvt_pk_bf16_f32 v45, -v60, -v61
	v_mfma_f32_16x16x32_bf16 v[58:61], v[98:101], v[38:41], 0
	v_cvt_pk_bf16_f32 v48, v42, v43
	v_cvt_pk_bf16_f32 v42, -v62, -v63
	v_cvt_pk_bf16_f32 v43, -v64, -v65
	v_mfma_f32_16x16x32_bf16 v[58:61], v[94:97], v[46:49], v[58:61]
	s_mov_b32 s0, 0
	v_mov_b32_e32 v110, v2
	v_mfma_f32_16x16x32_bf16 v[90:93], v[90:93], v[42:45], v[58:61]
	v_mfma_f32_16x16x32_bf16 v[58:61], v[82:85], v[38:41], 0
	v_mfma_f32_16x16x32_bf16 v[58:61], v[86:89], v[46:49], v[58:61]
	ds_read_b128 v[94:97], v152 offset:8192
	ds_read_b128 v[86:89], v152 offset:12544
	ds_read_b128 v[98:101], v152 offset:8256
	ds_read_b128 v[102:105], v152 offset:12608
	ds_read_b128 v[106:109], v152 offset:8320
	ds_read_b128 v[66:69], v152 offset:12672
	ds_read_b128 v[62:65], v152 offset:8384
	ds_read_b128 v[82:85], v152 offset:12736
; #define LAS __attribute__((address_space(3)))
; DI unsigned pk2(float lo, float hi) { return pg8::cvt_pk_bf16(lo, hi); }
; DI f32x4 mfma16(bf16x8 a, bf16x8 b, f32x4 c) { return __builtin_amdgcn_mfma_f32_16x16x32_bf16(a, b, c, 0, 0, 0); }
; template <int DIRN, int SUB> DI void s5_subtile(const LAS float* UF, LAS bf16* XT, float lr, float li, const f32x2 (&bb)[16], f32x2& x,
;                                                 const bf16x8 (&bfr)[4], f32x4& acc0, f32x4& acc1, int lane) {
; #pragma unroll 1
;     for (int i = 0; i < 32; ++i) { const int r = DIRN ? 31 - i : i;
;         x = s5_step((const LAS f32x4*)(UF + (32 * SUB + r) * 16), bb, lr, li, x);
;         const unsigned pkd = pk2(x.x, x.y); XT[r * 136 + lane] = (bf16)(pkd & 0xffffu); XT[r * 136 + 64 + lane] = (bf16)(pkd >> 16); }
; #pragma unroll
;     for (int ks = 0; ks < 4; ++ks) { const bf16x8 a0 = *(const LAS bf16x8*)(XT + (lane & 15) * 136 + 32 * ks + 8 * (lane >> 4)), a1 = *(const LAS bf16x8*)(XT + (16 + (lane & 15)) * 136 + 32 * ks + 8 * (lane >> 4));
;         acc0 = mfma16(a0, bfr[ks], acc0); acc1 = mfma16(a1, bfr[ks], acc1); }
.LBB0_701:
	s_add_i32 s1, s41, s0
	v_mov_b32_e32 v111, s1
	ds_read_b128 v[112:115], v111
	ds_read_b128 v[116:119], v111 offset:16
	ds_read_b128 v[230:233], v111 offset:32
	ds_read_b128 v[234:237], v111 offset:48
	s_waitcnt lgkmcnt(3)
	v_pk_mul_f32 v[120:121], v[178:179], v[112:113] op_sel:[0,1]
	v_pk_fma_f32 v[112:113], v[176:177], v[112:113], v[120:121] op_sel_hi:[1,0,1]
	v_pk_fma_f32 v[112:113], v[180:181], v[114:115], v[112:113] op_sel_hi:[1,0,1]
	v_mov_b32_e32 v114, v115
	v_pk_fma_f32 v[112:113], v[182:183], v[114:115], v[112:113] op_sel_hi:[1,0,1]
	s_waitcnt lgkmcnt(2)
	v_mov_b32_e32 v114, v119
	v_pk_fma_f32 v[112:113], v[184:185], v[116:117], v[112:113] op_sel_hi:[1,0,1]
	v_pk_fma_f32 v[112:113], v[186:187], v[116:117], v[112:113] op_sel:[0,1,0]
	s_waitcnt lgkmcnt(1)
	v_mov_b32_e32 v116, v233
	v_pk_fma_f32 v[112:113], v[188:189], v[118:119], v[112:113] op_sel_hi:[1,0,1]
	v_pk_fma_f32 v[112:113], v[190:191], v[114:115], v[112:113] op_sel_hi:[1,0,1]
	v_pk_mul_f32 v[114:115], v[194:195], v[230:231] op_sel:[0,1]
	v_pk_fma_f32 v[114:115], v[192:193], v[230:231], v[114:115] op_sel_hi:[1,0,1]
	v_pk_fma_f32 v[114:115], v[196:197], v[232:233], v[114:115] op_sel_hi:[1,0,1]
	v_pk_fma_f32 v[114:115], v[198:199], v[116:117], v[114:115] op_sel_hi:[1,0,1]
	s_waitcnt lgkmcnt(0)
	v_mov_b32_e32 v116, v237
	v_pk_fma_f32 v[114:115], v[200:201], v[234:235], v[114:115] op_sel_hi:[1,0,1]
	v_pk_fma_f32 v[114:115], v[202:203], v[234:235], v[114:115] op_sel:[0,1,0]
	v_pk_fma_f32 v[114:115], v[204:205], v[236:237], v[114:115] op_sel_hi:[1,0,1]
	v_pk_fma_f32 v[114:115], v[174:175], v[116:117], v[114:115] op_sel_hi:[1,0,1]
	v_pk_add_f32 v[112:113], v[112:113], v[114:115]
	v_pk_fma_f32 v[112:113], v[140:141], v[172:173], v[112:113] op_sel:[0,1,0] op_sel_hi:[1,0,1]
	v_pk_fma_f32 v[172:173], v[136:137], v[172:173], v[112:113]
	s_nop 0
	v_cvt_pk_bf16_f32 v111, v172, s0
	v_cvt_pk_bf16_f32 v112, v173, s0
	s_add_i32 s0, s0, 64
	ds_write_b16 v110, v111
	ds_write_b16 v110, v112 offset:128
	v_add_u32_e32 v110, 0x110, v110
	s_cmpk_lg_i32 s0, 0x800
	s_cbranch_scc1 .LBB0_701
	v_cvt_pk_bf16_f32 v54, -v54, -v55
	v_cvt_pk_bf16_f32 v55, -v56, -v57
	v_cvt_pk_bf16_f32 v56, -v50, -v51
	v_cvt_pk_bf16_f32 v57, -v52, -v53
	v_mfma_f32_16x16x32_bf16 v[86:89], v[86:89], v[38:41], 0
	s_mov_b32 s0, 0
	v_mfma_f32_16x16x32_bf16 v[50:53], v[78:81], v[54:57], v[90:93]
	v_mfma_f32_16x16x32_bf16 v[78:81], v[94:97], v[38:41], 0
	v_mfma_f32_16x16x32_bf16 v[78:81], v[98:101], v[46:49], v[78:81]
	v_mfma_f32_16x16x32_bf16 v[78:81], v[106:109], v[42:45], v[78:81]
	v_mfma_f32_16x16x32_bf16 v[86:89], v[102:105], v[46:49], v[86:89]
	ds_read_b128 v[94:97], v152 offset:8192
	ds_read_b128 v[90:93], v152 offset:12544
	ds_read_b128 v[102:105], v152 offset:8256
	ds_read_b128 v[98:101], v152 offset:12608
	ds_read_b128 v[110:113], v152 offset:8320
	ds_read_b128 v[106:109], v152 offset:12672
	ds_read_b128 v[118:121], v152 offset:8384
	ds_read_b128 v[114:117], v152 offset:12736
.LBB0_703:
	s_add_i32 s1, s42, s0
	v_mov_b32_e32 v158, s1
	ds_read_b128 v[230:233], v158
	ds_read_b128 v[234:237], v158 offset:16
	ds_read_b128 v[238:241], v158 offset:32
	ds_read_b128 v[242:245], v158 offset:48
	s_waitcnt lgkmcnt(3)
	v_pk_mul_f32 v[158:159], v[178:179], v[230:231] op_sel:[0,1]
	v_pk_fma_f32 v[158:159], v[176:177], v[230:231], v[158:159] op_sel_hi:[1,0,1]
	v_mov_b32_e32 v160, v233
	v_pk_fma_f32 v[158:159], v[180:181], v[232:233], v[158:159] op_sel_hi:[1,0,1]
	s_waitcnt lgkmcnt(1)
	v_mov_b32_e32 v230, v241
	v_pk_fma_f32 v[158:159], v[182:183], v[160:161], v[158:159] op_sel_hi:[1,0,1]
	v_mov_b32_e32 v160, v237
	v_pk_fma_f32 v[158:159], v[184:185], v[234:235], v[158:159] op_sel_hi:[1,0,1]
	v_pk_fma_f32 v[158:159], v[186:187], v[234:235], v[158:159] op_sel:[0,1,0]
	v_pk_fma_f32 v[158:159], v[188:189], v[236:237], v[158:159] op_sel_hi:[1,0,1]
	v_pk_fma_f32 v[158:159], v[190:191], v[160:161], v[158:159] op_sel_hi:[1,0,1]
	v_pk_mul_f32 v[160:161], v[194:195], v[238:239] op_sel:[0,1]
	v_pk_fma_f32 v[160:161], v[192:193], v[238:239], v[160:161] op_sel_hi:[1,0,1]
	v_pk_fma_f32 v[160:161], v[196:197], v[240:241], v[160:161] op_sel_hi:[1,0,1]
	v_pk_fma_f32 v[160:161], v[198:199], v[230:231], v[160:161] op_sel_hi:[1,0,1]
	s_waitcnt lgkmcnt(0)
	v_mov_b32_e32 v230, v245
	v_pk_fma_f32 v[160:161], v[200:201], v[242:243], v[160:161] op_sel_hi:[1,0,1]
	v_pk_fma_f32 v[160:161], v[202:203], v[242:243], v[160:161] op_sel:[0,1,0]
	v_pk_fma_f32 v[160:161], v[204:205], v[244:245], v[160:161] op_sel_hi:[1,0,1]
	v_pk_fma_f32 v[160:161], v[174:175], v[230:231], v[160:161] op_sel_hi:[1,0,1]
	v_pk_add_f32 v[158:159], v[158:159], v[160:161]
	v_pk_fma_f32 v[158:159], v[140:141], v[172:173], v[158:159] op_sel:[0,1,0] op_sel_hi:[1,0,1]
	v_pk_fma_f32 v[172:173], v[136:137], v[172:173], v[158:159]
	s_nop 0
	v_cvt_pk_bf16_f32 v158, v172, s0
	v_cvt_pk_bf16_f32 v159, v173, s0
	s_add_i32 s0, s0, 64
	ds_write_b16 v2, v158
	ds_write_b16 v2, v159 offset:128
	v_add_u32_e32 v2, 0x110, v2
	s_cmpk_eq_i32 s0, 0x800
	s_cbranch_scc0 .LBB0_703
; #define LAS __attribute__((address_space(3)))
; DI f32x4 mfma16(bf16x8 a, bf16x8 b, f32x4 c) { return __builtin_amdgcn_mfma_f32_16x16x32_bf16(a, b, c, 0, 0, 0); }
; DI void s5_disc(const S5P& P, int dir, int g, int p, float& lr, float& li, f32x2 (&bb)[16]) {
;     const float dt = expf(P.log_dt[dir * 64 + g]); const float are = P.a_re[(dir * 64 + g) * 64 + p], aim = P.a_im[(dir * 64 + g) * 64 + p];
;     const float mag = expf(dt * are); lr = mag * cosf(dt * aim); li = mag * sinf(dt * aim);
;     const float den = are * are + aim * aim, nr = lr - 1.0f; const float cr = (nr * are + li * aim) / den, ci = (li * are - nr * aim) / den;
; template <int DIRN, int SUB> DI void s5_subtile(const LAS float* UF, LAS bf16* XT, float lr, float li, const f32x2 (&bb)[16], f32x2& x,
;                                                 const bf16x8 (&bfr)[4], f32x4& acc0, f32x4& acc1, int lane) {
;     ...
;     for (int ks = 0; ks < 4; ++ks) { const bf16x8 a0 = *(const LAS bf16x8*)(XT + (lane & 15) * 136 + 32 * ks + 8 * (lane >> 4)), a1 = *(const LAS bf16x8*)(XT + (16 + (lane & 15)) * 136 + 32 * ks + 8 * (lane >> 4));
;         acc0 = mfma16(a0, bfr[ks], acc0); acc1 = mfma16(a1, bfr[ks], acc1); }
	v_mfma_f32_16x16x32_bf16 v[58:61], v[70:73], v[42:45], v[58:61]
	v_readlane_b32 s16, v252, 4
	v_readlane_b32 s28, v252, 16
	v_readlane_b32 s29, v252, 17
	v_mfma_f32_16x16x32_bf16 v[66:69], v[66:69], v[42:45], v[86:89]
	v_readlane_b32 s26, v252, 14
	v_readlane_b32 s27, v252, 15
	s_mov_b32 s0, 0x3fb8aa3b
	v_mfma_f32_16x16x32_bf16 v[62:65], v[62:65], v[54:57], v[78:81]
	v_readlane_b32 s20, v252, 8
	v_readlane_b32 s21, v252, 9
	v_readlane_b32 s22, v252, 10
	v_mfma_f32_16x16x32_bf16 v[58:61], v[74:77], v[54:57], v[58:61]
	v_readlane_b32 s23, v252, 11
	v_readlane_b32 s17, v252, 5
	v_readlane_b32 s18, v252, 6
	v_mfma_f32_16x16x32_bf16 v[66:69], v[82:85], v[54:57], v[66:69]
	ds_read_b128 v[78:81], v152 offset:8192
	ds_read_b128 v[82:85], v152 offset:8256
	v_readlane_b32 s19, v252, 7
	v_readlane_b32 s24, v252, 12
	v_mfma_f32_16x16x32_bf16 v[74:77], v[90:93], v[38:41], 0
	ds_read_b128 v[86:89], v152 offset:12544
	ds_read_b128 v[90:93], v152 offset:12608
	global_load_dword v2, v3, s[70:71] offset:256
	v_readlane_b32 s25, v252, 13
	s_waitcnt lgkmcnt(1)
	v_mfma_f32_16x16x32_bf16 v[86:89], v[86:89], v[38:41], 0
	v_readlane_b32 s30, v252, 18
	v_readlane_b32 s31, v252, 19
	v_mfma_f32_16x16x32_bf16 v[70:73], v[94:97], v[38:41], 0
	ds_read_b128 v[94:97], v152 offset:8320
	v_mfma_f32_16x16x32_bf16 v[78:81], v[78:81], v[38:41], 0
	s_waitcnt lgkmcnt(1)
	v_mfma_f32_16x16x32_bf16 v[86:89], v[90:93], v[46:49], v[86:89]
	v_add_u32_e32 v90, 0x1000, v122
	v_ashrrev_i32_e32 v91, 31, v90
	v_lshlrev_b64 v[90:91], 2, v[90:91]
	v_lshl_add_u64 v[92:93], s[28:29], 0, v[90:91]
	v_mfma_f32_16x16x32_bf16 v[70:73], v[102:105], v[46:49], v[70:73]
	v_lshl_add_u64 v[90:91], s[26:27], 0, v[90:91]
	v_mfma_f32_16x16x32_bf16 v[74:77], v[98:101], v[46:49], v[74:77]
	v_mfma_f32_16x16x32_bf16 v[78:81], v[82:85], v[46:49], v[78:81]
	ds_read_b128 v[82:85], v152 offset:8384
	ds_read_b128 v[98:101], v152 offset:12672
	ds_read_b128 v[102:105], v152 offset:12736
	global_load_dword v93, v[92:93], off
	s_nop 0
	global_load_dword v92, v[90:91], off
	s_waitcnt lgkmcnt(3)
	v_mfma_f32_16x16x32_bf16 v[78:81], v[94:97], v[42:45], v[78:81]
	s_waitcnt lgkmcnt(2)
	v_mfma_f32_16x16x32_bf16 v[78:81], v[82:85], v[54:57], v[78:81]
	s_waitcnt vmcnt(2)
	v_mul_f32_e32 v82, 0x3fb8aa3b, v2
	v_fma_f32 v83, v2, s0, -v82
	v_rndne_f32_e32 v84, v82
	v_fmac_f32_e32 v83, 0x32a5705f, v2
	v_sub_f32_e32 v82, v82, v84
	v_add_f32_e32 v82, v82, v83
	s_waitcnt lgkmcnt(1)
	v_mfma_f32_16x16x32_bf16 v[86:89], v[98:101], v[42:45], v[86:89]
	v_cvt_i32_f32_e32 v90, v84
	v_exp_f32_e32 v91, v82
	s_mov_b32 s0, 0xc2ce8ed0
	v_mfma_f32_16x16x32_bf16 v[70:73], v[110:113], v[42:45], v[70:73]
	v_cmp_ngt_f32_e32 vcc, s0, v2
	s_mov_b32 s0, 0x42b17218
	v_mfma_f32_16x16x32_bf16 v[74:77], v[106:109], v[42:45], v[74:77]
	s_waitcnt lgkmcnt(0)
	v_mfma_f32_16x16x32_bf16 v[82:85], v[102:105], v[54:57], v[86:89]
	v_mfma_f32_16x16x32_bf16 v[70:73], v[118:121], v[54:57], v[70:73]
	s_nop 1
	v_ldexp_f32 v86, v91, v90
	v_cndmask_b32_e32 v86, 0, v86, vcc
	v_cmp_nlt_f32_e32 vcc, s0, v2
	v_mfma_f32_16x16x32_bf16 v[74:77], v[114:117], v[54:57], v[74:77]
	s_brev_b32 s0, 18
	v_cndmask_b32_e32 v86, v219, v86, vcc
	s_waitcnt vmcnt(1)
	v_mul_f32_e32 v87, v86, v93
	v_and_b32_e32 v88, 0x7fffffff, v87
	v_cmp_nlt_f32_e64 s[20:21], |v87|, s0
	s_and_saveexec_b64 s[0:1], s[20:21]
	s_xor_b64 s[22:23], exec, s[0:1]
	s_cbranch_execz .LBB0_706
	v_lshrrev_b32_e32 v2, 23, v88
	v_add_u32_e32 v2, 0xffffff88, v2
	v_cmp_lt_u32_e32 vcc, 63, v2
	s_mov_b32 s10, 0xfe5163ab
	s_nop 0
	v_cndmask_b32_e32 v89, 0, v220, vcc
	v_add_u32_e32 v2, v89, v2
	v_cmp_lt_u32_e64 s[0:1], 31, v2
	s_nop 1
	v_cndmask_b32_e64 v89, 0, v221, s[0:1]
	v_add_u32_e32 v2, v89, v2
	v_cmp_lt_u32_e64 s[8:9], 31, v2
	s_nop 1
	v_cndmask_b32_e64 v89, 0, v221, s[8:9]
	v_add_u32_e32 v89, v89, v2
	v_and_b32_e32 v2, 0x7fffff, v88
	v_or_b32_e32 v104, 0x800000, v2
	v_mad_u64_u32 v[90:91], s[10:11], v104, s10, 0
	v_mov_b32_e32 v2, v91
	s_mov_b32 s10, 0x3c439041
	v_mad_u64_u32 v[94:95], s[10:11], v104, s10, v[2:3]
	v_mov_b32_e32 v2, v95
	s_mov_b32 s10, 0xdb629599
	v_mad_u64_u32 v[96:97], s[10:11], v104, s10, v[2:3]
	v_mov_b32_e32 v2, v97
	s_mov_b32 s10, 0xf534ddc0
	v_mad_u64_u32 v[98:99], s[10:11], v104, s10, v[2:3]
	v_mov_b32_e32 v2, v99
	s_mov_b32 s10, 0xfc2757d1
	v_mad_u64_u32 v[100:101], s[10:11], v104, s10, v[2:3]
	v_mov_b32_e32 v2, v101
	s_mov_b32 s10, 0x4e441529
	v_mad_u64_u32 v[102:103], s[10:11], v104, s10, v[2:3]
	v_mov_b32_e32 v2, v103
	s_mov_b32 s10, 0xa2f9836e
	v_mad_u64_u32 v[104:105], s[10:11], v104, s10, v[2:3]
	v_cndmask_b32_e32 v91, v102, v98, vcc
	v_cndmask_b32_e32 v2, v104, v100, vcc
	v_cndmask_b32_e32 v97, v105, v102, vcc
	v_cndmask_b32_e64 v95, v2, v91, s[0:1]
	v_cndmask_b32_e64 v2, v97, v2, s[0:1]
	v_cndmask_b32_e32 v97, v100, v96, vcc
	v_cndmask_b32_e64 v91, v91, v97, s[0:1]
	v_sub_u32_e32 v99, 32, v89
	v_cmp_eq_u32_e64 s[10:11], 0, v89
	v_cndmask_b32_e32 v89, v98, v94, vcc
	v_cndmask_b32_e64 v2, v2, v95, s[8:9]
	v_cndmask_b32_e64 v95, v95, v91, s[8:9]
	v_cndmask_b32_e64 v94, v97, v89, s[0:1]
	v_alignbit_b32 v100, v2, v95, v99
	v_cndmask_b32_e64 v91, v91, v94, s[8:9]
	v_cndmask_b32_e64 v2, v100, v2, s[10:11]
	v_alignbit_b32 v97, v95, v91, v99
	v_cndmask_b32_e32 v90, v96, v90, vcc
	v_cndmask_b32_e64 v95, v97, v95, s[10:11]
	v_bfe_u32 v100, v2, 29, 1
	v_cndmask_b32_e64 v89, v89, v90, s[0:1]
	v_alignbit_b32 v97, v2, v95, 30
	v_sub_u32_e32 v101, 0, v100
	v_cndmask_b32_e64 v89, v94, v89, s[8:9]
	v_xor_b32_e32 v97, v97, v101
	v_alignbit_b32 v90, v91, v89, v99
	v_cndmask_b32_e64 v90, v90, v91, s[10:11]
	v_ffbh_u32_e32 v94, v97
	v_alignbit_b32 v91, v95, v90, 30
	v_min_u32_e32 v94, 32, v94
	v_alignbit_b32 v89, v90, v89, 30
	v_xor_b32_e32 v91, v91, v101
	v_sub_u32_e32 v95, 31, v94
	v_xor_b32_e32 v89, v89, v101
	v_alignbit_b32 v96, v97, v91, v95
	v_alignbit_b32 v89, v91, v89, v95
	v_alignbit_b32 v90, v96, v89, 9
	v_ffbh_u32_e32 v91, v90
	v_min_u32_e32 v91, 32, v91
	v_lshrrev_b32_e32 v98, 29, v2
	v_not_b32_e32 v95, v91
	v_alignbit_b32 v89, v90, v89, v95
	v_lshlrev_b32_e32 v90, 31, v98
	v_or_b32_e32 v95, 0x33000000, v90
	v_add_lshl_u32 v91, v91, v94, 23
	v_lshrrev_b32_e32 v89, 9, v89
	v_sub_u32_e32 v91, v95, v91
	v_or_b32_e32 v90, 0.5, v90
	v_lshlrev_b32_e32 v94, 23, v94
	v_or_b32_e32 v89, v91, v89
	v_lshrrev_b32_e32 v91, 9, v96
	v_sub_u32_e32 v90, v90, v94
	v_or_b32_e32 v90, v91, v90
	v_mul_f32_e32 v91, 0x3fc90fda, v90
	s_mov_b32 s0, 0x3fc90fda
	v_fma_f32 v94, v90, s0, -v91
	v_fmac_f32_e32 v94, 0x33a22168, v90
	v_fmac_f32_e32 v94, 0x3fc90fda, v89
	v_lshrrev_b32_e32 v2, 30, v2
	v_add_f32_e32 v90, v91, v94
	v_add_u32_e32 v89, v100, v2

; #define LAS __attribute__((address_space(3)))
; DI unsigned pk2(float lo, float hi) { return pg8::cvt_pk_bf16(lo, hi); }
; DI f32x4 mfma16(bf16x8 a, bf16x8 b, f32x4 c) { return __builtin_amdgcn_mfma_f32_16x16x32_bf16(a, b, c, 0, 0, 0); }
; template <int DIRN, int SUB> DI void s5_subtile(const LAS float* UF, LAS bf16* XT, float lr, float li, const f32x2 (&bb)[16], f32x2& x,
;                                                 const bf16x8 (&bfr)[4], f32x4& acc0, f32x4& acc1, int lane) {
; #pragma unroll 1
;     for (int i = 0; i < 32; ++i) { const int r = DIRN ? 31 - i : i;
;         x = s5_step((const LAS f32x4*)(UF + (32 * SUB + r) * 16), bb, lr, li, x);
;         const unsigned pkd = pk2(x.x, x.y); XT[r * 136 + lane] = (bf16)(pkd & 0xffffu); XT[r * 136 + 64 + lane] = (bf16)(pkd >> 16); }
; #pragma unroll
;     for (int ks = 0; ks < 4; ++ks) { const bf16x8 a0 = *(const LAS bf16x8*)(XT + (lane & 15) * 136 + 32 * ks + 8 * (lane >> 4)), a1 = *(const LAS bf16x8*)(XT + (16 + (lane & 15)) * 136 + 32 * ks + 8 * (lane >> 4));
;         acc0 = mfma16(a0, bfr[ks], acc0); acc1 = mfma16(a1, bfr[ks], acc1); }
.LBB0_725:
	s_add_i32 s1, s43, s0
	v_mov_b32_e32 v2, s1
	ds_read_b128 v[6:9], v2
	ds_read_b128 v[10:13], v2 offset:16
	ds_read_b128 v[14:17], v2 offset:32
	ds_read_b128 v[18:21], v2 offset:48
	s_waitcnt lgkmcnt(3)
	v_pk_mul_f32 v[22:23], v[96:97], v[6:7] op_sel:[0,1]
	v_pk_fma_f32 v[6:7], v[94:95], v[6:7], v[22:23] op_sel_hi:[1,0,1]
	v_mov_b32_e32 v2, v9
	v_pk_fma_f32 v[6:7], v[34:35], v[8:9], v[6:7] op_sel_hi:[1,0,1]
	s_waitcnt lgkmcnt(1)
	v_pk_mul_f32 v[8:9], v[104:105], v[14:15] op_sel:[0,1]
	v_pk_fma_f32 v[6:7], v[30:31], v[2:3], v[6:7] op_sel_hi:[1,0,1]
	v_mov_b32_e32 v2, v13
	v_pk_fma_f32 v[6:7], v[32:33], v[10:11], v[6:7] op_sel_hi:[1,0,1]
	v_pk_fma_f32 v[8:9], v[102:103], v[14:15], v[8:9] op_sel_hi:[1,0,1]
	v_pk_fma_f32 v[6:7], v[36:37], v[10:11], v[6:7] op_sel:[0,1,0]
	v_pk_fma_f32 v[8:9], v[106:107], v[16:17], v[8:9] op_sel_hi:[1,0,1]
	v_pk_fma_f32 v[6:7], v[98:99], v[12:13], v[6:7] op_sel_hi:[1,0,1]
	v_pk_fma_f32 v[6:7], v[100:101], v[2:3], v[6:7] op_sel_hi:[1,0,1]
	v_mov_b32_e32 v2, v17
	v_pk_fma_f32 v[8:9], v[108:109], v[2:3], v[8:9] op_sel_hi:[1,0,1]
	s_waitcnt lgkmcnt(0)
	v_mov_b32_e32 v2, v21
	v_pk_fma_f32 v[8:9], v[110:111], v[18:19], v[8:9] op_sel_hi:[1,0,1]
	v_pk_fma_f32 v[8:9], v[112:113], v[18:19], v[8:9] op_sel:[0,1,0]
	v_pk_fma_f32 v[8:9], v[114:115], v[20:21], v[8:9] op_sel_hi:[1,0,1]
	v_pk_fma_f32 v[8:9], v[92:93], v[2:3], v[8:9] op_sel_hi:[1,0,1]
	v_pk_add_f32 v[6:7], v[6:7], v[8:9]
	v_pk_fma_f32 v[6:7], v[88:89], v[90:91], v[6:7] op_sel:[0,1,0] op_sel_hi:[1,0,1]
	v_pk_fma_f32 v[90:91], v[86:87], v[90:91], v[6:7]
	s_nop 0
	v_cvt_pk_bf16_f32 v2, v90, s0
	v_cvt_pk_bf16_f32 v6, v91, s0
	s_sub_i32 s0, s0, 64
	ds_write_b16 v1, v2
	ds_write_b16 v1, v6 offset:128
	v_add_u32_e32 v1, 0xfffffef0, v1
	s_cmpk_lg_i32 s0, 0xf800
	s_cbranch_scc1 .LBB0_725
	ds_read_b128 v[6:9], v152 offset:8192
	ds_read_b128 v[10:13], v152 offset:12544
	ds_read_b128 v[14:17], v152 offset:8256
	ds_read_b128 v[18:21], v152 offset:12608
	v_add_u32_e32 v1, 0x40f0, v206
	s_movk_i32 s0, 0x17c0
	s_waitcnt lgkmcnt(3)
	v_mfma_f32_16x16x32_bf16 v[6:9], v[6:9], v[38:41], v[78:81]
	v_mov_b32_e32 v2, v1
	s_waitcnt lgkmcnt(2)
	v_mfma_f32_16x16x32_bf16 v[10:13], v[10:13], v[38:41], v[82:85]
	s_waitcnt lgkmcnt(1)
	v_mfma_f32_16x16x32_bf16 v[6:9], v[14:17], v[46:49], v[6:9]
	s_waitcnt lgkmcnt(0)
	v_mfma_f32_16x16x32_bf16 v[10:13], v[18:21], v[46:49], v[10:13]
	ds_read_b128 v[14:17], v152 offset:8320
	ds_read_b128 v[18:21], v152 offset:12672
	s_waitcnt lgkmcnt(1)
	v_mfma_f32_16x16x32_bf16 v[6:9], v[14:17], v[42:45], v[6:9]
	s_waitcnt lgkmcnt(0)
	v_mfma_f32_16x16x32_bf16 v[14:17], v[18:21], v[42:45], v[10:13]
	s_nop 2
	ds_read_b128 v[10:13], v152 offset:8384
	ds_read_b128 v[18:21], v152 offset:12736
	s_waitcnt lgkmcnt(1)
	v_mfma_f32_16x16x32_bf16 v[10:13], v[10:13], v[54:57], v[6:9]
	s_waitcnt lgkmcnt(0)
	v_mfma_f32_16x16x32_bf16 v[6:9], v[18:21], v[54:57], v[14:17]
.LBB0_727:
	s_add_i32 s1, s49, s0
	v_mov_b32_e32 v26, s1
	s_nop 0
	ds_read_b128 v[14:17], v26
	ds_read_b128 v[18:21], v26 offset:16
	ds_read_b128 v[22:25], v26 offset:32
	ds_read_b128 v[26:29], v26 offset:48
	s_waitcnt lgkmcnt(3)
	v_pk_mul_f32 v[78:79], v[96:97], v[14:15] op_sel:[0,1]
	v_pk_fma_f32 v[14:15], v[94:95], v[14:15], v[78:79] op_sel_hi:[1,0,1]
	v_pk_fma_f32 v[14:15], v[34:35], v[16:17], v[14:15] op_sel_hi:[1,0,1]
	v_mov_b32_e32 v16, v17
	v_pk_fma_f32 v[14:15], v[30:31], v[16:17], v[14:15] op_sel_hi:[1,0,1]
	s_waitcnt lgkmcnt(2)
	v_mov_b32_e32 v16, v21
	v_pk_fma_f32 v[14:15], v[32:33], v[18:19], v[14:15] op_sel_hi:[1,0,1]
	v_pk_fma_f32 v[14:15], v[36:37], v[18:19], v[14:15] op_sel:[0,1,0]
	s_waitcnt lgkmcnt(1)
	v_mov_b32_e32 v18, v25
	v_pk_fma_f32 v[14:15], v[98:99], v[20:21], v[14:15] op_sel_hi:[1,0,1]
	v_pk_fma_f32 v[14:15], v[100:101], v[16:17], v[14:15] op_sel_hi:[1,0,1]
	v_pk_mul_f32 v[16:17], v[104:105], v[22:23] op_sel:[0,1]
	v_pk_fma_f32 v[16:17], v[102:103], v[22:23], v[16:17] op_sel_hi:[1,0,1]
	v_pk_fma_f32 v[16:17], v[106:107], v[24:25], v[16:17] op_sel_hi:[1,0,1]
	v_pk_fma_f32 v[16:17], v[108:109], v[18:19], v[16:17] op_sel_hi:[1,0,1]
	s_waitcnt lgkmcnt(0)
	v_mov_b32_e32 v18, v29
	v_pk_fma_f32 v[16:17], v[110:111], v[26:27], v[16:17] op_sel_hi:[1,0,1]
	v_pk_fma_f32 v[16:17], v[112:113], v[26:27], v[16:17] op_sel:[0,1,0]
	v_pk_fma_f32 v[16:17], v[114:115], v[28:29], v[16:17] op_sel_hi:[1,0,1]
	v_pk_fma_f32 v[16:17], v[92:93], v[18:19], v[16:17] op_sel_hi:[1,0,1]
	v_pk_add_f32 v[14:15], v[14:15], v[16:17]
	v_add_u32_e32 v16, s49, v2
	v_pk_fma_f32 v[14:15], v[88:89], v[90:91], v[14:15] op_sel:[0,1,0] op_sel_hi:[1,0,1]
	v_add_u32_e32 v2, 0xfffffef0, v2
	v_pk_fma_f32 v[90:91], v[86:87], v[90:91], v[14:15]
	s_nop 0
	v_cvt_pk_bf16_f32 v14, v90, s0
	v_cvt_pk_bf16_f32 v15, v91, s0
	s_sub_i32 s0, s0, 64
	s_cmpk_lg_i32 s0, 0xfc0
	ds_write_b16 v16, v14
	ds_write_b16 v16, v15 offset:128
	s_cbranch_scc1 .LBB0_727
	ds_read_b128 v[14:17], v152 offset:8192
	ds_read_b128 v[22:25], v152 offset:8256
	ds_read_b128 v[18:21], v152 offset:12544
	s_movk_i32 s0, 0xfc0
	v_mov_b32_e32 v2, v1
	s_waitcnt lgkmcnt(2)
	v_mfma_f32_16x16x32_bf16 v[14:17], v[14:17], v[38:41], v[70:73]
	s_waitcnt lgkmcnt(1)
	v_mfma_f32_16x16x32_bf16 v[14:17], v[22:25], v[46:49], v[14:17]
	ds_read_b128 v[22:25], v152 offset:12608
	s_waitcnt lgkmcnt(1)
	v_mfma_f32_16x16x32_bf16 v[18:21], v[18:21], v[38:41], v[74:77]
	s_waitcnt lgkmcnt(0)
	v_mfma_f32_16x16x32_bf16 v[18:21], v[22:25], v[46:49], v[18:21]
	ds_read_b128 v[22:25], v152 offset:8320
	s_waitcnt lgkmcnt(0)
	v_mfma_f32_16x16x32_bf16 v[14:17], v[22:25], v[42:45], v[14:17]
	ds_read_b128 v[22:25], v152 offset:12672
	s_waitcnt lgkmcnt(0)
	v_mfma_f32_16x16x32_bf16 v[22:25], v[22:25], v[42:45], v[18:21]
	s_nop 2
	ds_read_b128 v[18:21], v152 offset:8384
	s_waitcnt lgkmcnt(0)
	v_mfma_f32_16x16x32_bf16 v[18:21], v[18:21], v[54:57], v[14:17]
	s_nop 2
	ds_read_b128 v[14:17], v152 offset:12736
	s_waitcnt lgkmcnt(0)
	v_mfma_f32_16x16x32_bf16 v[14:17], v[14:17], v[54:57], v[22:25]
; #define LAS __attribute__((address_space(3)))
; DI unsigned pk2(float lo, float hi) { return pg8::cvt_pk_bf16(lo, hi); }
; DI f32x4 mfma16(bf16x8 a, bf16x8 b, f32x4 c) { return __builtin_amdgcn_mfma_f32_16x16x32_bf16(a, b, c, 0, 0, 0); }
; template <int DIRN, int SUB> DI void s5_subtile(const LAS float* UF, LAS bf16* XT, float lr, float li, const f32x2 (&bb)[16], f32x2& x,
;                                                 const bf16x8 (&bfr)[4], f32x4& acc0, f32x4& acc1, int lane) {
; #pragma unroll 1
;     for (int i = 0; i < 32; ++i) { const int r = DIRN ? 31 - i : i;
;         x = s5_step((const LAS f32x4*)(UF + (32 * SUB + r) * 16), bb, lr, li, x);
;         const unsigned pkd = pk2(x.x, x.y); XT[r * 136 + lane] = (bf16)(pkd & 0xffffu); XT[r * 136 + 64 + lane] = (bf16)(pkd >> 16); }
; #pragma unroll
;     for (int ks = 0; ks < 4; ++ks) { const bf16x8 a0 = *(const LAS bf16x8*)(XT + (lane & 15) * 136 + 32 * ks + 8 * (lane >> 4)), a1 = *(const LAS bf16x8*)(XT + (16 + (lane & 15)) * 136 + 32 * ks + 8 * (lane >> 4));
;         acc0 = mfma16(a0, bfr[ks], acc0); acc1 = mfma16(a1, bfr[ks], acc1); }
.LBB0_729:
	s_add_i32 s1, s49, s0
	v_mov_b32_e32 v74, s1
	s_nop 0
	ds_read_b128 v[22:25], v74
	ds_read_b128 v[26:29], v74 offset:16
	ds_read_b128 v[70:73], v74 offset:32
	ds_read_b128 v[74:77], v74 offset:48
	s_waitcnt lgkmcnt(3)
	v_pk_mul_f32 v[78:79], v[96:97], v[22:23] op_sel:[0,1]
	v_pk_fma_f32 v[22:23], v[94:95], v[22:23], v[78:79] op_sel_hi:[1,0,1]
	v_pk_fma_f32 v[22:23], v[34:35], v[24:25], v[22:23] op_sel_hi:[1,0,1]
	v_mov_b32_e32 v24, v25
	v_pk_fma_f32 v[22:23], v[30:31], v[24:25], v[22:23] op_sel_hi:[1,0,1]
	s_waitcnt lgkmcnt(2)
	v_mov_b32_e32 v24, v29
	v_pk_fma_f32 v[22:23], v[32:33], v[26:27], v[22:23] op_sel_hi:[1,0,1]
	v_pk_fma_f32 v[22:23], v[36:37], v[26:27], v[22:23] op_sel:[0,1,0]
	s_waitcnt lgkmcnt(1)
	v_mov_b32_e32 v26, v73
	v_pk_fma_f32 v[22:23], v[98:99], v[28:29], v[22:23] op_sel_hi:[1,0,1]
	v_pk_fma_f32 v[22:23], v[100:101], v[24:25], v[22:23] op_sel_hi:[1,0,1]
	v_pk_mul_f32 v[24:25], v[104:105], v[70:71] op_sel:[0,1]
	v_pk_fma_f32 v[24:25], v[102:103], v[70:71], v[24:25] op_sel_hi:[1,0,1]
	v_pk_fma_f32 v[24:25], v[106:107], v[72:73], v[24:25] op_sel_hi:[1,0,1]
	v_pk_fma_f32 v[24:25], v[108:109], v[26:27], v[24:25] op_sel_hi:[1,0,1]
	s_waitcnt lgkmcnt(0)
	v_mov_b32_e32 v26, v77
	v_pk_fma_f32 v[24:25], v[110:111], v[74:75], v[24:25] op_sel_hi:[1,0,1]
	v_pk_fma_f32 v[24:25], v[112:113], v[74:75], v[24:25] op_sel:[0,1,0]
	v_pk_fma_f32 v[24:25], v[114:115], v[76:77], v[24:25] op_sel_hi:[1,0,1]
	v_pk_fma_f32 v[24:25], v[92:93], v[26:27], v[24:25] op_sel_hi:[1,0,1]
	v_pk_add_f32 v[22:23], v[22:23], v[24:25]
	v_add_u32_e32 v24, s49, v2
	v_pk_fma_f32 v[22:23], v[88:89], v[90:91], v[22:23] op_sel:[0,1,0] op_sel_hi:[1,0,1]
	v_add_u32_e32 v2, 0xfffffef0, v2
	v_pk_fma_f32 v[90:91], v[86:87], v[90:91], v[22:23]
	s_nop 0
	v_cvt_pk_bf16_f32 v22, v90, s0
	v_cvt_pk_bf16_f32 v23, v91, s0
	s_sub_i32 s0, s0, 64
	s_cmpk_lg_i32 s0, 0x7c0
	ds_write_b16 v24, v22
	ds_write_b16 v24, v23 offset:128
	s_cbranch_scc1 .LBB0_729
	ds_read_b128 v[22:25], v152 offset:8192
	ds_read_b128 v[26:29], v152 offset:12544
	s_movk_i32 s0, 0x7c0
	s_waitcnt lgkmcnt(1)
	v_mfma_f32_16x16x32_bf16 v[22:25], v[22:25], v[38:41], v[62:65]
	s_nop 2
	ds_read_b128 v[62:65], v152 offset:8256
	s_waitcnt lgkmcnt(1)
	v_mfma_f32_16x16x32_bf16 v[26:29], v[26:29], v[38:41], v[66:69]
	s_waitcnt lgkmcnt(0)
	v_mfma_f32_16x16x32_bf16 v[22:25], v[62:65], v[46:49], v[22:25]
	ds_read_b128 v[62:65], v152 offset:12608
	s_waitcnt lgkmcnt(0)
	v_mfma_f32_16x16x32_bf16 v[26:29], v[62:65], v[46:49], v[26:29]
	ds_read_b128 v[62:65], v152 offset:8320
	s_waitcnt lgkmcnt(0)
	v_mfma_f32_16x16x32_bf16 v[22:25], v[62:65], v[42:45], v[22:25]
	ds_read_b128 v[62:65], v152 offset:12672
	s_waitcnt lgkmcnt(0)
	v_mfma_f32_16x16x32_bf16 v[62:65], v[62:65], v[42:45], v[26:29]
	s_nop 2
	ds_read_b128 v[26:29], v152 offset:8384
	s_waitcnt lgkmcnt(0)
	v_mfma_f32_16x16x32_bf16 v[26:29], v[26:29], v[54:57], v[22:25]
	s_nop 2
	ds_read_b128 v[22:25], v152 offset:12736
	s_waitcnt lgkmcnt(0)
	v_mfma_f32_16x16x32_bf16 v[22:25], v[22:25], v[54:57], v[62:65]
.LBB0_731:
	s_add_i32 s1, s49, s0
	v_mov_b32_e32 v2, s1
	s_nop 0
	ds_read_b128 v[62:65], v2
	ds_read_b128 v[66:69], v2 offset:16
	ds_read_b128 v[70:73], v2 offset:32
	ds_read_b128 v[74:77], v2 offset:48
	s_waitcnt lgkmcnt(3)
	v_pk_mul_f32 v[78:79], v[96:97], v[62:63] op_sel:[0,1]
	v_pk_fma_f32 v[62:63], v[94:95], v[62:63], v[78:79] op_sel_hi:[1,0,1]
	v_mov_b32_e32 v2, v65
	v_pk_fma_f32 v[62:63], v[34:35], v[64:65], v[62:63] op_sel_hi:[1,0,1]
	s_waitcnt lgkmcnt(1)
	v_pk_mul_f32 v[64:65], v[104:105], v[70:71] op_sel:[0,1]
	v_pk_fma_f32 v[62:63], v[30:31], v[2:3], v[62:63] op_sel_hi:[1,0,1]
	v_mov_b32_e32 v2, v69
	v_pk_fma_f32 v[62:63], v[32:33], v[66:67], v[62:63] op_sel_hi:[1,0,1]
	v_pk_fma_f32 v[64:65], v[102:103], v[70:71], v[64:65] op_sel_hi:[1,0,1]
	v_pk_fma_f32 v[62:63], v[36:37], v[66:67], v[62:63] op_sel:[0,1,0]
	v_pk_fma_f32 v[64:65], v[106:107], v[72:73], v[64:65] op_sel_hi:[1,0,1]
	v_pk_fma_f32 v[62:63], v[98:99], v[68:69], v[62:63] op_sel_hi:[1,0,1]
	v_pk_fma_f32 v[62:63], v[100:101], v[2:3], v[62:63] op_sel_hi:[1,0,1]
	v_mov_b32_e32 v2, v73
	v_pk_fma_f32 v[64:65], v[108:109], v[2:3], v[64:65] op_sel_hi:[1,0,1]
	s_waitcnt lgkmcnt(0)
	v_mov_b32_e32 v2, v77
	v_pk_fma_f32 v[64:65], v[110:111], v[74:75], v[64:65] op_sel_hi:[1,0,1]
	v_pk_fma_f32 v[64:65], v[112:113], v[74:75], v[64:65] op_sel:[0,1,0]
	v_pk_fma_f32 v[64:65], v[114:115], v[76:77], v[64:65] op_sel_hi:[1,0,1]
	v_pk_fma_f32 v[64:65], v[92:93], v[2:3], v[64:65] op_sel_hi:[1,0,1]
	v_pk_add_f32 v[62:63], v[62:63], v[64:65]
	v_pk_fma_f32 v[62:63], v[88:89], v[90:91], v[62:63] op_sel:[0,1,0] op_sel_hi:[1,0,1]
	v_pk_fma_f32 v[90:91], v[86:87], v[90:91], v[62:63]
	v_add_u32_e32 v63, s49, v1
	v_cvt_pk_bf16_f32 v2, v90, s0
	v_cvt_pk_bf16_f32 v62, v91, s0
	s_sub_i32 s0, s0, 64
	v_add_u32_e32 v1, 0xfffffef0, v1
	s_cmpk_eq_i32 s0, 0xffc0
	ds_write_b16 v63, v2
	ds_write_b16 v63, v62 offset:128
	s_cbranch_scc0 .LBB0_731
; DI bf16 f2bf(float f) { return (bf16)(pk2(f, 0.f) & 0xffffu); }
; DI float gelu_tanh(float x) { const float u = 0.7978845608028654f * (x + 0.044715f * x * x * x); return x * sigm(2.0f * u); }
; DI void s5_passC(const Ctx& C, const S5P& P, const bf16* PROJ, const f32x2* END, bf16* YG  , int item_lo, int item_hi) {
;     ...
;         const float dv = P.d[g * 16 + (lane & 15)];
; #pragma unroll
;         for (int r = 0; r < 8; ++r)
; #pragma unroll
;             for (int j = 0; j < 4; ++j) { const int t = 16 * r + (lane >> 4) * 4 + j; const float y = acc[r][j] + dv * UF[t * 16 + (lane & 15)]; YG[(tok0 + t) * 1024 + g * 16 + (lane & 15)] = f2bf(gelu_tanh(y)); }
	ds_read_b128 v[30:33], v152 offset:8192
	ds_read_b128 v[34:37], v152 offset:12544
	v_lshlrev_b32_e32 v1, 2, v123
	v_readlane_b32 s16, v252, 20
	v_lshl_or_b32 v2, s52, 6, v1
	s_waitcnt lgkmcnt(1)
	v_mfma_f32_16x16x32_bf16 v[30:33], v[30:33], v[38:41], v[50:53]
	v_readlane_b32 s24, v252, 28
	v_readlane_b32 s25, v252, 29
	s_lshl_b32 s0, s52, 5
	s_waitcnt lgkmcnt(0)
	v_mfma_f32_16x16x32_bf16 v[34:37], v[34:37], v[38:41], v[58:61]
	ds_read_b128 v[38:41], v152 offset:8256
	ds_read_b128 v[50:53], v152 offset:12608
	s_add_u32 s0, s47, s0
	s_addc_u32 s1, s48, 0
	s_waitcnt lgkmcnt(1)
	v_mfma_f32_16x16x32_bf16 v[30:33], v[38:41], v[46:49], v[30:33]
	v_readlane_b32 s17, v252, 21
	v_readlane_b32 s18, v252, 22
	v_readlane_b32 s19, v252, 23
	s_waitcnt lgkmcnt(0)
	v_mfma_f32_16x16x32_bf16 v[34:37], v[50:53], v[46:49], v[34:37]
	ds_read_b128 v[38:41], v152 offset:8320
	ds_read_b128 v[46:49], v152 offset:12672
	v_readlane_b32 s20, v252, 24
	v_readlane_b32 s21, v252, 25
	s_waitcnt lgkmcnt(1)
	v_mfma_f32_16x16x32_bf16 v[30:33], v[38:41], v[42:45], v[30:33]
	v_readlane_b32 s22, v252, 26
	v_readlane_b32 s23, v252, 27
	v_readlane_b32 s26, v252, 30
	s_waitcnt lgkmcnt(0)
	v_mfma_f32_16x16x32_bf16 v[38:41], v[46:49], v[42:45], v[34:37]
	s_nop 2
	ds_read_b128 v[34:37], v152 offset:8384
	ds_read_b128 v[42:45], v152 offset:12736
	v_readlane_b32 s27, v252, 31
	v_readlane_b32 s28, v252, 32
	s_waitcnt lgkmcnt(1)
	v_mfma_f32_16x16x32_bf16 v[34:37], v[34:37], v[54:57], v[30:33]
	v_readlane_b32 s29, v252, 33
	v_readlane_b32 s30, v252, 34
	v_readlane_b32 s31, v252, 35
	s_waitcnt lgkmcnt(0)
	v_mfma_f32_16x16x32_bf16 v[30:33], v[42:45], v[54:57], v[38:41]
	v_ashrrev_i32_e32 v44, 2, v0
	s_nop 1
	global_load_dword v40, v2, s[24:25]
	v_and_b32_e32 v38, -4, v44
	v_add_u32_e32 v41, s49, v1
	v_lshlrev_b32_e32 v2, 1, v123
	v_lshl_add_u64 v[0:1], s[0:1], 0, v[2:3]
	v_lshl_add_u32 v2, v38, 6, v41
	ds_read_b32 v2, v2
	v_ashrrev_i32_e32 v39, 31, v38
	v_lshl_add_u64 v[42:43], s[12:13], 0, v[38:39]
	v_lshlrev_b64 v[42:43], 11, v[42:43]
	v_lshl_add_u64 v[42:43], v[0:1], 0, v[42:43]
	s_waitcnt vmcnt(0) lgkmcnt(0)
	v_fma_f32 v2, v40, v2, v34
	v_mul_f32_e32 v34, 0x3d372713, v2
	v_mul_f32_e32 v34, v2, v34
	v_fma_f32 v34, v2, v34, v2
	v_mul_f32_e32 v34, 0x3f4c422a, v34
	v_add_f32_e32 v34, v34, v34
	v_mul_f32_e32 v34, 0xbfb8aa3b, v34
	v_exp_f32_e32 v34, v34
	s_nop 0
	v_add_f32_e32 v34, 1.0, v34
	v_rcp_f32_e32 v34, v34
	s_nop 0
	v_mul_f32_e32 v2, v2, v34
	v_cvt_pk_bf16_f32 v2, v2, s0
	v_or_b32_e32 v34, 1, v38
	global_store_short v[42:43], v2, off
	v_lshl_add_u32 v2, v34, 6, v41
	ds_read_b32 v2, v2
	s_waitcnt lgkmcnt(0)
	v_fma_f32 v2, v40, v2, v35
	v_mul_f32_e32 v35, 0x3d372713, v2
	v_mul_f32_e32 v35, v2, v35
	v_fma_f32 v35, v2, v35, v2
	v_mul_f32_e32 v35, 0x3f4c422a, v35
	v_add_f32_e32 v35, v35, v35
	v_mul_f32_e32 v35, 0xbfb8aa3b, v35
	v_exp_f32_e32 v35, v35
	s_nop 0
	v_add_f32_e32 v35, 1.0, v35
	v_rcp_f32_e32 v35, v35
	s_nop 0
	v_mul_f32_e32 v2, v2, v35
	v_ashrrev_i32_e32 v35, 31, v34
	v_lshl_add_u64 v[34:35], s[12:13], 0, v[34:35]
	v_lshlrev_b64 v[34:35], 11, v[34:35]
	v_cvt_pk_bf16_f32 v2, v2, s0
	v_lshl_add_u64 v[34:35], v[0:1], 0, v[34:35]
	global_store_short v[34:35], v2, off
	v_or_b32_e32 v34, 2, v38
	v_lshl_add_u32 v2, v34, 6, v41
	ds_read_b32 v2, v2
	s_waitcnt lgkmcnt(0)
	v_fma_f32 v2, v40, v2, v36
	v_mul_f32_e32 v35, 0x3d372713, v2
	v_mul_f32_e32 v35, v2, v35
	v_fma_f32 v35, v2, v35, v2
	v_mul_f32_e32 v35, 0x3f4c422a, v35
	v_add_f32_e32 v35, v35, v35
	v_mul_f32_e32 v35, 0xbfb8aa3b, v35
	v_exp_f32_e32 v35, v35
	s_nop 0
	v_add_f32_e32 v35, 1.0, v35
	v_rcp_f32_e32 v35, v35
	s_nop 0
	v_mul_f32_e32 v2, v2, v35
	v_ashrrev_i32_e32 v35, 31, v34
	v_lshl_add_u64 v[34:35], s[12:13], 0, v[34:35]
	v_lshlrev_b64 v[34:35], 11, v[34:35]
	v_cvt_pk_bf16_f32 v2, v2, s0
	v_lshl_add_u64 v[34:35], v[0:1], 0, v[34:35]
	global_store_short v[34:35], v2, off
	v_or_b32_e32 v34, 3, v44
	v_lshl_add_u32 v2, v34, 6, v41
	ds_read_b32 v2, v2
	v_ashrrev_i32_e32 v35, 31, v34
	v_lshl_add_u64 v[34:35], s[12:13], 0, v[34:35]
	v_lshlrev_b64 v[34:35], 11, v[34:35]
	v_lshl_add_u64 v[34:35], v[0:1], 0, v[34:35]
	s_waitcnt lgkmcnt(0)
	v_fmac_f32_e32 v37, v40, v2
	v_mul_f32_e32 v2, 0x3d372713, v37
	v_mul_f32_e32 v2, v37, v2
	v_fma_f32 v2, v37, v2, v37
	v_mul_f32_e32 v2, 0x3f4c422a, v2
	v_add_f32_e32 v2, v2, v2
	v_mul_f32_e32 v2, 0xbfb8aa3b, v2
	v_exp_f32_e32 v2, v2
	s_nop 0
	v_add_f32_e32 v2, 1.0, v2
	v_rcp_f32_e32 v2, v2
	s_nop 0
	v_mul_f32_e32 v2, v37, v2
	v_cvt_pk_bf16_f32 v2, v2, s0
	global_store_short v[34:35], v2, off
	v_add_u32_e32 v34, 16, v38
	v_lshl_add_u32 v2, v34, 6, v41
	ds_read_b32 v2, v2
	v_ashrrev_i32_e32 v35, 31, v34
	v_lshl_add_u64 v[34:35], s[12:13], 0, v[34:35]
	v_lshlrev_b64 v[34:35], 11, v[34:35]
	v_lshl_add_u64 v[34:35], v[0:1], 0, v[34:35]
	s_waitcnt lgkmcnt(0)
	v_fma_f32 v2, v40, v2, v30
	v_mul_f32_e32 v30, 0x3d372713, v2
	v_mul_f32_e32 v30, v2, v30
	v_fma_f32 v30, v2, v30, v2
	v_mul_f32_e32 v30, 0x3f4c422a, v30
	v_add_f32_e32 v30, v30, v30
	v_mul_f32_e32 v30, 0xbfb8aa3b, v30
	v_exp_f32_e32 v30, v30
	s_nop 0
	v_add_f32_e32 v30, 1.0, v30
	v_rcp_f32_e32 v30, v30
	s_nop 0
	v_mul_f32_e32 v2, v2, v30
	v_cvt_pk_bf16_f32 v2, v2, s0
	v_add_u32_e32 v30, 17, v38
	global_store_short v[34:35], v2, off
	v_lshl_add_u32 v2, v30, 6, v41
	ds_read_b32 v2, v2
	s_waitcnt lgkmcnt(0)
	v_fma_f32 v2, v40, v2, v31
	v_mul_f32_e32 v31, 0x3d372713, v2
	v_mul_f32_e32 v31, v2, v31
	v_fma_f32 v31, v2, v31, v2
	v_mul_f32_e32 v31, 0x3f4c422a, v31
	v_add_f32_e32 v31, v31, v31
	v_mul_f32_e32 v31, 0xbfb8aa3b, v31
	v_exp_f32_e32 v31, v31
	s_nop 0
	v_add_f32_e32 v31, 1.0, v31
	v_rcp_f32_e32 v31, v31
	s_nop 0
	v_mul_f32_e32 v2, v2, v31
	v_ashrrev_i32_e32 v31, 31, v30
	v_lshl_add_u64 v[30:31], s[12:13], 0, v[30:31]
	v_lshlrev_b64 v[30:31], 11, v[30:31]
	v_cvt_pk_bf16_f32 v2, v2, s0
	v_lshl_add_u64 v[30:31], v[0:1], 0, v[30:31]
	global_store_short v[30:31], v2, off
	v_add_u32_e32 v30, 18, v38
	v_lshl_add_u32 v2, v30, 6, v41
	ds_read_b32 v2, v2
	s_waitcnt lgkmcnt(0)
; DI bf16 f2bf(float f) { return (bf16)(pk2(f, 0.f) & 0xffffu); }
; DI float gelu_tanh(float x) { const float u = 0.7978845608028654f * (x + 0.044715f * x * x * x); return x * sigm(2.0f * u); }
; DI void s5_passC(const Ctx& C, const S5P& P, const bf16* PROJ, const f32x2* END, bf16* YG  , int item_lo, int item_hi) {
;     ...
;         const float dv = P.d[g * 16 + (lane & 15)];
; #pragma unroll
;         for (int r = 0; r < 8; ++r)
; #pragma unroll
;             for (int j = 0; j < 4; ++j) { const int t = 16 * r + (lane >> 4) * 4 + j; const float y = acc[r][j] + dv * UF[t * 16 + (lane & 15)]; YG[(tok0 + t) * 1024 + g * 16 + (lane & 15)] = f2bf(gelu_tanh(y)); }
	v_fma_f32 v2, v40, v2, v32
	v_mul_f32_e32 v31, 0x3d372713, v2
	v_mul_f32_e32 v31, v2, v31
	v_fma_f32 v31, v2, v31, v2
	v_mul_f32_e32 v31, 0x3f4c422a, v31
	v_add_f32_e32 v31, v31, v31
	v_mul_f32_e32 v31, 0xbfb8aa3b, v31
	v_exp_f32_e32 v31, v31
	s_nop 0
	v_add_f32_e32 v31, 1.0, v31
	v_rcp_f32_e32 v31, v31
	s_nop 0
	v_mul_f32_e32 v2, v2, v31
	v_ashrrev_i32_e32 v31, 31, v30
	v_lshl_add_u64 v[30:31], s[12:13], 0, v[30:31]
	v_lshlrev_b64 v[30:31], 11, v[30:31]
	v_cvt_pk_bf16_f32 v2, v2, s0
	v_lshl_add_u64 v[30:31], v[0:1], 0, v[30:31]
	global_store_short v[30:31], v2, off
	v_add_u32_e32 v30, 19, v38
	v_lshl_add_u32 v2, v30, 6, v41
	ds_read_b32 v2, v2
	v_ashrrev_i32_e32 v31, 31, v30
	v_lshl_add_u64 v[30:31], s[12:13], 0, v[30:31]
	v_lshlrev_b64 v[30:31], 11, v[30:31]
	v_lshl_add_u64 v[30:31], v[0:1], 0, v[30:31]
	s_waitcnt lgkmcnt(0)
	v_fmac_f32_e32 v33, v40, v2
	v_mul_f32_e32 v2, 0x3d372713, v33
	v_mul_f32_e32 v2, v33, v2
	v_fma_f32 v2, v33, v2, v33
	v_mul_f32_e32 v2, 0x3f4c422a, v2
	v_add_f32_e32 v2, v2, v2
	v_mul_f32_e32 v2, 0xbfb8aa3b, v2
	v_exp_f32_e32 v2, v2
	s_nop 0
	v_add_f32_e32 v2, 1.0, v2
	v_rcp_f32_e32 v2, v2
	s_nop 0
	v_mul_f32_e32 v2, v33, v2
	v_cvt_pk_bf16_f32 v2, v2, s0
	global_store_short v[30:31], v2, off
	v_add_u32_e32 v30, 32, v38
	v_lshl_add_u32 v2, v30, 6, v41
	ds_read_b32 v2, v2
	v_ashrrev_i32_e32 v31, 31, v30
	v_lshl_add_u64 v[30:31], s[12:13], 0, v[30:31]
	v_lshlrev_b64 v[30:31], 11, v[30:31]
	v_lshl_add_u64 v[30:31], v[0:1], 0, v[30:31]
	s_waitcnt lgkmcnt(0)
	v_fma_f32 v2, v40, v2, v26
	v_mul_f32_e32 v26, 0x3d372713, v2
	v_mul_f32_e32 v26, v2, v26
	v_fma_f32 v26, v2, v26, v2
	v_mul_f32_e32 v26, 0x3f4c422a, v26
	v_add_f32_e32 v26, v26, v26
	v_mul_f32_e32 v26, 0xbfb8aa3b, v26
	v_exp_f32_e32 v26, v26
	s_nop 0
	v_add_f32_e32 v26, 1.0, v26
	v_rcp_f32_e32 v26, v26
	s_nop 0
	v_mul_f32_e32 v2, v2, v26
	v_cvt_pk_bf16_f32 v2, v2, s0
	v_add_u32_e32 v26, 33, v38
	global_store_short v[30:31], v2, off
	v_lshl_add_u32 v2, v26, 6, v41
	ds_read_b32 v2, v2
	s_waitcnt lgkmcnt(0)
	v_fma_f32 v2, v40, v2, v27
	v_mul_f32_e32 v27, 0x3d372713, v2
	v_mul_f32_e32 v27, v2, v27
	v_fma_f32 v27, v2, v27, v2
	v_mul_f32_e32 v27, 0x3f4c422a, v27
	v_add_f32_e32 v27, v27, v27
	v_mul_f32_e32 v27, 0xbfb8aa3b, v27
	v_exp_f32_e32 v27, v27
	s_nop 0
	v_add_f32_e32 v27, 1.0, v27
	v_rcp_f32_e32 v27, v27
	s_nop 0
	v_mul_f32_e32 v2, v2, v27
	v_ashrrev_i32_e32 v27, 31, v26
	v_lshl_add_u64 v[26:27], s[12:13], 0, v[26:27]
	v_lshlrev_b64 v[26:27], 11, v[26:27]
	v_cvt_pk_bf16_f32 v2, v2, s0
	v_lshl_add_u64 v[26:27], v[0:1], 0, v[26:27]
	global_store_short v[26:27], v2, off
	v_add_u32_e32 v26, 34, v38
	v_lshl_add_u32 v2, v26, 6, v41
	ds_read_b32 v2, v2
	s_waitcnt lgkmcnt(0)
	v_fma_f32 v2, v40, v2, v28
	v_mul_f32_e32 v27, 0x3d372713, v2
	v_mul_f32_e32 v27, v2, v27
	v_fma_f32 v27, v2, v27, v2
	v_mul_f32_e32 v27, 0x3f4c422a, v27
	v_add_f32_e32 v27, v27, v27
	v_mul_f32_e32 v27, 0xbfb8aa3b, v27
	v_exp_f32_e32 v27, v27
	s_nop 0
	v_add_f32_e32 v27, 1.0, v27
	v_rcp_f32_e32 v27, v27
	s_nop 0
	v_mul_f32_e32 v2, v2, v27
	v_ashrrev_i32_e32 v27, 31, v26
	v_lshl_add_u64 v[26:27], s[12:13], 0, v[26:27]
	v_lshlrev_b64 v[26:27], 11, v[26:27]
	v_cvt_pk_bf16_f32 v2, v2, s0
	v_lshl_add_u64 v[26:27], v[0:1], 0, v[26:27]
	global_store_short v[26:27], v2, off
	v_add_u32_e32 v26, 35, v38
	v_lshl_add_u32 v2, v26, 6, v41
	ds_read_b32 v2, v2
	v_ashrrev_i32_e32 v27, 31, v26
	v_lshl_add_u64 v[26:27], s[12:13], 0, v[26:27]
	v_lshlrev_b64 v[26:27], 11, v[26:27]
	v_lshl_add_u64 v[26:27], v[0:1], 0, v[26:27]
	s_waitcnt lgkmcnt(0)
	v_fmac_f32_e32 v29, v40, v2
	v_mul_f32_e32 v2, 0x3d372713, v29
	v_mul_f32_e32 v2, v29, v2
	v_fma_f32 v2, v29, v2, v29
	v_mul_f32_e32 v2, 0x3f4c422a, v2
	v_add_f32_e32 v2, v2, v2
	v_mul_f32_e32 v2, 0xbfb8aa3b, v2
	v_exp_f32_e32 v2, v2
	s_nop 0
	v_add_f32_e32 v2, 1.0, v2
	v_rcp_f32_e32 v2, v2
	s_nop 0
	v_mul_f32_e32 v2, v29, v2
	v_cvt_pk_bf16_f32 v2, v2, s0
	global_store_short v[26:27], v2, off
	v_add_u32_e32 v26, 48, v38
	v_lshl_add_u32 v2, v26, 6, v41
	ds_read_b32 v2, v2
	v_ashrrev_i32_e32 v27, 31, v26
	v_lshl_add_u64 v[26:27], s[12:13], 0, v[26:27]
	v_lshlrev_b64 v[26:27], 11, v[26:27]
	v_lshl_add_u64 v[26:27], v[0:1], 0, v[26:27]
	s_waitcnt lgkmcnt(0)
	v_fma_f32 v2, v40, v2, v22
	v_mul_f32_e32 v22, 0x3d372713, v2
	v_mul_f32_e32 v22, v2, v22
	v_fma_f32 v22, v2, v22, v2
	v_mul_f32_e32 v22, 0x3f4c422a, v22
	v_add_f32_e32 v22, v22, v22
	v_mul_f32_e32 v22, 0xbfb8aa3b, v22
	v_exp_f32_e32 v22, v22
	s_nop 0
	v_add_f32_e32 v22, 1.0, v22
	v_rcp_f32_e32 v22, v22
	s_nop 0
	v_mul_f32_e32 v2, v2, v22
	v_cvt_pk_bf16_f32 v2, v2, s0
	v_add_u32_e32 v22, 49, v38
	global_store_short v[26:27], v2, off
	v_lshl_add_u32 v2, v22, 6, v41
	ds_read_b32 v2, v2
	s_waitcnt lgkmcnt(0)
	v_fma_f32 v2, v40, v2, v23
	v_mul_f32_e32 v23, 0x3d372713, v2
	v_mul_f32_e32 v23, v2, v23
	v_fma_f32 v23, v2, v23, v2
	v_mul_f32_e32 v23, 0x3f4c422a, v23
	v_add_f32_e32 v23, v23, v23
	v_mul_f32_e32 v23, 0xbfb8aa3b, v23
	v_exp_f32_e32 v23, v23
	s_nop 0
	v_add_f32_e32 v23, 1.0, v23
	v_rcp_f32_e32 v23, v23
	s_nop 0
	v_mul_f32_e32 v2, v2, v23
	v_ashrrev_i32_e32 v23, 31, v22
	v_lshl_add_u64 v[22:23], s[12:13], 0, v[22:23]
	v_lshlrev_b64 v[22:23], 11, v[22:23]
	v_cvt_pk_bf16_f32 v2, v2, s0
	v_lshl_add_u64 v[22:23], v[0:1], 0, v[22:23]
	global_store_short v[22:23], v2, off
	v_add_u32_e32 v22, 50, v38
	v_lshl_add_u32 v2, v22, 6, v41
	ds_read_b32 v2, v2
	s_waitcnt lgkmcnt(0)
; DI bf16 f2bf(float f) { return (bf16)(pk2(f, 0.f) & 0xffffu); }
; DI float gelu_tanh(float x) { const float u = 0.7978845608028654f * (x + 0.044715f * x * x * x); return x * sigm(2.0f * u); }
; DI void s5_passC(const Ctx& C, const S5P& P, const bf16* PROJ, const f32x2* END, bf16* YG  , int item_lo, int item_hi) {
;     ...
;         const float dv = P.d[g * 16 + (lane & 15)];
; #pragma unroll
;         for (int r = 0; r < 8; ++r)
; #pragma unroll
;             for (int j = 0; j < 4; ++j) { const int t = 16 * r + (lane >> 4) * 4 + j; const float y = acc[r][j] + dv * UF[t * 16 + (lane & 15)]; YG[(tok0 + t) * 1024 + g * 16 + (lane & 15)] = f2bf(gelu_tanh(y)); }
	v_fma_f32 v2, v40, v2, v24
	v_mul_f32_e32 v23, 0x3d372713, v2
	v_mul_f32_e32 v23, v2, v23
	v_fma_f32 v23, v2, v23, v2
	v_mul_f32_e32 v23, 0x3f4c422a, v23
	v_add_f32_e32 v23, v23, v23
	v_mul_f32_e32 v23, 0xbfb8aa3b, v23
	v_exp_f32_e32 v23, v23
	s_nop 0
	v_add_f32_e32 v23, 1.0, v23
	v_rcp_f32_e32 v23, v23
	s_nop 0
	v_mul_f32_e32 v2, v2, v23
	v_ashrrev_i32_e32 v23, 31, v22
	v_lshl_add_u64 v[22:23], s[12:13], 0, v[22:23]
	v_lshlrev_b64 v[22:23], 11, v[22:23]
	v_cvt_pk_bf16_f32 v2, v2, s0
	v_lshl_add_u64 v[22:23], v[0:1], 0, v[22:23]
	global_store_short v[22:23], v2, off
	v_add_u32_e32 v22, 51, v38
	v_lshl_add_u32 v2, v22, 6, v41
	ds_read_b32 v2, v2
	v_ashrrev_i32_e32 v23, 31, v22
	v_lshl_add_u64 v[22:23], s[12:13], 0, v[22:23]
	v_lshlrev_b64 v[22:23], 11, v[22:23]
	v_lshl_add_u64 v[22:23], v[0:1], 0, v[22:23]
	s_waitcnt lgkmcnt(0)
	v_fmac_f32_e32 v25, v40, v2
	v_mul_f32_e32 v2, 0x3d372713, v25
	v_mul_f32_e32 v2, v25, v2
	v_fma_f32 v2, v25, v2, v25
	v_mul_f32_e32 v2, 0x3f4c422a, v2
	v_add_f32_e32 v2, v2, v2
	v_mul_f32_e32 v2, 0xbfb8aa3b, v2
	v_exp_f32_e32 v2, v2
	s_nop 0
	v_add_f32_e32 v2, 1.0, v2
	v_rcp_f32_e32 v2, v2
	s_nop 0
	v_mul_f32_e32 v2, v25, v2
	v_cvt_pk_bf16_f32 v2, v2, s0
	global_store_short v[22:23], v2, off
	v_add_u32_e32 v22, 64, v38
	v_lshl_add_u32 v2, v22, 6, v41
	ds_read_b32 v2, v2
	v_ashrrev_i32_e32 v23, 31, v22
	v_lshl_add_u64 v[22:23], s[12:13], 0, v[22:23]
	v_lshlrev_b64 v[22:23], 11, v[22:23]
	v_lshl_add_u64 v[22:23], v[0:1], 0, v[22:23]
	s_waitcnt lgkmcnt(0)
	v_fma_f32 v2, v40, v2, v18
	v_mul_f32_e32 v18, 0x3d372713, v2
	v_mul_f32_e32 v18, v2, v18
	v_fma_f32 v18, v2, v18, v2
	v_mul_f32_e32 v18, 0x3f4c422a, v18
	v_add_f32_e32 v18, v18, v18
	v_mul_f32_e32 v18, 0xbfb8aa3b, v18
	v_exp_f32_e32 v18, v18
	s_nop 0
	v_add_f32_e32 v18, 1.0, v18
	v_rcp_f32_e32 v18, v18
	s_nop 0
	v_mul_f32_e32 v2, v2, v18
	v_cvt_pk_bf16_f32 v2, v2, s0
	v_add_u32_e32 v18, 0x41, v38
	global_store_short v[22:23], v2, off
	v_lshl_add_u32 v2, v18, 6, v41
	ds_read_b32 v2, v2
	s_waitcnt lgkmcnt(0)
	v_fma_f32 v2, v40, v2, v19
	v_mul_f32_e32 v19, 0x3d372713, v2
	v_mul_f32_e32 v19, v2, v19
	v_fma_f32 v19, v2, v19, v2
	v_mul_f32_e32 v19, 0x3f4c422a, v19
	v_add_f32_e32 v19, v19, v19
	v_mul_f32_e32 v19, 0xbfb8aa3b, v19
	v_exp_f32_e32 v19, v19
	s_nop 0
	v_add_f32_e32 v19, 1.0, v19
	v_rcp_f32_e32 v19, v19
	s_nop 0
	v_mul_f32_e32 v2, v2, v19
	v_ashrrev_i32_e32 v19, 31, v18
	v_lshl_add_u64 v[18:19], s[12:13], 0, v[18:19]
	v_lshlrev_b64 v[18:19], 11, v[18:19]
	v_cvt_pk_bf16_f32 v2, v2, s0
	v_lshl_add_u64 v[18:19], v[0:1], 0, v[18:19]
	global_store_short v[18:19], v2, off
	v_add_u32_e32 v18, 0x42, v38
	v_lshl_add_u32 v2, v18, 6, v41
	ds_read_b32 v2, v2
	s_waitcnt lgkmcnt(0)
	v_fma_f32 v2, v40, v2, v20
	v_mul_f32_e32 v19, 0x3d372713, v2
	v_mul_f32_e32 v19, v2, v19
	v_fma_f32 v19, v2, v19, v2
	v_mul_f32_e32 v19, 0x3f4c422a, v19
	v_add_f32_e32 v19, v19, v19
	v_mul_f32_e32 v19, 0xbfb8aa3b, v19
	v_exp_f32_e32 v19, v19
	s_nop 0
	v_add_f32_e32 v19, 1.0, v19
	v_rcp_f32_e32 v19, v19
	s_nop 0
	v_mul_f32_e32 v2, v2, v19
	v_ashrrev_i32_e32 v19, 31, v18
	v_lshl_add_u64 v[18:19], s[12:13], 0, v[18:19]
	v_lshlrev_b64 v[18:19], 11, v[18:19]
	v_cvt_pk_bf16_f32 v2, v2, s0
	v_lshl_add_u64 v[18:19], v[0:1], 0, v[18:19]
	global_store_short v[18:19], v2, off
	v_add_u32_e32 v18, 0x43, v38
	v_lshl_add_u32 v2, v18, 6, v41
	ds_read_b32 v2, v2
	v_ashrrev_i32_e32 v19, 31, v18
	v_lshl_add_u64 v[18:19], s[12:13], 0, v[18:19]
	v_lshlrev_b64 v[18:19], 11, v[18:19]
	v_lshl_add_u64 v[18:19], v[0:1], 0, v[18:19]
	s_waitcnt lgkmcnt(0)
	v_fmac_f32_e32 v21, v40, v2
	v_mul_f32_e32 v2, 0x3d372713, v21
	v_mul_f32_e32 v2, v21, v2
	v_fma_f32 v2, v21, v2, v21
	v_mul_f32_e32 v2, 0x3f4c422a, v2
	v_add_f32_e32 v2, v2, v2
	v_mul_f32_e32 v2, 0xbfb8aa3b, v2
	v_exp_f32_e32 v2, v2
	s_nop 0
	v_add_f32_e32 v2, 1.0, v2
	v_rcp_f32_e32 v2, v2
	s_nop 0
	v_mul_f32_e32 v2, v21, v2
	v_cvt_pk_bf16_f32 v2, v2, s0
	global_store_short v[18:19], v2, off
	v_add_u32_e32 v18, 0x50, v38
	v_lshl_add_u32 v2, v18, 6, v41
	ds_read_b32 v2, v2
	v_ashrrev_i32_e32 v19, 31, v18
	v_lshl_add_u64 v[18:19], s[12:13], 0, v[18:19]
	v_lshlrev_b64 v[18:19], 11, v[18:19]
	v_lshl_add_u64 v[18:19], v[0:1], 0, v[18:19]
	s_waitcnt lgkmcnt(0)
	v_fma_f32 v2, v40, v2, v14
	v_mul_f32_e32 v14, 0x3d372713, v2
	v_mul_f32_e32 v14, v2, v14
	v_fma_f32 v14, v2, v14, v2
	v_mul_f32_e32 v14, 0x3f4c422a, v14
	v_add_f32_e32 v14, v14, v14
	v_mul_f32_e32 v14, 0xbfb8aa3b, v14
	v_exp_f32_e32 v14, v14
	s_nop 0
	v_add_f32_e32 v14, 1.0, v14
	v_rcp_f32_e32 v14, v14
	s_nop 0
	v_mul_f32_e32 v2, v2, v14
	v_cvt_pk_bf16_f32 v2, v2, s0
	v_add_u32_e32 v14, 0x51, v38
	global_store_short v[18:19], v2, off
	v_lshl_add_u32 v2, v14, 6, v41
	ds_read_b32 v2, v2
	s_waitcnt lgkmcnt(0)
	v_fma_f32 v2, v40, v2, v15
	v_mul_f32_e32 v15, 0x3d372713, v2
	v_mul_f32_e32 v15, v2, v15
	v_fma_f32 v15, v2, v15, v2
	v_mul_f32_e32 v15, 0x3f4c422a, v15
	v_add_f32_e32 v15, v15, v15
	v_mul_f32_e32 v15, 0xbfb8aa3b, v15
	v_exp_f32_e32 v15, v15
	s_nop 0
	v_add_f32_e32 v15, 1.0, v15
	v_rcp_f32_e32 v15, v15
	s_nop 0
	v_mul_f32_e32 v2, v2, v15
	v_ashrrev_i32_e32 v15, 31, v14
	v_lshl_add_u64 v[14:15], s[12:13], 0, v[14:15]
	v_lshlrev_b64 v[14:15], 11, v[14:15]
	v_cvt_pk_bf16_f32 v2, v2, s0
	v_lshl_add_u64 v[14:15], v[0:1], 0, v[14:15]
	global_store_short v[14:15], v2, off
	v_add_u32_e32 v14, 0x52, v38
	v_lshl_add_u32 v2, v14, 6, v41
	ds_read_b32 v2, v2
	s_waitcnt lgkmcnt(0)
; DI bf16 f2bf(float f) { return (bf16)(pk2(f, 0.f) & 0xffffu); }
; DI float gelu_tanh(float x) { const float u = 0.7978845608028654f * (x + 0.044715f * x * x * x); return x * sigm(2.0f * u); }
; DI void s5_passC(const Ctx& C, const S5P& P, const bf16* PROJ, const f32x2* END, bf16* YG  , int item_lo, int item_hi) {
;     ...
;         const float dv = P.d[g * 16 + (lane & 15)];
; #pragma unroll
;         for (int r = 0; r < 8; ++r)
; #pragma unroll
;             for (int j = 0; j < 4; ++j) { const int t = 16 * r + (lane >> 4) * 4 + j; const float y = acc[r][j] + dv * UF[t * 16 + (lane & 15)]; YG[(tok0 + t) * 1024 + g * 16 + (lane & 15)] = f2bf(gelu_tanh(y)); }
	v_fma_f32 v2, v40, v2, v16
	v_mul_f32_e32 v15, 0x3d372713, v2
	v_mul_f32_e32 v15, v2, v15
	v_fma_f32 v15, v2, v15, v2
	v_mul_f32_e32 v15, 0x3f4c422a, v15
	v_add_f32_e32 v15, v15, v15
	v_mul_f32_e32 v15, 0xbfb8aa3b, v15
	v_exp_f32_e32 v15, v15
	s_nop 0
	v_add_f32_e32 v15, 1.0, v15
	v_rcp_f32_e32 v15, v15
	s_nop 0
	v_mul_f32_e32 v2, v2, v15
	v_ashrrev_i32_e32 v15, 31, v14
	v_lshl_add_u64 v[14:15], s[12:13], 0, v[14:15]
	v_lshlrev_b64 v[14:15], 11, v[14:15]
	v_cvt_pk_bf16_f32 v2, v2, s0
	v_lshl_add_u64 v[14:15], v[0:1], 0, v[14:15]
	global_store_short v[14:15], v2, off
	v_add_u32_e32 v14, 0x53, v38
	v_lshl_add_u32 v2, v14, 6, v41
	ds_read_b32 v2, v2
	v_ashrrev_i32_e32 v15, 31, v14
	v_lshl_add_u64 v[14:15], s[12:13], 0, v[14:15]
	v_lshlrev_b64 v[14:15], 11, v[14:15]
	v_lshl_add_u64 v[14:15], v[0:1], 0, v[14:15]
	s_waitcnt lgkmcnt(0)
	v_fmac_f32_e32 v17, v40, v2
	v_mul_f32_e32 v2, 0x3d372713, v17
	v_mul_f32_e32 v2, v17, v2
	v_fma_f32 v2, v17, v2, v17
	v_mul_f32_e32 v2, 0x3f4c422a, v2
	v_add_f32_e32 v2, v2, v2
	v_mul_f32_e32 v2, 0xbfb8aa3b, v2
	v_exp_f32_e32 v2, v2
	s_nop 0
	v_add_f32_e32 v2, 1.0, v2
	v_rcp_f32_e32 v2, v2
	s_nop 0
	v_mul_f32_e32 v2, v17, v2
	v_cvt_pk_bf16_f32 v2, v2, s0
	global_store_short v[14:15], v2, off
	v_add_u32_e32 v14, 0x60, v38
	v_lshl_add_u32 v2, v14, 6, v41
	ds_read_b32 v2, v2
	v_ashrrev_i32_e32 v15, 31, v14
	v_lshl_add_u64 v[14:15], s[12:13], 0, v[14:15]
	v_lshlrev_b64 v[14:15], 11, v[14:15]
	v_lshl_add_u64 v[14:15], v[0:1], 0, v[14:15]
	s_waitcnt lgkmcnt(0)
	v_fma_f32 v2, v40, v2, v10
	v_mul_f32_e32 v10, 0x3d372713, v2
	v_mul_f32_e32 v10, v2, v10
	v_fma_f32 v10, v2, v10, v2
	v_mul_f32_e32 v10, 0x3f4c422a, v10
	v_add_f32_e32 v10, v10, v10
	v_mul_f32_e32 v10, 0xbfb8aa3b, v10
	v_exp_f32_e32 v10, v10
	s_nop 0
	v_add_f32_e32 v10, 1.0, v10
	v_rcp_f32_e32 v10, v10
	s_nop 0
	v_mul_f32_e32 v2, v2, v10
	v_cvt_pk_bf16_f32 v2, v2, s0
	v_add_u32_e32 v10, 0x61, v38
	global_store_short v[14:15], v2, off
	v_lshl_add_u32 v2, v10, 6, v41
	ds_read_b32 v2, v2
	s_waitcnt lgkmcnt(0)
	v_fma_f32 v2, v40, v2, v11
	v_mul_f32_e32 v11, 0x3d372713, v2
	v_mul_f32_e32 v11, v2, v11
	v_fma_f32 v11, v2, v11, v2
	v_mul_f32_e32 v11, 0x3f4c422a, v11
	v_add_f32_e32 v11, v11, v11
	v_mul_f32_e32 v11, 0xbfb8aa3b, v11
	v_exp_f32_e32 v11, v11
	s_nop 0
	v_add_f32_e32 v11, 1.0, v11
	v_rcp_f32_e32 v11, v11
	s_nop 0
	v_mul_f32_e32 v2, v2, v11
	v_ashrrev_i32_e32 v11, 31, v10
	v_lshl_add_u64 v[10:11], s[12:13], 0, v[10:11]
	v_lshlrev_b64 v[10:11], 11, v[10:11]
	v_cvt_pk_bf16_f32 v2, v2, s0
	v_lshl_add_u64 v[10:11], v[0:1], 0, v[10:11]
	global_store_short v[10:11], v2, off
	v_add_u32_e32 v10, 0x62, v38
	v_lshl_add_u32 v2, v10, 6, v41
	ds_read_b32 v2, v2
	s_waitcnt lgkmcnt(0)
	v_fma_f32 v2, v40, v2, v12
	v_mul_f32_e32 v11, 0x3d372713, v2
	v_mul_f32_e32 v11, v2, v11
	v_fma_f32 v11, v2, v11, v2
	v_mul_f32_e32 v11, 0x3f4c422a, v11
	v_add_f32_e32 v11, v11, v11
	v_mul_f32_e32 v11, 0xbfb8aa3b, v11
	v_exp_f32_e32 v11, v11
	s_nop 0
	v_add_f32_e32 v11, 1.0, v11
	v_rcp_f32_e32 v11, v11
	s_nop 0
	v_mul_f32_e32 v2, v2, v11
	v_ashrrev_i32_e32 v11, 31, v10
	v_lshl_add_u64 v[10:11], s[12:13], 0, v[10:11]
	v_lshlrev_b64 v[10:11], 11, v[10:11]
	v_cvt_pk_bf16_f32 v2, v2, s0
	v_lshl_add_u64 v[10:11], v[0:1], 0, v[10:11]
	global_store_short v[10:11], v2, off
	v_add_u32_e32 v10, 0x63, v38
	v_lshl_add_u32 v2, v10, 6, v41
	ds_read_b32 v2, v2
	v_ashrrev_i32_e32 v11, 31, v10
	v_lshl_add_u64 v[10:11], s[12:13], 0, v[10:11]
	v_lshlrev_b64 v[10:11], 11, v[10:11]
	v_lshl_add_u64 v[10:11], v[0:1], 0, v[10:11]
	s_waitcnt lgkmcnt(0)
	v_fmac_f32_e32 v13, v40, v2
	v_mul_f32_e32 v2, 0x3d372713, v13
	v_mul_f32_e32 v2, v13, v2
	v_fma_f32 v2, v13, v2, v13
	v_mul_f32_e32 v2, 0x3f4c422a, v2
	v_add_f32_e32 v2, v2, v2
	v_mul_f32_e32 v2, 0xbfb8aa3b, v2
	v_exp_f32_e32 v2, v2
	s_nop 0
	v_add_f32_e32 v2, 1.0, v2
	v_rcp_f32_e32 v2, v2
	s_nop 0
	v_mul_f32_e32 v2, v13, v2
	v_cvt_pk_bf16_f32 v2, v2, s0
	global_store_short v[10:11], v2, off
	v_add_u32_e32 v10, 0x70, v38
	v_lshl_add_u32 v2, v10, 6, v41
	ds_read_b32 v2, v2
	v_ashrrev_i32_e32 v11, 31, v10
	v_lshl_add_u64 v[10:11], s[12:13], 0, v[10:11]
	v_lshlrev_b64 v[10:11], 11, v[10:11]
	v_lshl_add_u64 v[10:11], v[0:1], 0, v[10:11]
	s_waitcnt lgkmcnt(0)
	v_fma_f32 v2, v40, v2, v6
	v_mul_f32_e32 v6, 0x3d372713, v2
	v_mul_f32_e32 v6, v2, v6
	v_fma_f32 v6, v2, v6, v2
	v_mul_f32_e32 v6, 0x3f4c422a, v6
	v_add_f32_e32 v6, v6, v6
	v_mul_f32_e32 v6, 0xbfb8aa3b, v6
	v_exp_f32_e32 v6, v6
	s_nop 0
	v_add_f32_e32 v6, 1.0, v6
	v_rcp_f32_e32 v6, v6
	s_nop 0
	v_mul_f32_e32 v2, v2, v6
	v_cvt_pk_bf16_f32 v2, v2, s0
	v_add_u32_e32 v6, 0x71, v38
	global_store_short v[10:11], v2, off
	v_lshl_add_u32 v2, v6, 6, v41
	ds_read_b32 v2, v2
	s_waitcnt lgkmcnt(0)
	v_fma_f32 v2, v40, v2, v7
	v_mul_f32_e32 v7, 0x3d372713, v2
	v_mul_f32_e32 v7, v2, v7
	v_fma_f32 v7, v2, v7, v2
	v_mul_f32_e32 v7, 0x3f4c422a, v7
	v_add_f32_e32 v7, v7, v7
	v_mul_f32_e32 v7, 0xbfb8aa3b, v7
	v_exp_f32_e32 v7, v7
	s_nop 0
	v_add_f32_e32 v7, 1.0, v7
	v_rcp_f32_e32 v7, v7
	s_nop 0
	v_mul_f32_e32 v2, v2, v7
	v_ashrrev_i32_e32 v7, 31, v6
	v_lshl_add_u64 v[6:7], s[12:13], 0, v[6:7]
	v_lshlrev_b64 v[6:7], 11, v[6:7]
	v_cvt_pk_bf16_f32 v2, v2, s0
	v_lshl_add_u64 v[6:7], v[0:1], 0, v[6:7]
	global_store_short v[6:7], v2, off
	v_add_u32_e32 v6, 0x72, v38
	v_lshl_add_u32 v2, v6, 6, v41
	ds_read_b32 v2, v2
	s_waitcnt lgkmcnt(0)
	v_fma_f32 v2, v40, v2, v8
	v_mul_f32_e32 v7, 0x3d372713, v2
	v_mul_f32_e32 v7, v2, v7
	v_fma_f32 v7, v2, v7, v2
	v_mul_f32_e32 v7, 0x3f4c422a, v7
	v_add_f32_e32 v7, v7, v7
	v_mul_f32_e32 v7, 0xbfb8aa3b, v7
	v_exp_f32_e32 v7, v7
	s_nop 0
	v_add_f32_e32 v7, 1.0, v7
	v_rcp_f32_e32 v7, v7
	s_nop 0
	v_mul_f32_e32 v2, v2, v7
	v_ashrrev_i32_e32 v7, 31, v6
	v_lshl_add_u64 v[6:7], s[12:13], 0, v[6:7]
	v_lshlrev_b64 v[6:7], 11, v[6:7]
	v_cvt_pk_bf16_f32 v2, v2, s0
	v_lshl_add_u64 v[6:7], v[0:1], 0, v[6:7]
	global_store_short v[6:7], v2, off
	v_add_u32_e32 v6, 0x73, v38
	v_lshl_add_u32 v2, v6, 6, v41
	ds_read_b32 v2, v2
	v_ashrrev_i32_e32 v7, 31, v6
	v_lshl_add_u64 v[6:7], s[12:13], 0, v[6:7]
	v_lshlrev_b64 v[6:7], 11, v[6:7]
	v_lshl_add_u64 v[0:1], v[0:1], 0, v[6:7]
	s_waitcnt lgkmcnt(0)
	v_fmac_f32_e32 v9, v40, v2
	v_mul_f32_e32 v2, 0x3d372713, v9
	v_mul_f32_e32 v2, v9, v2
	v_fma_f32 v2, v9, v2, v9
	v_mul_f32_e32 v2, 0x3f4c422a, v2
	v_add_f32_e32 v2, v2, v2
	v_mul_f32_e32 v2, 0xbfb8aa3b, v2
	v_exp_f32_e32 v2, v2
	s_nop 0
	v_add_f32_e32 v2, 1.0, v2
	v_rcp_f32_e32 v2, v2
	s_nop 0
	v_mul_f32_e32 v2, v9, v2
	v_cvt_pk_bf16_f32 v2, v2, s0
	global_store_short v[0:1], v2, off
	s_waitcnt lgkmcnt(0)
	s_add_i32 s0, s54, 0x400
	s_cmpk_gt_i32 s54, 0x1bff
	s_mov_b32 s54, s0
	s_cbranch_scc0 .LBB0_680
